# removed the redundant post-barrier s_waitcnt lgkmcnt(0) at the head of every MFMA segment (40 sites in the five K-loops and their peeled copies); the pre-barrier lgkmcnt(0) already drained the reads
# baseline (speedup 1.0000x reference)
; #define PG8_STAGE(bufoff, gbase, voff) do { _Pragma("unroll") for (int _i = 0; _i < 2; ++_i) \
;         __builtin_amdgcn_global_load_lds((const unsigned*)((const char*)(gbase) + (voff)[_i]), (LAS unsigned*)(lds + (bufoff) + ldsw + _i * 8192), 16, 0, 0); } while (0)
; #define PG8_LDA(dst, b, h) do { _Pragma("unroll") for (int m = 0; m < 4; ++m) _Pragma("unroll") for (int k = 0; k < 2; ++k) dst[m][k] = *(const LAS bf16x8*)(lds + PG8_SA(b, h) + aoff + m * 2048 + k * 1024); } while (0)
; #define PG8_LDB(dst, b, h) do { _Pragma("unroll") for (int n = 0; n < 2; ++n) _Pragma("unroll") for (int k = 0; k < 2; ++k) dst[n][k] = *(const LAS bf16x8*)(lds + PG8_SB(b, h) + boff + n * 2048 + k * 1024); } while (0)
; #define PG8_MMA(ai, bj, At, Bt) do { __builtin_amdgcn_s_setprio(1); _Pragma("unroll") for (int m = 0; m < 4; ++m) _Pragma("unroll") for (int n = 0; n < 2; ++n) _Pragma("unroll") for (int k = 0; k < 2; ++k) \
;         acc[ai][bj][m][n] = __builtin_amdgcn_mfma_f32_16x16x32_bf16(Bt[n][k], At[m][k], acc[ai][bj][m][n], 0, 0, 0); __builtin_amdgcn_s_setprio(0); } while (0)
; #define PG8_BAR __builtin_amdgcn_s_barrier()
; template <class Epi, class Sched>
; __device__ __forceinline__ void gemm_phase(LAS unsigned char* lds, const Gemm g, const Sched& S, const Epi& E) {
;     ...
;         for (int t = 0; t < nt; t += 2) {
;             const bool last = (t == nt - 2);
;             const char* a1 = cA + (size_t)(t + 1) * kstep;
;             const char* a2 = last ? nA : cA + (size_t)(t + 2) * kstep; const char* b2 = last ? nB : cB + (size_t)(t + 2) * kstep;
;             const char* a3 = a2 + kstep; const char* b3 = b2 + kstep;
;             PG8_LDB(B0, 0, 0); PG8_LDB(B1, 0, 1); PG8_SCHED; PG8_LDA(At, 0, 0); PG8_STAGE(PG8_SA(1, 1), a1 + hstepA, voffA);
;             PG8_WAIT_V(8); PG8_WAIT_L(0); PG8_BAR; PG8_MMA(0, 0, At, B0); PG8_MMA(0, 1, At, B1); PG8_BAR; PG8_SCHED;
;             PG8_LDA(At, 0, 1); PG8_STAGE(PG8_SB(0, 0), b2, voffB); PG8_STAGE(PG8_SB(0, 1), b2 + hstepB, voffB); PG8_STAGE(PG8_SA(0, 0), a2, voffA);
;             PG8_WAIT_V(8); PG8_WAIT_L(0); PG8_BAR; PG8_MMA(1, 0, At, B0); PG8_MMA(1, 1, At, B1); PG8_BAR; PG8_SCHED;
;             PG8_LDB(B0, 1, 0); PG8_LDB(B1, 1, 1); PG8_SCHED; PG8_LDA(At, 1, 0); PG8_STAGE(PG8_SA(0, 1), a2 + hstepA, voffA);
;             PG8_WAIT_V(8); PG8_WAIT_L(0); PG8_BAR; PG8_MMA(0, 0, At, B0); PG8_MMA(0, 1, At, B1); PG8_BAR; PG8_SCHED;
.Lprio_96:
	s_cmp_eq_u32 s40, 12
	s_cselect_b32 s101, 1, 0
	s_cmp_eq_u64 s[22:23], 0
	s_cselect_b32 s100, s101, 0
	s_add_u32 s0, s42, 0xfffc0080
	s_addc_u32 s6, s43, -1
	s_add_i32 s26, 0, 0x10000
	s_cmp_eq_u32 s69, 12
	s_cselect_b32 s15, s13, s6
	s_cselect_b32 s14, s57, s0
	v_add_u32_e32 v152, s26, v156
	s_cselect_b32 s7, s45, s53
	s_cselect_b32 s6, s68, s52
	s_add_i32 s0, 0, 0x14000
	ds_read_b128 v[144:147], v152
	ds_read_b128 v[148:151], v152 offset:1024
	ds_read_b128 v[164:167], v152 offset:2048
	ds_read_b128 v[168:171], v152 offset:3072
	v_add_u32_e32 v152, s0, v156
	ds_read_b128 v[172:175], v152
	ds_read_b128 v[190:193], v152 offset:1024
	ds_read_b128 v[196:199], v152 offset:2048
	ds_read_b128 v[200:203], v152 offset:3072
	v_lshl_add_u64 v[152:153], s[42:43], 0, v[140:141]
	s_add_i32 m0, s21, 0xc000
	ds_read_b128 v[204:207], v162
	ds_read_b128 v[208:211], v162 offset:1024
	ds_read_b128 v[212:215], v162 offset:2048
	ds_read_b128 v[216:219], v162 offset:3072
	ds_read_b128 v[220:223], v162 offset:4096
	ds_read_b128 v[224:227], v162 offset:5120
	ds_read_b128 v[228:231], v162 offset:6144
	ds_read_b128 v[232:235], v162 offset:7168
	global_load_lds_dwordx4 v[152:153], off
	v_lshl_add_u64 v[152:153], s[42:43], 0, v[142:143]
	s_add_i32 m0, s21, 0xe000
	s_nop 0
	global_load_lds_dwordx4 v[152:153], off
	s_cmp_lg_u32 s101, 0
	s_waitcnt vmcnt(8)
	s_waitcnt lgkmcnt(0)
	s_barrier
	s_cbranch_scc1 .Lgt_p_0
	v_mfma_f32_16x16x32_bf16 v[128:131], v[144:147], v[204:207], 0
	v_mfma_f32_16x16x32_bf16 v[124:127], v[164:167], v[204:207], 0
	v_mfma_f32_16x16x32_bf16 v[120:123], v[144:147], v[212:215], 0
	v_mfma_f32_16x16x32_bf16 v[108:111], v[164:167], v[212:215], 0
	v_mfma_f32_16x16x32_bf16 v[104:107], v[144:147], v[220:223], 0
	v_mfma_f32_16x16x32_bf16 v[92:95], v[164:167], v[220:223], 0
	v_mfma_f32_16x16x32_bf16 v[88:91], v[144:147], v[228:231], 0
	v_mfma_f32_16x16x32_bf16 v[76:79], v[164:167], v[228:231], 0
	v_mfma_f32_16x16x32_bf16 v[128:131], v[148:151], v[208:211], v[128:131]
	v_mfma_f32_16x16x32_bf16 v[124:127], v[168:171], v[208:211], v[124:127]
	v_mfma_f32_16x16x32_bf16 v[120:123], v[148:151], v[216:219], v[120:123]
	v_mfma_f32_16x16x32_bf16 v[108:111], v[168:171], v[216:219], v[108:111]
	v_mfma_f32_16x16x32_bf16 v[104:107], v[148:151], v[224:227], v[104:107]
	v_mfma_f32_16x16x32_bf16 v[92:95], v[168:171], v[224:227], v[92:95]
	v_mfma_f32_16x16x32_bf16 v[88:91], v[148:151], v[232:235], v[88:91]
	v_mfma_f32_16x16x32_bf16 v[76:79], v[168:171], v[232:235], v[76:79]
	v_mfma_f32_16x16x32_bf16 v[116:119], v[172:175], v[204:207], 0
	v_mfma_f32_16x16x32_bf16 v[112:115], v[196:199], v[204:207], 0
	v_mfma_f32_16x16x32_bf16 v[100:103], v[172:175], v[212:215], 0
	v_mfma_f32_16x16x32_bf16 v[96:99], v[196:199], v[212:215], 0
	v_mfma_f32_16x16x32_bf16 v[84:87], v[172:175], v[220:223], 0
	v_mfma_f32_16x16x32_bf16 v[80:83], v[196:199], v[220:223], 0
	v_mfma_f32_16x16x32_bf16 v[72:75], v[172:175], v[228:231], 0
	v_mfma_f32_16x16x32_bf16 v[68:71], v[196:199], v[228:231], 0
	v_mfma_f32_16x16x32_bf16 v[116:119], v[190:193], v[208:211], v[116:119]
	v_mfma_f32_16x16x32_bf16 v[112:115], v[200:203], v[208:211], v[112:115]
	v_mfma_f32_16x16x32_bf16 v[100:103], v[190:193], v[216:219], v[100:103]
	v_mfma_f32_16x16x32_bf16 v[96:99], v[200:203], v[216:219], v[96:99]
	v_mfma_f32_16x16x32_bf16 v[84:87], v[190:193], v[224:227], v[84:87]
	v_mfma_f32_16x16x32_bf16 v[80:83], v[200:203], v[224:227], v[80:83]
	v_mfma_f32_16x16x32_bf16 v[72:75], v[190:193], v[232:235], v[72:75]
	v_mfma_f32_16x16x32_bf16 v[68:71], v[200:203], v[232:235], v[68:71]
.Lgt_p_0_done:
	s_barrier
	s_add_i32 s26, s26, s20
	v_lshl_add_u64 v[152:153], s[6:7], 0, v[160:161]
	s_mov_b32 m0, s26
	ds_read_b128 v[204:207], v162 offset:16384
	ds_read_b128 v[208:211], v162 offset:17408
	ds_read_b128 v[212:215], v162 offset:18432
	ds_read_b128 v[216:219], v162 offset:19456
	ds_read_b128 v[220:223], v162 offset:20480
	ds_read_b128 v[224:227], v162 offset:21504
	ds_read_b128 v[228:231], v162 offset:22528
	ds_read_b128 v[232:235], v162 offset:23552
	global_load_lds_dwordx4 v[152:153], off
	s_add_i32 m0, s26, 0x2000
	s_add_u32 s78, s6, 0x40000
	v_lshl_add_u64 v[176:177], s[6:7], 0, v[136:137]
	s_addc_u32 s79, s7, 0
	s_add_i32 s0, s0, s20
	global_load_lds_dwordx4 v[176:177], off
	v_lshl_add_u64 v[236:237], s[78:79], 0, v[160:161]
	s_mov_b32 m0, s0
	v_lshl_add_u64 v[238:239], s[14:15], 0, v[134:135]
	global_load_lds_dwordx4 v[236:237], off
	v_lshl_add_u64 v[236:237], s[78:79], 0, v[136:137]
	s_add_i32 m0, s0, 0x2000
	s_nop 0
	global_load_lds_dwordx4 v[236:237], off
	v_lshl_add_u64 v[236:237], s[14:15], 0, v[132:133]
	s_mov_b32 m0, s21
	s_nop 0
	global_load_lds_dwordx4 v[236:237], off
	s_mov_b32 m0, s24
	s_nop 0
	global_load_lds_dwordx4 v[238:239], off
	s_cmp_lg_u32 s101, 0
	s_waitcnt vmcnt(8)
	s_waitcnt lgkmcnt(0)
	s_barrier
	s_cbranch_scc1 .Lgt_p_1
	v_mfma_f32_16x16x32_bf16 v[64:67], v[144:147], v[204:207], 0
	v_mfma_f32_16x16x32_bf16 v[60:63], v[164:167], v[204:207], 0
	v_mfma_f32_16x16x32_bf16 v[56:59], v[144:147], v[212:215], 0
	v_mfma_f32_16x16x32_bf16 v[44:47], v[164:167], v[212:215], 0
	v_mfma_f32_16x16x32_bf16 v[40:43], v[144:147], v[220:223], 0
	v_mfma_f32_16x16x32_bf16 v[28:31], v[164:167], v[220:223], 0
	v_mfma_f32_16x16x32_bf16 v[24:27], v[144:147], v[228:231], 0
	v_mfma_f32_16x16x32_bf16 v[12:15], v[164:167], v[228:231], 0
	v_mfma_f32_16x16x32_bf16 v[64:67], v[148:151], v[208:211], v[64:67]
	v_mfma_f32_16x16x32_bf16 v[60:63], v[168:171], v[208:211], v[60:63]
	v_mfma_f32_16x16x32_bf16 v[56:59], v[148:151], v[216:219], v[56:59]
	v_mfma_f32_16x16x32_bf16 v[44:47], v[168:171], v[216:219], v[44:47]
	v_mfma_f32_16x16x32_bf16 v[40:43], v[148:151], v[224:227], v[40:43]
	v_mfma_f32_16x16x32_bf16 v[28:31], v[168:171], v[224:227], v[28:31]
	v_mfma_f32_16x16x32_bf16 v[24:27], v[148:151], v[232:235], v[24:27]
	v_mfma_f32_16x16x32_bf16 v[12:15], v[168:171], v[232:235], v[12:15]
	v_mfma_f32_16x16x32_bf16 v[52:55], v[172:175], v[204:207], 0
	v_mfma_f32_16x16x32_bf16 v[48:51], v[196:199], v[204:207], 0
	v_mfma_f32_16x16x32_bf16 v[36:39], v[172:175], v[212:215], 0
	v_mfma_f32_16x16x32_bf16 v[32:35], v[196:199], v[212:215], 0
	v_mfma_f32_16x16x32_bf16 v[20:23], v[172:175], v[220:223], 0
	v_mfma_f32_16x16x32_bf16 v[16:19], v[196:199], v[220:223], 0
	v_mfma_f32_16x16x32_bf16 v[8:11], v[172:175], v[228:231], 0
	v_mfma_f32_16x16x32_bf16 v[4:7], v[196:199], v[228:231], 0
	v_mfma_f32_16x16x32_bf16 v[52:55], v[190:193], v[208:211], v[52:55]
	v_mfma_f32_16x16x32_bf16 v[48:51], v[200:203], v[208:211], v[48:51]
	v_mfma_f32_16x16x32_bf16 v[36:39], v[190:193], v[216:219], v[36:39]
	v_mfma_f32_16x16x32_bf16 v[32:35], v[200:203], v[216:219], v[32:35]
	v_mfma_f32_16x16x32_bf16 v[20:23], v[190:193], v[224:227], v[20:23]
	v_mfma_f32_16x16x32_bf16 v[16:19], v[200:203], v[224:227], v[16:19]
	v_mfma_f32_16x16x32_bf16 v[8:11], v[190:193], v[232:235], v[8:11]
	v_mfma_f32_16x16x32_bf16 v[4:7], v[200:203], v[232:235], v[4:7]
; #define PG8_STAGE(bufoff, gbase, voff) do { _Pragma("unroll") for (int _i = 0; _i < 2; ++_i) \
;         __builtin_amdgcn_global_load_lds((const unsigned*)((const char*)(gbase) + (voff)[_i]), (LAS unsigned*)(lds + (bufoff) + ldsw + _i * 8192), 16, 0, 0); } while (0)
; #define PG8_LDA(dst, b, h) do { _Pragma("unroll") for (int m = 0; m < 4; ++m) _Pragma("unroll") for (int k = 0; k < 2; ++k) dst[m][k] = *(const LAS bf16x8*)(lds + PG8_SA(b, h) + aoff + m * 2048 + k * 1024); } while (0)
; #define PG8_LDB(dst, b, h) do { _Pragma("unroll") for (int n = 0; n < 2; ++n) _Pragma("unroll") for (int k = 0; k < 2; ++k) dst[n][k] = *(const LAS bf16x8*)(lds + PG8_SB(b, h) + boff + n * 2048 + k * 1024); } while (0)
; #define PG8_MMA(ai, bj, At, Bt) do { __builtin_amdgcn_s_setprio(1); _Pragma("unroll") for (int m = 0; m < 4; ++m) _Pragma("unroll") for (int n = 0; n < 2; ++n) _Pragma("unroll") for (int k = 0; k < 2; ++k) \
;         acc[ai][bj][m][n] = __builtin_amdgcn_mfma_f32_16x16x32_bf16(Bt[n][k], At[m][k], acc[ai][bj][m][n], 0, 0, 0); __builtin_amdgcn_s_setprio(0); } while (0)
; #define PG8_WAIT_V(n) asm volatile("s_waitcnt vmcnt(" #n ")" ::: "memory")
; #define PG8_WAIT_L(n) asm volatile("s_waitcnt lgkmcnt(" #n ")" ::: "memory")
; #define PG8_BAR __builtin_amdgcn_s_barrier()
; #define PG8_SCHED __builtin_amdgcn_sched_barrier(0)
; template <class Epi, class Sched>
; __device__ __forceinline__ void gemm_phase(LAS unsigned char* lds, const Gemm g, const Sched& S, const Epi& E) {
;     ...
;             PG8_LDB(B0, 1, 0); PG8_LDB(B1, 1, 1); PG8_SCHED; PG8_LDA(At, 1, 0); PG8_STAGE(PG8_SA(0, 1), a2 + hstepA, voffA);
;             PG8_WAIT_V(8); PG8_WAIT_L(0); PG8_BAR; PG8_MMA(0, 0, At, B0); PG8_MMA(0, 1, At, B1); PG8_BAR; PG8_SCHED;
;             PG8_LDA(At, 1, 1); PG8_STAGE(PG8_SB(1, 0), b3, voffB); PG8_STAGE(PG8_SB(1, 1), b3 + hstepB, voffB); PG8_STAGE(PG8_SA(1, 0), a3, voffA);
;             PG8_WAIT_V(8); PG8_WAIT_L(0); PG8_BAR; PG8_MMA(1, 0, At, B0); PG8_MMA(1, 1, At, B1); PG8_BAR; PG8_SCHED;
.Lgt_p_1_done:
	s_barrier
	s_add_i32 s0, 0, 0x18000
	v_add_u32_e32 v163, s0, v156
	s_add_i32 s26, 0, 0x1c000
	ds_read_b128 v[144:147], v163
	ds_read_b128 v[148:151], v163 offset:1024
	ds_read_b128 v[164:167], v163 offset:2048
	ds_read_b128 v[168:171], v163 offset:3072
	v_add_u32_e32 v163, s26, v156
	ds_read_b128 v[172:175], v163
	ds_read_b128 v[190:193], v163 offset:1024
	ds_read_b128 v[196:199], v163 offset:2048
	ds_read_b128 v[200:203], v163 offset:3072
	s_add_u32 s14, s14, 0x40000
	s_addc_u32 s15, s15, 0
	s_mov_b32 m0, s25
	v_lshl_add_u64 v[240:241], s[14:15], 0, v[132:133]
	ds_read_b128 v[204:207], v162 offset:32768
	ds_read_b128 v[208:211], v162 offset:33792
	ds_read_b128 v[212:215], v162 offset:34816
	ds_read_b128 v[216:219], v162 offset:35840
	ds_read_b128 v[220:223], v162 offset:36864
	ds_read_b128 v[224:227], v162 offset:37888
	ds_read_b128 v[228:231], v162 offset:38912
	ds_read_b128 v[232:235], v162 offset:39936
	global_load_lds_dwordx4 v[240:241], off
	v_lshl_add_u64 v[240:241], s[14:15], 0, v[134:135]
	s_mov_b32 m0, s28
	s_nop 0
	global_load_lds_dwordx4 v[240:241], off
	s_cmp_lg_u32 s101, 0
	s_waitcnt vmcnt(8)
	s_waitcnt lgkmcnt(0)
	s_barrier
	s_cbranch_scc1 .Lgt_p_2
	v_mfma_f32_16x16x32_bf16 v[128:131], v[144:147], v[204:207], v[128:131]
	v_mfma_f32_16x16x32_bf16 v[124:127], v[164:167], v[204:207], v[124:127]
	v_mfma_f32_16x16x32_bf16 v[120:123], v[144:147], v[212:215], v[120:123]
	v_mfma_f32_16x16x32_bf16 v[108:111], v[164:167], v[212:215], v[108:111]
	v_mfma_f32_16x16x32_bf16 v[104:107], v[144:147], v[220:223], v[104:107]
	v_mfma_f32_16x16x32_bf16 v[92:95], v[164:167], v[220:223], v[92:95]
	v_mfma_f32_16x16x32_bf16 v[88:91], v[144:147], v[228:231], v[88:91]
	v_mfma_f32_16x16x32_bf16 v[76:79], v[164:167], v[228:231], v[76:79]
	v_mfma_f32_16x16x32_bf16 v[128:131], v[148:151], v[208:211], v[128:131]
	v_mfma_f32_16x16x32_bf16 v[124:127], v[168:171], v[208:211], v[124:127]
	v_mfma_f32_16x16x32_bf16 v[120:123], v[148:151], v[216:219], v[120:123]
	v_mfma_f32_16x16x32_bf16 v[108:111], v[168:171], v[216:219], v[108:111]
	v_mfma_f32_16x16x32_bf16 v[104:107], v[148:151], v[224:227], v[104:107]
	v_mfma_f32_16x16x32_bf16 v[92:95], v[168:171], v[224:227], v[92:95]
	v_mfma_f32_16x16x32_bf16 v[88:91], v[148:151], v[232:235], v[88:91]
	v_mfma_f32_16x16x32_bf16 v[76:79], v[168:171], v[232:235], v[76:79]
	v_mfma_f32_16x16x32_bf16 v[116:119], v[172:175], v[204:207], v[116:119]
	v_mfma_f32_16x16x32_bf16 v[112:115], v[196:199], v[204:207], v[112:115]
	v_mfma_f32_16x16x32_bf16 v[100:103], v[172:175], v[212:215], v[100:103]
	v_mfma_f32_16x16x32_bf16 v[96:99], v[196:199], v[212:215], v[96:99]
	v_mfma_f32_16x16x32_bf16 v[84:87], v[172:175], v[220:223], v[84:87]
	v_mfma_f32_16x16x32_bf16 v[80:83], v[196:199], v[220:223], v[80:83]
	v_mfma_f32_16x16x32_bf16 v[72:75], v[172:175], v[228:231], v[72:75]
	v_mfma_f32_16x16x32_bf16 v[68:71], v[196:199], v[228:231], v[68:71]
	v_mfma_f32_16x16x32_bf16 v[116:119], v[190:193], v[208:211], v[116:119]
	v_mfma_f32_16x16x32_bf16 v[112:115], v[200:203], v[208:211], v[112:115]
	v_mfma_f32_16x16x32_bf16 v[100:103], v[190:193], v[216:219], v[100:103]
	v_mfma_f32_16x16x32_bf16 v[96:99], v[200:203], v[216:219], v[96:99]
	v_mfma_f32_16x16x32_bf16 v[84:87], v[190:193], v[224:227], v[84:87]
	v_mfma_f32_16x16x32_bf16 v[80:83], v[200:203], v[224:227], v[80:83]
	v_mfma_f32_16x16x32_bf16 v[72:75], v[190:193], v[232:235], v[72:75]
	v_mfma_f32_16x16x32_bf16 v[68:71], v[200:203], v[232:235], v[68:71]
.Lgt_p_2_done:
	s_barrier
	s_add_i32 s0, s0, s20
	v_lshl_add_u64 v[152:153], v[152:153], 0, s[30:31]
	s_mov_b32 m0, s0
	ds_read_b128 v[204:207], v162 offset:49152
	ds_read_b128 v[208:211], v162 offset:50176
	ds_read_b128 v[212:215], v162 offset:51200
	ds_read_b128 v[216:219], v162 offset:52224
	ds_read_b128 v[220:223], v162 offset:53248
	ds_read_b128 v[224:227], v162 offset:54272
	ds_read_b128 v[228:231], v162 offset:55296
	ds_read_b128 v[232:235], v162 offset:56320
	global_load_lds_dwordx4 v[152:153], off
	s_add_i32 m0, s0, 0x2000
	s_add_u32 s6, s6, 0x40080
	v_lshl_add_u64 v[152:153], v[176:177], 0, s[30:31]
	s_addc_u32 s7, s7, 0
	s_add_i32 s0, s26, s20
	global_load_lds_dwordx4 v[152:153], off
	v_lshl_add_u64 v[152:153], s[6:7], 0, v[160:161]
	s_mov_b32 m0, s0
	s_nop 0
	global_load_lds_dwordx4 v[152:153], off
	v_lshl_add_u64 v[152:153], s[6:7], 0, v[136:137]
	s_add_i32 m0, s0, 0x2000
	s_nop 0
	global_load_lds_dwordx4 v[152:153], off
	v_lshl_add_u64 v[152:153], v[236:237], 0, s[30:31]
	s_mov_b32 m0, s33
	s_nop 0
	global_load_lds_dwordx4 v[152:153], off
	v_lshl_add_u64 v[152:153], v[238:239], 0, s[30:31]
	s_mov_b32 m0, s54
	s_nop 0
	global_load_lds_dwordx4 v[152:153], off
	s_cmp_lg_u32 s101, 0
	s_waitcnt vmcnt(8)
	s_waitcnt lgkmcnt(0)
	s_barrier
	s_cbranch_scc1 .Lgt_p_3
	v_mfma_f32_16x16x32_bf16 v[64:67], v[144:147], v[204:207], v[64:67]
	v_mfma_f32_16x16x32_bf16 v[60:63], v[164:167], v[204:207], v[60:63]
	v_mfma_f32_16x16x32_bf16 v[56:59], v[144:147], v[212:215], v[56:59]
	v_mfma_f32_16x16x32_bf16 v[44:47], v[164:167], v[212:215], v[44:47]
	v_mfma_f32_16x16x32_bf16 v[40:43], v[144:147], v[220:223], v[40:43]
	v_mfma_f32_16x16x32_bf16 v[28:31], v[164:167], v[220:223], v[28:31]
	v_mfma_f32_16x16x32_bf16 v[24:27], v[144:147], v[228:231], v[24:27]
	v_mfma_f32_16x16x32_bf16 v[12:15], v[164:167], v[228:231], v[12:15]
	v_mfma_f32_16x16x32_bf16 v[64:67], v[148:151], v[208:211], v[64:67]
	v_mfma_f32_16x16x32_bf16 v[60:63], v[168:171], v[208:211], v[60:63]
	v_mfma_f32_16x16x32_bf16 v[56:59], v[148:151], v[216:219], v[56:59]
	v_mfma_f32_16x16x32_bf16 v[44:47], v[168:171], v[216:219], v[44:47]
	v_mfma_f32_16x16x32_bf16 v[40:43], v[148:151], v[224:227], v[40:43]
	v_mfma_f32_16x16x32_bf16 v[28:31], v[168:171], v[224:227], v[28:31]
	v_mfma_f32_16x16x32_bf16 v[24:27], v[148:151], v[232:235], v[24:27]
	v_mfma_f32_16x16x32_bf16 v[12:15], v[168:171], v[232:235], v[12:15]
	v_mfma_f32_16x16x32_bf16 v[52:55], v[172:175], v[204:207], v[52:55]
	v_mfma_f32_16x16x32_bf16 v[48:51], v[196:199], v[204:207], v[48:51]
	v_mfma_f32_16x16x32_bf16 v[36:39], v[172:175], v[212:215], v[36:39]
	v_mfma_f32_16x16x32_bf16 v[32:35], v[196:199], v[212:215], v[32:35]
	v_mfma_f32_16x16x32_bf16 v[20:23], v[172:175], v[220:223], v[20:23]
	v_mfma_f32_16x16x32_bf16 v[16:19], v[196:199], v[220:223], v[16:19]
	v_mfma_f32_16x16x32_bf16 v[8:11], v[172:175], v[228:231], v[8:11]
	v_mfma_f32_16x16x32_bf16 v[4:7], v[196:199], v[228:231], v[4:7]
	v_mfma_f32_16x16x32_bf16 v[52:55], v[190:193], v[208:211], v[52:55]
	v_mfma_f32_16x16x32_bf16 v[48:51], v[200:203], v[208:211], v[48:51]
	v_mfma_f32_16x16x32_bf16 v[36:39], v[190:193], v[216:219], v[36:39]
	v_mfma_f32_16x16x32_bf16 v[32:35], v[200:203], v[216:219], v[32:35]
	v_mfma_f32_16x16x32_bf16 v[20:23], v[190:193], v[224:227], v[20:23]
	v_mfma_f32_16x16x32_bf16 v[16:19], v[200:203], v[224:227], v[16:19]
	v_mfma_f32_16x16x32_bf16 v[8:11], v[190:193], v[232:235], v[8:11]
	v_mfma_f32_16x16x32_bf16 v[4:7], v[200:203], v[232:235], v[4:7]

; #define PG8_STAGE(bufoff, gbase, voff) do { _Pragma("unroll") for (int _i = 0; _i < 2; ++_i) \
;         __builtin_amdgcn_global_load_lds((const unsigned*)((const char*)(gbase) + (voff)[_i]), (LAS unsigned*)(lds + (bufoff) + ldsw + _i * 8192), 16, 0, 0); } while (0)
; #define PG8_LDA(dst, b, h) do { _Pragma("unroll") for (int m = 0; m < 4; ++m) _Pragma("unroll") for (int k = 0; k < 2; ++k) dst[m][k] = *(const LAS bf16x8*)(lds + PG8_SA(b, h) + aoff + m * 2048 + k * 1024); } while (0)
; #define PG8_LDB(dst, b, h) do { _Pragma("unroll") for (int n = 0; n < 2; ++n) _Pragma("unroll") for (int k = 0; k < 2; ++k) dst[n][k] = *(const LAS bf16x8*)(lds + PG8_SB(b, h) + boff + n * 2048 + k * 1024); } while (0)
; #define PG8_MMA(ai, bj, At, Bt) do { __builtin_amdgcn_s_setprio(1); _Pragma("unroll") for (int m = 0; m < 4; ++m) _Pragma("unroll") for (int n = 0; n < 2; ++n) _Pragma("unroll") for (int k = 0; k < 2; ++k) \
;         acc[ai][bj][m][n] = __builtin_amdgcn_mfma_f32_16x16x32_bf16(Bt[n][k], At[m][k], acc[ai][bj][m][n], 0, 0, 0); __builtin_amdgcn_s_setprio(0); } while (0)
; #define PG8_WAIT_V(n) asm volatile("s_waitcnt vmcnt(" #n ")" ::: "memory")
; #define PG8_WAIT_L(n) asm volatile("s_waitcnt lgkmcnt(" #n ")" ::: "memory")
; #define PG8_BAR __builtin_amdgcn_s_barrier()
; #define PG8_SCHED __builtin_amdgcn_sched_barrier(0)
; template <class Epi, class Sched>
; __device__ __forceinline__ void gemm_phase(LAS unsigned char* lds, const Gemm g, const Sched& S, const Epi& E) {
;     ...
;         for (int t = 0; t < nt; t += 2) {
;             const bool last = (t == nt - 2);
;             const char* a1 = cA + (size_t)(t + 1) * kstep;
;             const char* a2 = last ? nA : cA + (size_t)(t + 2) * kstep; const char* b2 = last ? nB : cB + (size_t)(t + 2) * kstep;
;             const char* a3 = a2 + kstep; const char* b3 = b2 + kstep;
;             PG8_LDB(B0, 0, 0); PG8_LDB(B1, 0, 1); PG8_SCHED; PG8_LDA(At, 0, 0); PG8_STAGE(PG8_SA(1, 1), a1 + hstepA, voffA);
;             PG8_WAIT_V(8); PG8_WAIT_L(0); PG8_BAR; PG8_MMA(0, 0, At, B0); PG8_MMA(0, 1, At, B1); PG8_BAR; PG8_SCHED;
.LBB0_96:
	s_add_u32 s0, s42, 0xfffc0080
	s_addc_u32 s6, s43, -1
	s_add_i32 s26, 0, 0x10000
	s_cmp_eq_u32 s69, 12
	s_cselect_b32 s15, s13, s6
	s_cselect_b32 s14, s57, s0
	v_add_u32_e32 v152, s26, v156
	s_cselect_b32 s7, s45, s53
	s_cselect_b32 s6, s68, s52
	s_add_i32 s0, 0, 0x14000
	ds_read_b128 v[144:147], v152
	ds_read_b128 v[148:151], v152 offset:1024
	ds_read_b128 v[164:167], v152 offset:2048
	ds_read_b128 v[168:171], v152 offset:3072
	v_add_u32_e32 v152, s0, v156
	ds_read_b128 v[172:175], v152
	ds_read_b128 v[190:193], v152 offset:1024
	ds_read_b128 v[196:199], v152 offset:2048
	ds_read_b128 v[200:203], v152 offset:3072
	v_lshl_add_u64 v[152:153], s[42:43], 0, v[140:141]
	s_add_i32 m0, s21, 0xc000
	ds_read_b128 v[204:207], v162
	ds_read_b128 v[208:211], v162 offset:1024
	ds_read_b128 v[212:215], v162 offset:2048
	ds_read_b128 v[216:219], v162 offset:3072
	ds_read_b128 v[220:223], v162 offset:4096
	ds_read_b128 v[224:227], v162 offset:5120
	ds_read_b128 v[228:231], v162 offset:6144
	ds_read_b128 v[232:235], v162 offset:7168
	global_load_lds_dwordx4 v[152:153], off
	v_lshl_add_u64 v[152:153], s[42:43], 0, v[142:143]
	s_add_i32 m0, s21, 0xe000
	s_nop 0
	global_load_lds_dwordx4 v[152:153], off
	s_cmp_lg_u32 s101, 0
	s_waitcnt vmcnt(8)
	s_waitcnt lgkmcnt(0)
	s_barrier
	s_cbranch_scc1 .Lgt_l_0
	v_mfma_f32_16x16x32_bf16 v[128:131], v[144:147], v[204:207], v[128:131]
	v_mfma_f32_16x16x32_bf16 v[124:127], v[164:167], v[204:207], v[124:127]
	v_mfma_f32_16x16x32_bf16 v[120:123], v[144:147], v[212:215], v[120:123]
	v_mfma_f32_16x16x32_bf16 v[108:111], v[164:167], v[212:215], v[108:111]
	v_mfma_f32_16x16x32_bf16 v[104:107], v[144:147], v[220:223], v[104:107]
	v_mfma_f32_16x16x32_bf16 v[92:95], v[164:167], v[220:223], v[92:95]
	v_mfma_f32_16x16x32_bf16 v[88:91], v[144:147], v[228:231], v[88:91]
	v_mfma_f32_16x16x32_bf16 v[76:79], v[164:167], v[228:231], v[76:79]
	v_mfma_f32_16x16x32_bf16 v[128:131], v[148:151], v[208:211], v[128:131]
	v_mfma_f32_16x16x32_bf16 v[124:127], v[168:171], v[208:211], v[124:127]
	v_mfma_f32_16x16x32_bf16 v[120:123], v[148:151], v[216:219], v[120:123]
	v_mfma_f32_16x16x32_bf16 v[108:111], v[168:171], v[216:219], v[108:111]
	v_mfma_f32_16x16x32_bf16 v[104:107], v[148:151], v[224:227], v[104:107]
	v_mfma_f32_16x16x32_bf16 v[92:95], v[168:171], v[224:227], v[92:95]
	v_mfma_f32_16x16x32_bf16 v[88:91], v[148:151], v[232:235], v[88:91]
	v_mfma_f32_16x16x32_bf16 v[76:79], v[168:171], v[232:235], v[76:79]
	v_mfma_f32_16x16x32_bf16 v[116:119], v[172:175], v[204:207], v[116:119]
	v_mfma_f32_16x16x32_bf16 v[112:115], v[196:199], v[204:207], v[112:115]
	v_mfma_f32_16x16x32_bf16 v[100:103], v[172:175], v[212:215], v[100:103]
	v_mfma_f32_16x16x32_bf16 v[96:99], v[196:199], v[212:215], v[96:99]
	v_mfma_f32_16x16x32_bf16 v[84:87], v[172:175], v[220:223], v[84:87]
	v_mfma_f32_16x16x32_bf16 v[80:83], v[196:199], v[220:223], v[80:83]
	v_mfma_f32_16x16x32_bf16 v[72:75], v[172:175], v[228:231], v[72:75]
	v_mfma_f32_16x16x32_bf16 v[68:71], v[196:199], v[228:231], v[68:71]
	v_mfma_f32_16x16x32_bf16 v[116:119], v[190:193], v[208:211], v[116:119]
	v_mfma_f32_16x16x32_bf16 v[112:115], v[200:203], v[208:211], v[112:115]
	v_mfma_f32_16x16x32_bf16 v[100:103], v[190:193], v[216:219], v[100:103]
	v_mfma_f32_16x16x32_bf16 v[96:99], v[200:203], v[216:219], v[96:99]
	v_mfma_f32_16x16x32_bf16 v[84:87], v[190:193], v[224:227], v[84:87]
	v_mfma_f32_16x16x32_bf16 v[80:83], v[200:203], v[224:227], v[80:83]
	v_mfma_f32_16x16x32_bf16 v[72:75], v[190:193], v[232:235], v[72:75]
	v_mfma_f32_16x16x32_bf16 v[68:71], v[200:203], v[232:235], v[68:71]
; #define PG8_STAGE(bufoff, gbase, voff) do { _Pragma("unroll") for (int _i = 0; _i < 2; ++_i) \
;         __builtin_amdgcn_global_load_lds((const unsigned*)((const char*)(gbase) + (voff)[_i]), (LAS unsigned*)(lds + (bufoff) + ldsw + _i * 8192), 16, 0, 0); } while (0)
; #define PG8_LDA(dst, b, h) do { _Pragma("unroll") for (int m = 0; m < 4; ++m) _Pragma("unroll") for (int k = 0; k < 2; ++k) dst[m][k] = *(const LAS bf16x8*)(lds + PG8_SA(b, h) + aoff + m * 2048 + k * 1024); } while (0)
; #define PG8_MMA(ai, bj, At, Bt) do { __builtin_amdgcn_s_setprio(1); _Pragma("unroll") for (int m = 0; m < 4; ++m) _Pragma("unroll") for (int n = 0; n < 2; ++n) _Pragma("unroll") for (int k = 0; k < 2; ++k) \
;         acc[ai][bj][m][n] = __builtin_amdgcn_mfma_f32_16x16x32_bf16(Bt[n][k], At[m][k], acc[ai][bj][m][n], 0, 0, 0); __builtin_amdgcn_s_setprio(0); } while (0)
; #define PG8_WAIT_V(n) asm volatile("s_waitcnt vmcnt(" #n ")" ::: "memory")
; #define PG8_WAIT_L(n) asm volatile("s_waitcnt lgkmcnt(" #n ")" ::: "memory")
; #define PG8_BAR __builtin_amdgcn_s_barrier()
; #define PG8_SCHED __builtin_amdgcn_sched_barrier(0)
; template <class Epi, class Sched>
; __device__ __forceinline__ void gemm_phase(LAS unsigned char* lds, const Gemm g, const Sched& S, const Epi& E) {
;     ...
;             PG8_LDA(At, 0, 1); PG8_STAGE(PG8_SB(0, 0), b2, voffB); PG8_STAGE(PG8_SB(0, 1), b2 + hstepB, voffB); PG8_STAGE(PG8_SA(0, 0), a2, voffA);
;             PG8_WAIT_V(8); PG8_WAIT_L(0); PG8_BAR; PG8_MMA(1, 0, At, B0); PG8_MMA(1, 1, At, B1); PG8_BAR; PG8_SCHED;
.Lgt_l_0_done:
	s_barrier
	s_add_i32 s26, s26, s20
	v_lshl_add_u64 v[152:153], s[6:7], 0, v[160:161]
	s_mov_b32 m0, s26
	ds_read_b128 v[204:207], v162 offset:16384
	ds_read_b128 v[208:211], v162 offset:17408
	ds_read_b128 v[212:215], v162 offset:18432
	ds_read_b128 v[216:219], v162 offset:19456
	ds_read_b128 v[220:223], v162 offset:20480
	ds_read_b128 v[224:227], v162 offset:21504
	ds_read_b128 v[228:231], v162 offset:22528
	ds_read_b128 v[232:235], v162 offset:23552
	global_load_lds_dwordx4 v[152:153], off
	s_add_i32 m0, s26, 0x2000
	s_add_u32 s78, s6, 0x40000
	v_lshl_add_u64 v[176:177], s[6:7], 0, v[136:137]
	s_addc_u32 s79, s7, 0
	s_add_i32 s0, s0, s20
	global_load_lds_dwordx4 v[176:177], off
	v_lshl_add_u64 v[236:237], s[78:79], 0, v[160:161]
	s_mov_b32 m0, s0
	v_lshl_add_u64 v[238:239], s[14:15], 0, v[134:135]
	global_load_lds_dwordx4 v[236:237], off
	v_lshl_add_u64 v[236:237], s[78:79], 0, v[136:137]
	s_add_i32 m0, s0, 0x2000
	s_nop 0
	global_load_lds_dwordx4 v[236:237], off
	v_lshl_add_u64 v[236:237], s[14:15], 0, v[132:133]
	s_mov_b32 m0, s21
	s_nop 0
	global_load_lds_dwordx4 v[236:237], off
	s_mov_b32 m0, s24
	s_nop 0
	global_load_lds_dwordx4 v[238:239], off
	s_cmp_lg_u32 s101, 0
	s_waitcnt vmcnt(8)
	s_waitcnt lgkmcnt(0)
	s_barrier
	s_cbranch_scc1 .Lgt_l_1
	v_mfma_f32_16x16x32_bf16 v[64:67], v[144:147], v[204:207], v[64:67]
	v_mfma_f32_16x16x32_bf16 v[60:63], v[164:167], v[204:207], v[60:63]
	v_mfma_f32_16x16x32_bf16 v[56:59], v[144:147], v[212:215], v[56:59]
	v_mfma_f32_16x16x32_bf16 v[44:47], v[164:167], v[212:215], v[44:47]
	v_mfma_f32_16x16x32_bf16 v[40:43], v[144:147], v[220:223], v[40:43]
	v_mfma_f32_16x16x32_bf16 v[28:31], v[164:167], v[220:223], v[28:31]
	v_mfma_f32_16x16x32_bf16 v[24:27], v[144:147], v[228:231], v[24:27]
	v_mfma_f32_16x16x32_bf16 v[12:15], v[164:167], v[228:231], v[12:15]
	v_mfma_f32_16x16x32_bf16 v[64:67], v[148:151], v[208:211], v[64:67]
	v_mfma_f32_16x16x32_bf16 v[60:63], v[168:171], v[208:211], v[60:63]
	v_mfma_f32_16x16x32_bf16 v[56:59], v[148:151], v[216:219], v[56:59]
	v_mfma_f32_16x16x32_bf16 v[44:47], v[168:171], v[216:219], v[44:47]
	v_mfma_f32_16x16x32_bf16 v[40:43], v[148:151], v[224:227], v[40:43]
	v_mfma_f32_16x16x32_bf16 v[28:31], v[168:171], v[224:227], v[28:31]
	v_mfma_f32_16x16x32_bf16 v[24:27], v[148:151], v[232:235], v[24:27]
	v_mfma_f32_16x16x32_bf16 v[12:15], v[168:171], v[232:235], v[12:15]
	v_mfma_f32_16x16x32_bf16 v[52:55], v[172:175], v[204:207], v[52:55]
	v_mfma_f32_16x16x32_bf16 v[48:51], v[196:199], v[204:207], v[48:51]
	v_mfma_f32_16x16x32_bf16 v[36:39], v[172:175], v[212:215], v[36:39]
	v_mfma_f32_16x16x32_bf16 v[32:35], v[196:199], v[212:215], v[32:35]
	v_mfma_f32_16x16x32_bf16 v[20:23], v[172:175], v[220:223], v[20:23]
	v_mfma_f32_16x16x32_bf16 v[16:19], v[196:199], v[220:223], v[16:19]
	v_mfma_f32_16x16x32_bf16 v[8:11], v[172:175], v[228:231], v[8:11]
	v_mfma_f32_16x16x32_bf16 v[4:7], v[196:199], v[228:231], v[4:7]
	v_mfma_f32_16x16x32_bf16 v[52:55], v[190:193], v[208:211], v[52:55]
	v_mfma_f32_16x16x32_bf16 v[48:51], v[200:203], v[208:211], v[48:51]
	v_mfma_f32_16x16x32_bf16 v[36:39], v[190:193], v[216:219], v[36:39]
	v_mfma_f32_16x16x32_bf16 v[32:35], v[200:203], v[216:219], v[32:35]
	v_mfma_f32_16x16x32_bf16 v[20:23], v[190:193], v[224:227], v[20:23]
	v_mfma_f32_16x16x32_bf16 v[16:19], v[200:203], v[224:227], v[16:19]
	v_mfma_f32_16x16x32_bf16 v[8:11], v[190:193], v[232:235], v[8:11]
	v_mfma_f32_16x16x32_bf16 v[4:7], v[200:203], v[232:235], v[4:7]

; #define PG8_STAGE(bufoff, gbase, voff) do { _Pragma("unroll") for (int _i = 0; _i < 2; ++_i) \
;         __builtin_amdgcn_global_load_lds((const unsigned*)((const char*)(gbase) + (voff)[_i]), (LAS unsigned*)(lds + (bufoff) + ldsw + _i * 8192), 16, 0, 0); } while (0)
; #define PG8_LDA(dst, b, h) do { _Pragma("unroll") for (int m = 0; m < 4; ++m) _Pragma("unroll") for (int k = 0; k < 2; ++k) dst[m][k] = *(const LAS bf16x8*)(lds + PG8_SA(b, h) + aoff + m * 2048 + k * 1024); } while (0)
; #define PG8_LDB(dst, b, h) do { _Pragma("unroll") for (int n = 0; n < 2; ++n) _Pragma("unroll") for (int k = 0; k < 2; ++k) dst[n][k] = *(const LAS bf16x8*)(lds + PG8_SB(b, h) + boff + n * 2048 + k * 1024); } while (0)
; #define PG8_MMA(ai, bj, At, Bt) do { __builtin_amdgcn_s_setprio(1); _Pragma("unroll") for (int m = 0; m < 4; ++m) _Pragma("unroll") for (int n = 0; n < 2; ++n) _Pragma("unroll") for (int k = 0; k < 2; ++k) \
;         acc[ai][bj][m][n] = __builtin_amdgcn_mfma_f32_16x16x32_bf16(Bt[n][k], At[m][k], acc[ai][bj][m][n], 0, 0, 0); __builtin_amdgcn_s_setprio(0); } while (0)
; #define PG8_WAIT_V(n) asm volatile("s_waitcnt vmcnt(" #n ")" ::: "memory")
; #define PG8_WAIT_L(n) asm volatile("s_waitcnt lgkmcnt(" #n ")" ::: "memory")
; #define PG8_BAR __builtin_amdgcn_s_barrier()
; #define PG8_SCHED __builtin_amdgcn_sched_barrier(0)
; template <class Epi, class Sched>
; __device__ __forceinline__ void gemm_phase(LAS unsigned char* lds, const Gemm g, const Sched& S, const Epi& E) {
;     ...
;         for (int t = 0; t < nt; t += 2) {
;             const bool last = (t == nt - 2);
;             const char* a1 = cA + (size_t)(t + 1) * kstep;
;             const char* a2 = last ? nA : cA + (size_t)(t + 2) * kstep; const char* b2 = last ? nB : cB + (size_t)(t + 2) * kstep;
;             const char* a3 = a2 + kstep; const char* b3 = b2 + kstep;
;             PG8_LDB(B0, 0, 0); PG8_LDB(B1, 0, 1); PG8_SCHED; PG8_LDA(At, 0, 0); PG8_STAGE(PG8_SA(1, 1), a1 + hstepA, voffA);
;             PG8_WAIT_V(8); PG8_WAIT_L(0); PG8_BAR; PG8_MMA(0, 0, At, B0); PG8_MMA(0, 1, At, B1); PG8_BAR; PG8_SCHED;
;             PG8_LDA(At, 0, 1); PG8_STAGE(PG8_SB(0, 0), b2, voffB); PG8_STAGE(PG8_SB(0, 1), b2 + hstepB, voffB); PG8_STAGE(PG8_SA(0, 0), a2, voffA);
;             PG8_WAIT_V(8); PG8_WAIT_L(0); PG8_BAR; PG8_MMA(1, 0, At, B0); PG8_MMA(1, 1, At, B1); PG8_BAR; PG8_SCHED;
.Lprio_358:
	s_add_u32 s0, s52, 0xfffc0080
	s_addc_u32 s6, s53, -1
	s_add_i32 s26, 0, 0x10000
	s_cmp_eq_u32 s54, 12
	s_cselect_b32 s15, s9, s6
	s_cselect_b32 s14, s13, s0
	s_cselect_b32 s7, s21, s43
	s_cselect_b32 s6, s23, s33
	s_add_i32 s0, 0, 0x14000
	v_add_u32_e32 v140, s26, v186
	v_add_u32_e32 v168, s0, v186
	ds_read_b128 v[128:131], v140
	ds_read_b128 v[132:135], v140 offset:1024
	ds_read_b128 v[136:139], v140 offset:2048
	ds_read_b128 v[140:143], v140 offset:3072
	ds_read_b128 v[144:147], v168
	ds_read_b128 v[148:151], v168 offset:1024
	ds_read_b128 v[152:155], v168 offset:2048
	ds_read_b128 v[168:171], v168 offset:3072
	v_lshl_add_u64 v[226:227], s[52:53], 0, v[164:165]
	s_add_i32 m0, s51, 0xc000
	ds_read_b128 v[172:175], v196
	ds_read_b128 v[198:201], v196 offset:1024
	ds_read_b128 v[202:205], v196 offset:2048
	ds_read_b128 v[206:209], v196 offset:3072
	ds_read_b128 v[210:213], v196 offset:4096
	ds_read_b128 v[214:217], v196 offset:5120
	ds_read_b128 v[218:221], v196 offset:6144
	ds_read_b128 v[222:225], v196 offset:7168
	global_load_lds_dwordx4 v[226:227], off
	v_lshl_add_u64 v[226:227], s[52:53], 0, v[166:167]
	s_add_i32 m0, s51, 0xe000
	s_nop 0
	global_load_lds_dwordx4 v[226:227], off
	s_waitcnt vmcnt(8)
	s_waitcnt lgkmcnt(0)
	s_barrier
	v_mfma_f32_16x16x32_bf16 v[124:127], v[128:131], v[172:175], 0
	v_mfma_f32_16x16x32_bf16 v[120:123], v[136:139], v[172:175], 0
	v_mfma_f32_16x16x32_bf16 v[108:111], v[128:131], v[202:205], 0
	v_mfma_f32_16x16x32_bf16 v[104:107], v[136:139], v[202:205], 0
	v_mfma_f32_16x16x32_bf16 v[92:95], v[128:131], v[210:213], 0
	v_mfma_f32_16x16x32_bf16 v[88:91], v[136:139], v[210:213], 0
	v_mfma_f32_16x16x32_bf16 v[76:79], v[128:131], v[218:221], 0
	v_mfma_f32_16x16x32_bf16 v[72:75], v[136:139], v[218:221], 0
	v_mfma_f32_16x16x32_bf16 v[124:127], v[132:135], v[198:201], v[124:127]
	v_mfma_f32_16x16x32_bf16 v[120:123], v[140:143], v[198:201], v[120:123]
	v_mfma_f32_16x16x32_bf16 v[108:111], v[132:135], v[206:209], v[108:111]
	v_mfma_f32_16x16x32_bf16 v[104:107], v[140:143], v[206:209], v[104:107]
	v_mfma_f32_16x16x32_bf16 v[92:95], v[132:135], v[214:217], v[92:95]
	v_mfma_f32_16x16x32_bf16 v[88:91], v[140:143], v[214:217], v[88:91]
	v_mfma_f32_16x16x32_bf16 v[76:79], v[132:135], v[222:225], v[76:79]
	v_mfma_f32_16x16x32_bf16 v[72:75], v[140:143], v[222:225], v[72:75]
	v_mfma_f32_16x16x32_bf16 v[116:119], v[144:147], v[172:175], 0
	v_mfma_f32_16x16x32_bf16 v[112:115], v[152:155], v[172:175], 0
	v_mfma_f32_16x16x32_bf16 v[100:103], v[144:147], v[202:205], 0
	v_mfma_f32_16x16x32_bf16 v[96:99], v[152:155], v[202:205], 0
	v_mfma_f32_16x16x32_bf16 v[84:87], v[144:147], v[210:213], 0
	v_mfma_f32_16x16x32_bf16 v[80:83], v[152:155], v[210:213], 0
	v_mfma_f32_16x16x32_bf16 v[68:71], v[144:147], v[218:221], 0
	v_mfma_f32_16x16x32_bf16 v[64:67], v[152:155], v[218:221], 0
	v_mfma_f32_16x16x32_bf16 v[116:119], v[148:151], v[198:201], v[116:119]
	v_mfma_f32_16x16x32_bf16 v[112:115], v[168:171], v[198:201], v[112:115]
	v_mfma_f32_16x16x32_bf16 v[100:103], v[148:151], v[206:209], v[100:103]
	v_mfma_f32_16x16x32_bf16 v[96:99], v[168:171], v[206:209], v[96:99]
	v_mfma_f32_16x16x32_bf16 v[84:87], v[148:151], v[214:217], v[84:87]
	v_mfma_f32_16x16x32_bf16 v[80:83], v[168:171], v[214:217], v[80:83]
	v_mfma_f32_16x16x32_bf16 v[68:71], v[148:151], v[222:225], v[68:71]
	v_mfma_f32_16x16x32_bf16 v[64:67], v[168:171], v[222:225], v[64:67]
	s_barrier
	s_add_i32 s26, s26, s20
	v_lshl_add_u64 v[226:227], s[6:7], 0, v[160:161]
	s_mov_b32 m0, s26
	ds_read_b128 v[172:175], v196 offset:16384
	ds_read_b128 v[198:201], v196 offset:17408
	ds_read_b128 v[202:205], v196 offset:18432
	ds_read_b128 v[206:209], v196 offset:19456
	ds_read_b128 v[210:213], v196 offset:20480
	ds_read_b128 v[214:217], v196 offset:21504
	ds_read_b128 v[218:221], v196 offset:22528
	ds_read_b128 v[222:225], v196 offset:23552
	global_load_lds_dwordx4 v[226:227], off
	s_add_i32 m0, s26, 0x2000
	s_add_u32 s78, s6, 0x40000
	v_lshl_add_u64 v[228:229], s[6:7], 0, v[162:163]
	s_addc_u32 s79, s7, 0
	s_add_i32 s0, s0, s20
	global_load_lds_dwordx4 v[228:229], off
	v_lshl_add_u64 v[230:231], s[78:79], 0, v[160:161]
	s_mov_b32 m0, s0
	v_lshl_add_u64 v[232:233], s[14:15], 0, v[158:159]
	global_load_lds_dwordx4 v[230:231], off
	v_lshl_add_u64 v[230:231], s[78:79], 0, v[162:163]
	s_add_i32 m0, s0, 0x2000
	s_nop 0
	global_load_lds_dwordx4 v[230:231], off
	v_lshl_add_u64 v[230:231], s[14:15], 0, v[156:157]
	s_mov_b32 m0, s51
	s_nop 0
	global_load_lds_dwordx4 v[230:231], off
	s_mov_b32 m0, s56
	s_nop 0
	global_load_lds_dwordx4 v[232:233], off
	s_waitcnt vmcnt(8)
	s_waitcnt lgkmcnt(0)
	s_barrier
; #define PG8_STAGE(bufoff, gbase, voff) do { _Pragma("unroll") for (int _i = 0; _i < 2; ++_i) \
;         __builtin_amdgcn_global_load_lds((const unsigned*)((const char*)(gbase) + (voff)[_i]), (LAS unsigned*)(lds + (bufoff) + ldsw + _i * 8192), 16, 0, 0); } while (0)
; #define PG8_LDA(dst, b, h) do { _Pragma("unroll") for (int m = 0; m < 4; ++m) _Pragma("unroll") for (int k = 0; k < 2; ++k) dst[m][k] = *(const LAS bf16x8*)(lds + PG8_SA(b, h) + aoff + m * 2048 + k * 1024); } while (0)
; #define PG8_LDB(dst, b, h) do { _Pragma("unroll") for (int n = 0; n < 2; ++n) _Pragma("unroll") for (int k = 0; k < 2; ++k) dst[n][k] = *(const LAS bf16x8*)(lds + PG8_SB(b, h) + boff + n * 2048 + k * 1024); } while (0)
; #define PG8_MMA(ai, bj, At, Bt) do { __builtin_amdgcn_s_setprio(1); _Pragma("unroll") for (int m = 0; m < 4; ++m) _Pragma("unroll") for (int n = 0; n < 2; ++n) _Pragma("unroll") for (int k = 0; k < 2; ++k) \
;         acc[ai][bj][m][n] = __builtin_amdgcn_mfma_f32_16x16x32_bf16(Bt[n][k], At[m][k], acc[ai][bj][m][n], 0, 0, 0); __builtin_amdgcn_s_setprio(0); } while (0)
; #define PG8_WAIT_V(n) asm volatile("s_waitcnt vmcnt(" #n ")" ::: "memory")
; #define PG8_WAIT_L(n) asm volatile("s_waitcnt lgkmcnt(" #n ")" ::: "memory")
; #define PG8_BAR __builtin_amdgcn_s_barrier()
; #define PG8_SCHED __builtin_amdgcn_sched_barrier(0)
; template <class Epi, class Sched>
; __device__ __forceinline__ void gemm_phase(LAS unsigned char* lds, const Gemm g, const Sched& S, const Epi& E) {
;     ...
;             PG8_WAIT_V(8); PG8_WAIT_L(0); PG8_BAR; PG8_MMA(1, 0, At, B0); PG8_MMA(1, 1, At, B1); PG8_BAR; PG8_SCHED;
;             PG8_LDB(B0, 1, 0); PG8_LDB(B1, 1, 1); PG8_SCHED; PG8_LDA(At, 1, 0); PG8_STAGE(PG8_SA(0, 1), a2 + hstepA, voffA);
;             PG8_WAIT_V(8); PG8_WAIT_L(0); PG8_BAR; PG8_MMA(0, 0, At, B0); PG8_MMA(0, 1, At, B1); PG8_BAR; PG8_SCHED;
	v_mfma_f32_16x16x32_bf16 v[60:63], v[128:131], v[172:175], 0
	v_mfma_f32_16x16x32_bf16 v[56:59], v[136:139], v[172:175], 0
	v_mfma_f32_16x16x32_bf16 v[44:47], v[128:131], v[202:205], 0
	v_mfma_f32_16x16x32_bf16 v[40:43], v[136:139], v[202:205], 0
	v_mfma_f32_16x16x32_bf16 v[28:31], v[128:131], v[210:213], 0
	v_mfma_f32_16x16x32_bf16 v[24:27], v[136:139], v[210:213], 0
	v_mfma_f32_16x16x32_bf16 v[12:15], v[128:131], v[218:221], 0
	v_mfma_f32_16x16x32_bf16 v[8:11], v[136:139], v[218:221], 0
	v_mfma_f32_16x16x32_bf16 v[60:63], v[132:135], v[198:201], v[60:63]
	v_mfma_f32_16x16x32_bf16 v[56:59], v[140:143], v[198:201], v[56:59]
	v_mfma_f32_16x16x32_bf16 v[44:47], v[132:135], v[206:209], v[44:47]
	v_mfma_f32_16x16x32_bf16 v[40:43], v[140:143], v[206:209], v[40:43]
	v_mfma_f32_16x16x32_bf16 v[28:31], v[132:135], v[214:217], v[28:31]
	v_mfma_f32_16x16x32_bf16 v[24:27], v[140:143], v[214:217], v[24:27]
	v_mfma_f32_16x16x32_bf16 v[12:15], v[132:135], v[222:225], v[12:15]
	v_mfma_f32_16x16x32_bf16 v[8:11], v[140:143], v[222:225], v[8:11]
	v_mfma_f32_16x16x32_bf16 v[52:55], v[144:147], v[172:175], 0
	v_mfma_f32_16x16x32_bf16 v[48:51], v[152:155], v[172:175], 0
	v_mfma_f32_16x16x32_bf16 v[36:39], v[144:147], v[202:205], 0
	v_mfma_f32_16x16x32_bf16 v[32:35], v[152:155], v[202:205], 0
	v_mfma_f32_16x16x32_bf16 v[20:23], v[144:147], v[210:213], 0
	v_mfma_f32_16x16x32_bf16 v[16:19], v[152:155], v[210:213], 0
	v_mfma_f32_16x16x32_bf16 v[4:7], v[144:147], v[218:221], 0
	v_mfma_f32_16x16x32_bf16 v[0:3], v[152:155], v[218:221], 0
	v_mfma_f32_16x16x32_bf16 v[52:55], v[148:151], v[198:201], v[52:55]
	v_mfma_f32_16x16x32_bf16 v[48:51], v[168:171], v[198:201], v[48:51]
	v_mfma_f32_16x16x32_bf16 v[36:39], v[148:151], v[206:209], v[36:39]
	v_mfma_f32_16x16x32_bf16 v[32:35], v[168:171], v[206:209], v[32:35]
	v_mfma_f32_16x16x32_bf16 v[20:23], v[148:151], v[214:217], v[20:23]
	v_mfma_f32_16x16x32_bf16 v[16:19], v[168:171], v[214:217], v[16:19]
	v_mfma_f32_16x16x32_bf16 v[4:7], v[148:151], v[222:225], v[4:7]
	v_mfma_f32_16x16x32_bf16 v[0:3], v[168:171], v[222:225], v[0:3]
	s_barrier
	s_add_i32 s0, 0, 0x18000
	s_add_i32 s26, 0, 0x1c000
	v_add_u32_e32 v140, s0, v186
	v_add_u32_e32 v168, s26, v186
	ds_read_b128 v[128:131], v140
	ds_read_b128 v[132:135], v140 offset:1024
	ds_read_b128 v[136:139], v140 offset:2048
	ds_read_b128 v[140:143], v140 offset:3072
	ds_read_b128 v[144:147], v168
	ds_read_b128 v[148:151], v168 offset:1024
	ds_read_b128 v[152:155], v168 offset:2048
	ds_read_b128 v[168:171], v168 offset:3072
	s_add_u32 s14, s14, 0x40000
	s_addc_u32 s15, s15, 0
	s_mov_b32 m0, s57
	v_lshl_add_u64 v[234:235], s[14:15], 0, v[156:157]
	ds_read_b128 v[172:175], v196 offset:32768
	ds_read_b128 v[198:201], v196 offset:33792
	ds_read_b128 v[202:205], v196 offset:34816
	ds_read_b128 v[206:209], v196 offset:35840
	ds_read_b128 v[210:213], v196 offset:36864
	ds_read_b128 v[214:217], v196 offset:37888
	ds_read_b128 v[218:221], v196 offset:38912
	ds_read_b128 v[222:225], v196 offset:39936
	global_load_lds_dwordx4 v[234:235], off
	v_lshl_add_u64 v[234:235], s[14:15], 0, v[158:159]
	s_mov_b32 m0, s68
	s_nop 0
	global_load_lds_dwordx4 v[234:235], off
	s_waitcnt vmcnt(8)
	s_waitcnt lgkmcnt(0)
	s_barrier
	v_mfma_f32_16x16x32_bf16 v[124:127], v[128:131], v[172:175], v[124:127]
	v_mfma_f32_16x16x32_bf16 v[120:123], v[136:139], v[172:175], v[120:123]
	v_mfma_f32_16x16x32_bf16 v[108:111], v[128:131], v[202:205], v[108:111]
	v_mfma_f32_16x16x32_bf16 v[104:107], v[136:139], v[202:205], v[104:107]
	v_mfma_f32_16x16x32_bf16 v[92:95], v[128:131], v[210:213], v[92:95]
	v_mfma_f32_16x16x32_bf16 v[88:91], v[136:139], v[210:213], v[88:91]
	v_mfma_f32_16x16x32_bf16 v[76:79], v[128:131], v[218:221], v[76:79]
	v_mfma_f32_16x16x32_bf16 v[72:75], v[136:139], v[218:221], v[72:75]
	v_mfma_f32_16x16x32_bf16 v[124:127], v[132:135], v[198:201], v[124:127]
	v_mfma_f32_16x16x32_bf16 v[120:123], v[140:143], v[198:201], v[120:123]
	v_mfma_f32_16x16x32_bf16 v[108:111], v[132:135], v[206:209], v[108:111]
	v_mfma_f32_16x16x32_bf16 v[104:107], v[140:143], v[206:209], v[104:107]
	v_mfma_f32_16x16x32_bf16 v[92:95], v[132:135], v[214:217], v[92:95]
	v_mfma_f32_16x16x32_bf16 v[88:91], v[140:143], v[214:217], v[88:91]
	v_mfma_f32_16x16x32_bf16 v[76:79], v[132:135], v[222:225], v[76:79]
	v_mfma_f32_16x16x32_bf16 v[72:75], v[140:143], v[222:225], v[72:75]
	v_mfma_f32_16x16x32_bf16 v[116:119], v[144:147], v[172:175], v[116:119]
	v_mfma_f32_16x16x32_bf16 v[112:115], v[152:155], v[172:175], v[112:115]
	v_mfma_f32_16x16x32_bf16 v[100:103], v[144:147], v[202:205], v[100:103]
	v_mfma_f32_16x16x32_bf16 v[96:99], v[152:155], v[202:205], v[96:99]
	v_mfma_f32_16x16x32_bf16 v[84:87], v[144:147], v[210:213], v[84:87]
	v_mfma_f32_16x16x32_bf16 v[80:83], v[152:155], v[210:213], v[80:83]
	v_mfma_f32_16x16x32_bf16 v[68:71], v[144:147], v[218:221], v[68:71]
	v_mfma_f32_16x16x32_bf16 v[64:67], v[152:155], v[218:221], v[64:67]
	v_mfma_f32_16x16x32_bf16 v[116:119], v[148:151], v[198:201], v[116:119]
	v_mfma_f32_16x16x32_bf16 v[112:115], v[168:171], v[198:201], v[112:115]
	v_mfma_f32_16x16x32_bf16 v[100:103], v[148:151], v[206:209], v[100:103]
	v_mfma_f32_16x16x32_bf16 v[96:99], v[168:171], v[206:209], v[96:99]
	v_mfma_f32_16x16x32_bf16 v[84:87], v[148:151], v[214:217], v[84:87]
	v_mfma_f32_16x16x32_bf16 v[80:83], v[168:171], v[214:217], v[80:83]
	v_mfma_f32_16x16x32_bf16 v[68:71], v[148:151], v[222:225], v[68:71]
	v_mfma_f32_16x16x32_bf16 v[64:67], v[168:171], v[222:225], v[64:67]
	s_barrier
; #define PG8_STAGE(bufoff, gbase, voff) do { _Pragma("unroll") for (int _i = 0; _i < 2; ++_i) \
;         __builtin_amdgcn_global_load_lds((const unsigned*)((const char*)(gbase) + (voff)[_i]), (LAS unsigned*)(lds + (bufoff) + ldsw + _i * 8192), 16, 0, 0); } while (0)
; #define PG8_LDA(dst, b, h) do { _Pragma("unroll") for (int m = 0; m < 4; ++m) _Pragma("unroll") for (int k = 0; k < 2; ++k) dst[m][k] = *(const LAS bf16x8*)(lds + PG8_SA(b, h) + aoff + m * 2048 + k * 1024); } while (0)
; #define PG8_LDB(dst, b, h) do { _Pragma("unroll") for (int n = 0; n < 2; ++n) _Pragma("unroll") for (int k = 0; k < 2; ++k) dst[n][k] = *(const LAS bf16x8*)(lds + PG8_SB(b, h) + boff + n * 2048 + k * 1024); } while (0)
; #define PG8_WAIT_V(n) asm volatile("s_waitcnt vmcnt(" #n ")" ::: "memory")
; #define PG8_BAR __builtin_amdgcn_s_barrier()
; template <class Epi, class Sched>
; __device__ __forceinline__ void gemm_phase(LAS unsigned char* lds, const Gemm g, const Sched& S, const Epi& E) {
;     ...
;         for (int t = 0; t < nt; t += 2) {
;             const bool last = (t == nt - 2);
;             const char* a1 = cA + (size_t)(t + 1) * kstep;
;             const char* a2 = last ? nA : cA + (size_t)(t + 2) * kstep; const char* b2 = last ? nB : cB + (size_t)(t + 2) * kstep;
;             const char* a3 = a2 + kstep; const char* b3 = b2 + kstep;
;             PG8_LDB(B0, 0, 0); PG8_LDB(B1, 0, 1); PG8_SCHED; PG8_LDA(At, 0, 0); PG8_STAGE(PG8_SA(1, 1), a1 + hstepA, voffA);
;             PG8_WAIT_V(8); PG8_WAIT_L(0); PG8_BAR; PG8_MMA(0, 0, At, B0); PG8_MMA(0, 1, At, B1); PG8_BAR; PG8_SCHED;
;             PG8_LDA(At, 0, 1); PG8_STAGE(PG8_SB(0, 0), b2, voffB); PG8_STAGE(PG8_SB(0, 1), b2 + hstepB, voffB); PG8_STAGE(PG8_SA(0, 0), a2, voffA);
;             PG8_WAIT_V(8); PG8_WAIT_L(0); PG8_BAR; PG8_MMA(1, 0, At, B0); PG8_MMA(1, 1, At, B1); PG8_BAR; PG8_SCHED;
;             PG8_LDB(B0, 1, 0); PG8_LDB(B1, 1, 1); PG8_SCHED; PG8_LDA(At, 1, 0); PG8_STAGE(PG8_SA(0, 1), a2 + hstepA, voffA);
;             PG8_WAIT_V(8); PG8_WAIT_L(0); PG8_BAR; PG8_MMA(0, 0, At, B0); PG8_MMA(0, 1, At, B1); PG8_BAR; PG8_SCHED;
;             PG8_LDA(At, 1, 1); PG8_STAGE(PG8_SB(1, 0), b3, voffB); PG8_STAGE(PG8_SB(1, 1), b3 + hstepB, voffB); PG8_STAGE(PG8_SA(1, 0), a3, voffA);
;             PG8_WAIT_V(8); PG8_WAIT_L(0); PG8_BAR; PG8_MMA(1, 0, At, B0); PG8_MMA(1, 1, At, B1); PG8_BAR; PG8_SCHED;
;         }
	s_add_i32 s0, s0, s20
	v_lshl_add_u64 v[226:227], v[226:227], 0, s[30:31]
	s_mov_b32 m0, s0
	ds_read_b128 v[172:175], v196 offset:49152
	ds_read_b128 v[198:201], v196 offset:50176
	ds_read_b128 v[202:205], v196 offset:51200
	ds_read_b128 v[206:209], v196 offset:52224
	ds_read_b128 v[210:213], v196 offset:53248
	ds_read_b128 v[214:217], v196 offset:54272
	ds_read_b128 v[218:221], v196 offset:55296
	ds_read_b128 v[222:225], v196 offset:56320
	global_load_lds_dwordx4 v[226:227], off
	s_add_i32 m0, s0, 0x2000
	s_add_u32 s6, s6, 0x40080
	v_lshl_add_u64 v[226:227], v[228:229], 0, s[30:31]
	s_addc_u32 s7, s7, 0
	s_add_i32 s0, s26, s20
	global_load_lds_dwordx4 v[226:227], off
	v_lshl_add_u64 v[226:227], s[6:7], 0, v[160:161]
	s_mov_b32 m0, s0
	s_nop 0
	global_load_lds_dwordx4 v[226:227], off
	v_lshl_add_u64 v[226:227], s[6:7], 0, v[162:163]
	s_add_i32 m0, s0, 0x2000
	s_nop 0
	global_load_lds_dwordx4 v[226:227], off
	v_lshl_add_u64 v[226:227], v[230:231], 0, s[30:31]
	s_mov_b32 m0, s24
	s_nop 0
	global_load_lds_dwordx4 v[226:227], off
	v_lshl_add_u64 v[226:227], v[232:233], 0, s[30:31]
	s_mov_b32 m0, s25
	s_nop 0
	global_load_lds_dwordx4 v[226:227], off
	s_waitcnt vmcnt(8)
	s_waitcnt lgkmcnt(0)
	s_barrier
	v_mfma_f32_16x16x32_bf16 v[60:63], v[128:131], v[172:175], v[60:63]
	v_mfma_f32_16x16x32_bf16 v[56:59], v[136:139], v[172:175], v[56:59]
	v_mfma_f32_16x16x32_bf16 v[44:47], v[128:131], v[202:205], v[44:47]
	v_mfma_f32_16x16x32_bf16 v[40:43], v[136:139], v[202:205], v[40:43]
	v_mfma_f32_16x16x32_bf16 v[28:31], v[128:131], v[210:213], v[28:31]
	v_mfma_f32_16x16x32_bf16 v[24:27], v[136:139], v[210:213], v[24:27]
	v_mfma_f32_16x16x32_bf16 v[12:15], v[128:131], v[218:221], v[12:15]
	v_mfma_f32_16x16x32_bf16 v[8:11], v[136:139], v[218:221], v[8:11]
	v_mfma_f32_16x16x32_bf16 v[60:63], v[132:135], v[198:201], v[60:63]
	v_mfma_f32_16x16x32_bf16 v[56:59], v[140:143], v[198:201], v[56:59]
	v_mfma_f32_16x16x32_bf16 v[44:47], v[132:135], v[206:209], v[44:47]
	v_mfma_f32_16x16x32_bf16 v[40:43], v[140:143], v[206:209], v[40:43]
	v_mfma_f32_16x16x32_bf16 v[28:31], v[132:135], v[214:217], v[28:31]
	v_mfma_f32_16x16x32_bf16 v[24:27], v[140:143], v[214:217], v[24:27]
	v_mfma_f32_16x16x32_bf16 v[12:15], v[132:135], v[222:225], v[12:15]
	v_mfma_f32_16x16x32_bf16 v[8:11], v[140:143], v[222:225], v[8:11]
	v_mfma_f32_16x16x32_bf16 v[52:55], v[144:147], v[172:175], v[52:55]
	v_mfma_f32_16x16x32_bf16 v[48:51], v[152:155], v[172:175], v[48:51]
	v_mfma_f32_16x16x32_bf16 v[36:39], v[144:147], v[202:205], v[36:39]
	v_mfma_f32_16x16x32_bf16 v[32:35], v[152:155], v[202:205], v[32:35]
	v_mfma_f32_16x16x32_bf16 v[20:23], v[144:147], v[210:213], v[20:23]
	v_mfma_f32_16x16x32_bf16 v[16:19], v[152:155], v[210:213], v[16:19]
	v_mfma_f32_16x16x32_bf16 v[4:7], v[144:147], v[218:221], v[4:7]
	v_mfma_f32_16x16x32_bf16 v[0:3], v[152:155], v[218:221], v[0:3]
	v_mfma_f32_16x16x32_bf16 v[52:55], v[148:151], v[198:201], v[52:55]
	v_mfma_f32_16x16x32_bf16 v[48:51], v[168:171], v[198:201], v[48:51]
	v_mfma_f32_16x16x32_bf16 v[36:39], v[148:151], v[206:209], v[36:39]
	v_mfma_f32_16x16x32_bf16 v[32:35], v[168:171], v[206:209], v[32:35]
	v_mfma_f32_16x16x32_bf16 v[20:23], v[148:151], v[214:217], v[20:23]
	v_mfma_f32_16x16x32_bf16 v[16:19], v[168:171], v[214:217], v[16:19]
	v_mfma_f32_16x16x32_bf16 v[4:7], v[148:151], v[222:225], v[4:7]
	v_mfma_f32_16x16x32_bf16 v[0:3], v[168:171], v[222:225], v[0:3]
	s_barrier
	s_add_i32 s54, s54, 2
	s_add_u32 s52, s52, 0x100
	s_addc_u32 s53, s53, 0
	s_add_u32 s33, s33, 0x100
	s_addc_u32 s43, s43, 0
	s_cmp_gt_u32 s54, 13
.LBB0_358:
	s_add_u32 s0, s52, 0xfffc0080
	s_addc_u32 s6, s53, -1
	s_add_i32 s26, 0, 0x10000
	s_cmp_eq_u32 s54, 12
	s_cselect_b32 s15, s9, s6
	s_cselect_b32 s14, s13, s0
	s_cselect_b32 s7, s21, s43
	s_cselect_b32 s6, s23, s33
	s_add_i32 s0, 0, 0x14000
	v_add_u32_e32 v140, s26, v186
	v_add_u32_e32 v168, s0, v186
	ds_read_b128 v[128:131], v140
	ds_read_b128 v[132:135], v140 offset:1024
	ds_read_b128 v[136:139], v140 offset:2048
	ds_read_b128 v[140:143], v140 offset:3072
	ds_read_b128 v[144:147], v168
	ds_read_b128 v[148:151], v168 offset:1024
	ds_read_b128 v[152:155], v168 offset:2048
	ds_read_b128 v[168:171], v168 offset:3072
	v_lshl_add_u64 v[226:227], s[52:53], 0, v[164:165]
	s_add_i32 m0, s51, 0xc000
	ds_read_b128 v[172:175], v196
	ds_read_b128 v[198:201], v196 offset:1024
	ds_read_b128 v[202:205], v196 offset:2048
	ds_read_b128 v[206:209], v196 offset:3072
	ds_read_b128 v[210:213], v196 offset:4096
	ds_read_b128 v[214:217], v196 offset:5120
	ds_read_b128 v[218:221], v196 offset:6144
	ds_read_b128 v[222:225], v196 offset:7168
	global_load_lds_dwordx4 v[226:227], off
	v_lshl_add_u64 v[226:227], s[52:53], 0, v[166:167]
	s_add_i32 m0, s51, 0xe000
	s_nop 0
	global_load_lds_dwordx4 v[226:227], off
	s_waitcnt vmcnt(8)
	s_waitcnt lgkmcnt(0)
	s_barrier
; #define PG8_STAGE(bufoff, gbase, voff) do { _Pragma("unroll") for (int _i = 0; _i < 2; ++_i) \
;         __builtin_amdgcn_global_load_lds((const unsigned*)((const char*)(gbase) + (voff)[_i]), (LAS unsigned*)(lds + (bufoff) + ldsw + _i * 8192), 16, 0, 0); } while (0)
; #define PG8_LDA(dst, b, h) do { _Pragma("unroll") for (int m = 0; m < 4; ++m) _Pragma("unroll") for (int k = 0; k < 2; ++k) dst[m][k] = *(const LAS bf16x8*)(lds + PG8_SA(b, h) + aoff + m * 2048 + k * 1024); } while (0)
; #define PG8_LDB(dst, b, h) do { _Pragma("unroll") for (int n = 0; n < 2; ++n) _Pragma("unroll") for (int k = 0; k < 2; ++k) dst[n][k] = *(const LAS bf16x8*)(lds + PG8_SB(b, h) + boff + n * 2048 + k * 1024); } while (0)
; #define PG8_MMA(ai, bj, At, Bt) do { __builtin_amdgcn_s_setprio(1); _Pragma("unroll") for (int m = 0; m < 4; ++m) _Pragma("unroll") for (int n = 0; n < 2; ++n) _Pragma("unroll") for (int k = 0; k < 2; ++k) \
;         acc[ai][bj][m][n] = __builtin_amdgcn_mfma_f32_16x16x32_bf16(Bt[n][k], At[m][k], acc[ai][bj][m][n], 0, 0, 0); __builtin_amdgcn_s_setprio(0); } while (0)
; #define PG8_WAIT_V(n) asm volatile("s_waitcnt vmcnt(" #n ")" ::: "memory")
; #define PG8_WAIT_L(n) asm volatile("s_waitcnt lgkmcnt(" #n ")" ::: "memory")
; #define PG8_BAR __builtin_amdgcn_s_barrier()
; #define PG8_SCHED __builtin_amdgcn_sched_barrier(0)
; template <class Epi, class Sched>
; __device__ __forceinline__ void gemm_phase(LAS unsigned char* lds, const Gemm g, const Sched& S, const Epi& E) {
;     ...
;             PG8_WAIT_V(8); PG8_WAIT_L(0); PG8_BAR; PG8_MMA(0, 0, At, B0); PG8_MMA(0, 1, At, B1); PG8_BAR; PG8_SCHED;
;             PG8_LDA(At, 0, 1); PG8_STAGE(PG8_SB(0, 0), b2, voffB); PG8_STAGE(PG8_SB(0, 1), b2 + hstepB, voffB); PG8_STAGE(PG8_SA(0, 0), a2, voffA);
;             PG8_WAIT_V(8); PG8_WAIT_L(0); PG8_BAR; PG8_MMA(1, 0, At, B0); PG8_MMA(1, 1, At, B1); PG8_BAR; PG8_SCHED;
;             PG8_LDB(B0, 1, 0); PG8_LDB(B1, 1, 1); PG8_SCHED; PG8_LDA(At, 1, 0); PG8_STAGE(PG8_SA(0, 1), a2 + hstepA, voffA);
;             PG8_WAIT_V(8); PG8_WAIT_L(0); PG8_BAR; PG8_MMA(0, 0, At, B0); PG8_MMA(0, 1, At, B1); PG8_BAR; PG8_SCHED;
	v_mfma_f32_16x16x32_bf16 v[124:127], v[128:131], v[172:175], v[124:127]
	v_mfma_f32_16x16x32_bf16 v[120:123], v[136:139], v[172:175], v[120:123]
	v_mfma_f32_16x16x32_bf16 v[108:111], v[128:131], v[202:205], v[108:111]
	v_mfma_f32_16x16x32_bf16 v[104:107], v[136:139], v[202:205], v[104:107]
	v_mfma_f32_16x16x32_bf16 v[92:95], v[128:131], v[210:213], v[92:95]
	v_mfma_f32_16x16x32_bf16 v[88:91], v[136:139], v[210:213], v[88:91]
	v_mfma_f32_16x16x32_bf16 v[76:79], v[128:131], v[218:221], v[76:79]
	v_mfma_f32_16x16x32_bf16 v[72:75], v[136:139], v[218:221], v[72:75]
	v_mfma_f32_16x16x32_bf16 v[124:127], v[132:135], v[198:201], v[124:127]
	v_mfma_f32_16x16x32_bf16 v[120:123], v[140:143], v[198:201], v[120:123]
	v_mfma_f32_16x16x32_bf16 v[108:111], v[132:135], v[206:209], v[108:111]
	v_mfma_f32_16x16x32_bf16 v[104:107], v[140:143], v[206:209], v[104:107]
	v_mfma_f32_16x16x32_bf16 v[92:95], v[132:135], v[214:217], v[92:95]
	v_mfma_f32_16x16x32_bf16 v[88:91], v[140:143], v[214:217], v[88:91]
	v_mfma_f32_16x16x32_bf16 v[76:79], v[132:135], v[222:225], v[76:79]
	v_mfma_f32_16x16x32_bf16 v[72:75], v[140:143], v[222:225], v[72:75]
	v_mfma_f32_16x16x32_bf16 v[116:119], v[144:147], v[172:175], v[116:119]
	v_mfma_f32_16x16x32_bf16 v[112:115], v[152:155], v[172:175], v[112:115]
	v_mfma_f32_16x16x32_bf16 v[100:103], v[144:147], v[202:205], v[100:103]
	v_mfma_f32_16x16x32_bf16 v[96:99], v[152:155], v[202:205], v[96:99]
	v_mfma_f32_16x16x32_bf16 v[84:87], v[144:147], v[210:213], v[84:87]
	v_mfma_f32_16x16x32_bf16 v[80:83], v[152:155], v[210:213], v[80:83]
	v_mfma_f32_16x16x32_bf16 v[68:71], v[144:147], v[218:221], v[68:71]
	v_mfma_f32_16x16x32_bf16 v[64:67], v[152:155], v[218:221], v[64:67]
	v_mfma_f32_16x16x32_bf16 v[116:119], v[148:151], v[198:201], v[116:119]
	v_mfma_f32_16x16x32_bf16 v[112:115], v[168:171], v[198:201], v[112:115]
	v_mfma_f32_16x16x32_bf16 v[100:103], v[148:151], v[206:209], v[100:103]
	v_mfma_f32_16x16x32_bf16 v[96:99], v[168:171], v[206:209], v[96:99]
	v_mfma_f32_16x16x32_bf16 v[84:87], v[148:151], v[214:217], v[84:87]
	v_mfma_f32_16x16x32_bf16 v[80:83], v[168:171], v[214:217], v[80:83]
	v_mfma_f32_16x16x32_bf16 v[68:71], v[148:151], v[222:225], v[68:71]
	v_mfma_f32_16x16x32_bf16 v[64:67], v[168:171], v[222:225], v[64:67]
	s_barrier
	s_add_i32 s26, s26, s20
	v_lshl_add_u64 v[226:227], s[6:7], 0, v[160:161]
	s_mov_b32 m0, s26
	ds_read_b128 v[172:175], v196 offset:16384
	ds_read_b128 v[198:201], v196 offset:17408
	ds_read_b128 v[202:205], v196 offset:18432
	ds_read_b128 v[206:209], v196 offset:19456
	ds_read_b128 v[210:213], v196 offset:20480
	ds_read_b128 v[214:217], v196 offset:21504
	ds_read_b128 v[218:221], v196 offset:22528
	ds_read_b128 v[222:225], v196 offset:23552
	global_load_lds_dwordx4 v[226:227], off
	s_add_i32 m0, s26, 0x2000
	s_add_u32 s78, s6, 0x40000
	v_lshl_add_u64 v[228:229], s[6:7], 0, v[162:163]
	s_addc_u32 s79, s7, 0
	s_add_i32 s0, s0, s20
	global_load_lds_dwordx4 v[228:229], off
	v_lshl_add_u64 v[230:231], s[78:79], 0, v[160:161]
	s_mov_b32 m0, s0
	v_lshl_add_u64 v[232:233], s[14:15], 0, v[158:159]
	global_load_lds_dwordx4 v[230:231], off
	v_lshl_add_u64 v[230:231], s[78:79], 0, v[162:163]
	s_add_i32 m0, s0, 0x2000
	s_nop 0
	global_load_lds_dwordx4 v[230:231], off
	v_lshl_add_u64 v[230:231], s[14:15], 0, v[156:157]
	s_mov_b32 m0, s51
	s_nop 0
	global_load_lds_dwordx4 v[230:231], off
	s_mov_b32 m0, s56
	s_nop 0
	global_load_lds_dwordx4 v[232:233], off
	s_waitcnt vmcnt(8)
	s_waitcnt lgkmcnt(0)
	s_barrier
	v_mfma_f32_16x16x32_bf16 v[60:63], v[128:131], v[172:175], v[60:63]
	v_mfma_f32_16x16x32_bf16 v[56:59], v[136:139], v[172:175], v[56:59]
	v_mfma_f32_16x16x32_bf16 v[44:47], v[128:131], v[202:205], v[44:47]
	v_mfma_f32_16x16x32_bf16 v[40:43], v[136:139], v[202:205], v[40:43]
	v_mfma_f32_16x16x32_bf16 v[28:31], v[128:131], v[210:213], v[28:31]
	v_mfma_f32_16x16x32_bf16 v[24:27], v[136:139], v[210:213], v[24:27]
	v_mfma_f32_16x16x32_bf16 v[12:15], v[128:131], v[218:221], v[12:15]
	v_mfma_f32_16x16x32_bf16 v[8:11], v[136:139], v[218:221], v[8:11]
	v_mfma_f32_16x16x32_bf16 v[60:63], v[132:135], v[198:201], v[60:63]
	v_mfma_f32_16x16x32_bf16 v[56:59], v[140:143], v[198:201], v[56:59]
	v_mfma_f32_16x16x32_bf16 v[44:47], v[132:135], v[206:209], v[44:47]
	v_mfma_f32_16x16x32_bf16 v[40:43], v[140:143], v[206:209], v[40:43]
	v_mfma_f32_16x16x32_bf16 v[28:31], v[132:135], v[214:217], v[28:31]
	v_mfma_f32_16x16x32_bf16 v[24:27], v[140:143], v[214:217], v[24:27]
	v_mfma_f32_16x16x32_bf16 v[12:15], v[132:135], v[222:225], v[12:15]
	v_mfma_f32_16x16x32_bf16 v[8:11], v[140:143], v[222:225], v[8:11]
	v_mfma_f32_16x16x32_bf16 v[52:55], v[144:147], v[172:175], v[52:55]
	v_mfma_f32_16x16x32_bf16 v[48:51], v[152:155], v[172:175], v[48:51]
	v_mfma_f32_16x16x32_bf16 v[36:39], v[144:147], v[202:205], v[36:39]
	v_mfma_f32_16x16x32_bf16 v[32:35], v[152:155], v[202:205], v[32:35]
	v_mfma_f32_16x16x32_bf16 v[20:23], v[144:147], v[210:213], v[20:23]
	v_mfma_f32_16x16x32_bf16 v[16:19], v[152:155], v[210:213], v[16:19]
	v_mfma_f32_16x16x32_bf16 v[4:7], v[144:147], v[218:221], v[4:7]
	v_mfma_f32_16x16x32_bf16 v[0:3], v[152:155], v[218:221], v[0:3]
	v_mfma_f32_16x16x32_bf16 v[52:55], v[148:151], v[198:201], v[52:55]
	v_mfma_f32_16x16x32_bf16 v[48:51], v[168:171], v[198:201], v[48:51]
	v_mfma_f32_16x16x32_bf16 v[36:39], v[148:151], v[206:209], v[36:39]
	v_mfma_f32_16x16x32_bf16 v[32:35], v[168:171], v[206:209], v[32:35]
	v_mfma_f32_16x16x32_bf16 v[20:23], v[148:151], v[214:217], v[20:23]
	v_mfma_f32_16x16x32_bf16 v[16:19], v[168:171], v[214:217], v[16:19]
	v_mfma_f32_16x16x32_bf16 v[4:7], v[148:151], v[222:225], v[4:7]
	v_mfma_f32_16x16x32_bf16 v[0:3], v[168:171], v[222:225], v[0:3]
	s_barrier
; #define PG8_STAGE(bufoff, gbase, voff) do { _Pragma("unroll") for (int _i = 0; _i < 2; ++_i) \
;         __builtin_amdgcn_global_load_lds((const unsigned*)((const char*)(gbase) + (voff)[_i]), (LAS unsigned*)(lds + (bufoff) + ldsw + _i * 8192), 16, 0, 0); } while (0)
; #define PG8_LDA(dst, b, h) do { _Pragma("unroll") for (int m = 0; m < 4; ++m) _Pragma("unroll") for (int k = 0; k < 2; ++k) dst[m][k] = *(const LAS bf16x8*)(lds + PG8_SA(b, h) + aoff + m * 2048 + k * 1024); } while (0)
; #define PG8_LDB(dst, b, h) do { _Pragma("unroll") for (int n = 0; n < 2; ++n) _Pragma("unroll") for (int k = 0; k < 2; ++k) dst[n][k] = *(const LAS bf16x8*)(lds + PG8_SB(b, h) + boff + n * 2048 + k * 1024); } while (0)
; #define PG8_MMA(ai, bj, At, Bt) do { __builtin_amdgcn_s_setprio(1); _Pragma("unroll") for (int m = 0; m < 4; ++m) _Pragma("unroll") for (int n = 0; n < 2; ++n) _Pragma("unroll") for (int k = 0; k < 2; ++k) \
;         acc[ai][bj][m][n] = __builtin_amdgcn_mfma_f32_16x16x32_bf16(Bt[n][k], At[m][k], acc[ai][bj][m][n], 0, 0, 0); __builtin_amdgcn_s_setprio(0); } while (0)
; #define PG8_WAIT_V(n) asm volatile("s_waitcnt vmcnt(" #n ")" ::: "memory")
; #define PG8_WAIT_L(n) asm volatile("s_waitcnt lgkmcnt(" #n ")" ::: "memory")
; #define PG8_BAR __builtin_amdgcn_s_barrier()
; #define PG8_SCHED __builtin_amdgcn_sched_barrier(0)
; template <class Epi, class Sched>
; __device__ __forceinline__ void gemm_phase(LAS unsigned char* lds, const Gemm g, const Sched& S, const Epi& E) {
;     ...
;             PG8_LDB(B0, 1, 0); PG8_LDB(B1, 1, 1); PG8_SCHED; PG8_LDA(At, 1, 0); PG8_STAGE(PG8_SA(0, 1), a2 + hstepA, voffA);
;             PG8_WAIT_V(8); PG8_WAIT_L(0); PG8_BAR; PG8_MMA(0, 0, At, B0); PG8_MMA(0, 1, At, B1); PG8_BAR; PG8_SCHED;
	s_add_i32 s0, 0, 0x18000
	s_add_i32 s26, 0, 0x1c000
	v_add_u32_e32 v140, s0, v186
	v_add_u32_e32 v168, s26, v186
	ds_read_b128 v[128:131], v140
	ds_read_b128 v[132:135], v140 offset:1024
	ds_read_b128 v[136:139], v140 offset:2048
	ds_read_b128 v[140:143], v140 offset:3072
	ds_read_b128 v[144:147], v168
	ds_read_b128 v[148:151], v168 offset:1024
	ds_read_b128 v[152:155], v168 offset:2048
	ds_read_b128 v[168:171], v168 offset:3072
	s_add_u32 s14, s14, 0x40000
	s_addc_u32 s15, s15, 0
	s_mov_b32 m0, s57
	v_lshl_add_u64 v[234:235], s[14:15], 0, v[156:157]
	ds_read_b128 v[172:175], v196 offset:32768
	ds_read_b128 v[198:201], v196 offset:33792
	ds_read_b128 v[202:205], v196 offset:34816
	ds_read_b128 v[206:209], v196 offset:35840
	ds_read_b128 v[210:213], v196 offset:36864
	ds_read_b128 v[214:217], v196 offset:37888
	ds_read_b128 v[218:221], v196 offset:38912
	ds_read_b128 v[222:225], v196 offset:39936
	global_load_lds_dwordx4 v[234:235], off
	v_lshl_add_u64 v[234:235], s[14:15], 0, v[158:159]
	s_mov_b32 m0, s68
	s_nop 0
	global_load_lds_dwordx4 v[234:235], off
	s_waitcnt vmcnt(8)
	s_waitcnt lgkmcnt(0)
	s_barrier
	v_mfma_f32_16x16x32_bf16 v[124:127], v[128:131], v[172:175], v[124:127]
	v_mfma_f32_16x16x32_bf16 v[120:123], v[136:139], v[172:175], v[120:123]
	v_mfma_f32_16x16x32_bf16 v[108:111], v[128:131], v[202:205], v[108:111]
	v_mfma_f32_16x16x32_bf16 v[104:107], v[136:139], v[202:205], v[104:107]
	v_mfma_f32_16x16x32_bf16 v[92:95], v[128:131], v[210:213], v[92:95]
	v_mfma_f32_16x16x32_bf16 v[88:91], v[136:139], v[210:213], v[88:91]
	v_mfma_f32_16x16x32_bf16 v[76:79], v[128:131], v[218:221], v[76:79]
	v_mfma_f32_16x16x32_bf16 v[72:75], v[136:139], v[218:221], v[72:75]
	v_mfma_f32_16x16x32_bf16 v[124:127], v[132:135], v[198:201], v[124:127]
	v_mfma_f32_16x16x32_bf16 v[120:123], v[140:143], v[198:201], v[120:123]
	v_mfma_f32_16x16x32_bf16 v[108:111], v[132:135], v[206:209], v[108:111]
	v_mfma_f32_16x16x32_bf16 v[104:107], v[140:143], v[206:209], v[104:107]
	v_mfma_f32_16x16x32_bf16 v[92:95], v[132:135], v[214:217], v[92:95]
	v_mfma_f32_16x16x32_bf16 v[88:91], v[140:143], v[214:217], v[88:91]
	v_mfma_f32_16x16x32_bf16 v[76:79], v[132:135], v[222:225], v[76:79]
	v_mfma_f32_16x16x32_bf16 v[72:75], v[140:143], v[222:225], v[72:75]
	v_mfma_f32_16x16x32_bf16 v[116:119], v[144:147], v[172:175], v[116:119]
	v_mfma_f32_16x16x32_bf16 v[112:115], v[152:155], v[172:175], v[112:115]
	v_mfma_f32_16x16x32_bf16 v[100:103], v[144:147], v[202:205], v[100:103]
	v_mfma_f32_16x16x32_bf16 v[96:99], v[152:155], v[202:205], v[96:99]
	v_mfma_f32_16x16x32_bf16 v[84:87], v[144:147], v[210:213], v[84:87]
	v_mfma_f32_16x16x32_bf16 v[80:83], v[152:155], v[210:213], v[80:83]
	v_mfma_f32_16x16x32_bf16 v[68:71], v[144:147], v[218:221], v[68:71]
	v_mfma_f32_16x16x32_bf16 v[64:67], v[152:155], v[218:221], v[64:67]
	v_mfma_f32_16x16x32_bf16 v[116:119], v[148:151], v[198:201], v[116:119]
	v_mfma_f32_16x16x32_bf16 v[112:115], v[168:171], v[198:201], v[112:115]
	v_mfma_f32_16x16x32_bf16 v[100:103], v[148:151], v[206:209], v[100:103]
	v_mfma_f32_16x16x32_bf16 v[96:99], v[168:171], v[206:209], v[96:99]
	v_mfma_f32_16x16x32_bf16 v[84:87], v[148:151], v[214:217], v[84:87]
	v_mfma_f32_16x16x32_bf16 v[80:83], v[168:171], v[214:217], v[80:83]
	v_mfma_f32_16x16x32_bf16 v[68:71], v[148:151], v[222:225], v[68:71]
	v_mfma_f32_16x16x32_bf16 v[64:67], v[168:171], v[222:225], v[64:67]
	s_barrier
; #define PG8_STAGE(bufoff, gbase, voff) do { _Pragma("unroll") for (int _i = 0; _i < 2; ++_i) \
;         __builtin_amdgcn_global_load_lds((const unsigned*)((const char*)(gbase) + (voff)[_i]), (LAS unsigned*)(lds + (bufoff) + ldsw + _i * 8192), 16, 0, 0); } while (0)
; #define PG8_LDA(dst, b, h) do { _Pragma("unroll") for (int m = 0; m < 4; ++m) _Pragma("unroll") for (int k = 0; k < 2; ++k) dst[m][k] = *(const LAS bf16x8*)(lds + PG8_SA(b, h) + aoff + m * 2048 + k * 1024); } while (0)
; #define PG8_MMA(ai, bj, At, Bt) do { __builtin_amdgcn_s_setprio(1); _Pragma("unroll") for (int m = 0; m < 4; ++m) _Pragma("unroll") for (int n = 0; n < 2; ++n) _Pragma("unroll") for (int k = 0; k < 2; ++k) \
;         acc[ai][bj][m][n] = __builtin_amdgcn_mfma_f32_16x16x32_bf16(Bt[n][k], At[m][k], acc[ai][bj][m][n], 0, 0, 0); __builtin_amdgcn_s_setprio(0); } while (0)
; #define PG8_WAIT_V(n) asm volatile("s_waitcnt vmcnt(" #n ")" ::: "memory")
; #define PG8_WAIT_L(n) asm volatile("s_waitcnt lgkmcnt(" #n ")" ::: "memory")
; #define PG8_BAR __builtin_amdgcn_s_barrier()
; #define PG8_SCHED __builtin_amdgcn_sched_barrier(0)
; template <class Epi, class Sched>
; __device__ __forceinline__ void gemm_phase(LAS unsigned char* lds, const Gemm g, const Sched& S, const Epi& E) {
;     ...
;             PG8_LDA(At, 1, 1); PG8_STAGE(PG8_SB(1, 0), b3, voffB); PG8_STAGE(PG8_SB(1, 1), b3 + hstepB, voffB); PG8_STAGE(PG8_SA(1, 0), a3, voffA);
;             PG8_WAIT_V(8); PG8_WAIT_L(0); PG8_BAR; PG8_MMA(1, 0, At, B0); PG8_MMA(1, 1, At, B1); PG8_BAR; PG8_SCHED;
;         }
;         if (wr == 0) PG8_BAR;
	s_add_i32 s0, s0, s20
	v_lshl_add_u64 v[226:227], v[226:227], 0, s[30:31]
	s_mov_b32 m0, s0
	ds_read_b128 v[172:175], v196 offset:49152
	ds_read_b128 v[198:201], v196 offset:50176
	ds_read_b128 v[202:205], v196 offset:51200
	ds_read_b128 v[206:209], v196 offset:52224
	ds_read_b128 v[210:213], v196 offset:53248
	ds_read_b128 v[214:217], v196 offset:54272
	ds_read_b128 v[218:221], v196 offset:55296
	ds_read_b128 v[222:225], v196 offset:56320
	global_load_lds_dwordx4 v[226:227], off
	s_add_i32 m0, s0, 0x2000
	s_add_u32 s6, s6, 0x40080
	v_lshl_add_u64 v[226:227], v[228:229], 0, s[30:31]
	s_addc_u32 s7, s7, 0
	s_add_i32 s0, s26, s20
	global_load_lds_dwordx4 v[226:227], off
	v_lshl_add_u64 v[226:227], s[6:7], 0, v[160:161]
	s_mov_b32 m0, s0
	s_nop 0
	global_load_lds_dwordx4 v[226:227], off
	v_lshl_add_u64 v[226:227], s[6:7], 0, v[162:163]
	s_add_i32 m0, s0, 0x2000
	s_nop 0
	global_load_lds_dwordx4 v[226:227], off
	v_lshl_add_u64 v[226:227], v[230:231], 0, s[30:31]
	s_mov_b32 m0, s24
	s_nop 0
	global_load_lds_dwordx4 v[226:227], off
	v_lshl_add_u64 v[226:227], v[232:233], 0, s[30:31]
	s_mov_b32 m0, s25
	s_nop 0
	global_load_lds_dwordx4 v[226:227], off
	s_waitcnt vmcnt(8)
	s_waitcnt lgkmcnt(0)
	s_barrier
	v_mfma_f32_16x16x32_bf16 v[60:63], v[128:131], v[172:175], v[60:63]
	v_mfma_f32_16x16x32_bf16 v[56:59], v[136:139], v[172:175], v[56:59]
	v_mfma_f32_16x16x32_bf16 v[44:47], v[128:131], v[202:205], v[44:47]
	v_mfma_f32_16x16x32_bf16 v[40:43], v[136:139], v[202:205], v[40:43]
	v_mfma_f32_16x16x32_bf16 v[28:31], v[128:131], v[210:213], v[28:31]
	v_mfma_f32_16x16x32_bf16 v[24:27], v[136:139], v[210:213], v[24:27]
	v_mfma_f32_16x16x32_bf16 v[12:15], v[128:131], v[218:221], v[12:15]
	v_mfma_f32_16x16x32_bf16 v[8:11], v[136:139], v[218:221], v[8:11]
	v_mfma_f32_16x16x32_bf16 v[60:63], v[132:135], v[198:201], v[60:63]
	v_mfma_f32_16x16x32_bf16 v[56:59], v[140:143], v[198:201], v[56:59]
	v_mfma_f32_16x16x32_bf16 v[44:47], v[132:135], v[206:209], v[44:47]
	v_mfma_f32_16x16x32_bf16 v[40:43], v[140:143], v[206:209], v[40:43]
	v_mfma_f32_16x16x32_bf16 v[28:31], v[132:135], v[214:217], v[28:31]
	v_mfma_f32_16x16x32_bf16 v[24:27], v[140:143], v[214:217], v[24:27]
	v_mfma_f32_16x16x32_bf16 v[12:15], v[132:135], v[222:225], v[12:15]
	v_mfma_f32_16x16x32_bf16 v[8:11], v[140:143], v[222:225], v[8:11]
	v_mfma_f32_16x16x32_bf16 v[52:55], v[144:147], v[172:175], v[52:55]
	v_mfma_f32_16x16x32_bf16 v[48:51], v[152:155], v[172:175], v[48:51]
	v_mfma_f32_16x16x32_bf16 v[36:39], v[144:147], v[202:205], v[36:39]
	v_mfma_f32_16x16x32_bf16 v[32:35], v[152:155], v[202:205], v[32:35]
	v_mfma_f32_16x16x32_bf16 v[20:23], v[144:147], v[210:213], v[20:23]
	v_mfma_f32_16x16x32_bf16 v[16:19], v[152:155], v[210:213], v[16:19]
	v_mfma_f32_16x16x32_bf16 v[4:7], v[144:147], v[218:221], v[4:7]
	v_mfma_f32_16x16x32_bf16 v[0:3], v[152:155], v[218:221], v[0:3]
	v_mfma_f32_16x16x32_bf16 v[52:55], v[148:151], v[198:201], v[52:55]
	v_mfma_f32_16x16x32_bf16 v[48:51], v[168:171], v[198:201], v[48:51]
	v_mfma_f32_16x16x32_bf16 v[36:39], v[148:151], v[206:209], v[36:39]
	v_mfma_f32_16x16x32_bf16 v[32:35], v[168:171], v[206:209], v[32:35]
	v_mfma_f32_16x16x32_bf16 v[20:23], v[148:151], v[214:217], v[20:23]
	v_mfma_f32_16x16x32_bf16 v[16:19], v[168:171], v[214:217], v[16:19]
	v_mfma_f32_16x16x32_bf16 v[4:7], v[148:151], v[222:225], v[4:7]
	v_mfma_f32_16x16x32_bf16 v[0:3], v[168:171], v[222:225], v[0:3]
	s_barrier
	s_add_i32 s54, s54, 2
	s_add_u32 s52, s52, 0x100
	s_addc_u32 s53, s53, 0
	s_add_u32 s33, s33, 0x100
	s_addc_u32 s43, s43, 0
	s_cmp_gt_u32 s54, 13
	s_cbranch_scc0 .LBB0_358
	s_setprio 0
	s_and_b64 vcc, exec, s[18:19]
	s_cbranch_vccz .LBB0_361
	s_barrier

; #define PG8_STAGE(bufoff, gbase, voff) do { _Pragma("unroll") for (int _i = 0; _i < 2; ++_i) \
;         __builtin_amdgcn_global_load_lds((const unsigned*)((const char*)(gbase) + (voff)[_i]), (LAS unsigned*)(lds + (bufoff) + ldsw + _i * 8192), 16, 0, 0); } while (0)
; #define PG8_LDA(dst, b, h) do { _Pragma("unroll") for (int m = 0; m < 4; ++m) _Pragma("unroll") for (int k = 0; k < 2; ++k) dst[m][k] = *(const LAS bf16x8*)(lds + PG8_SA(b, h) + aoff + m * 2048 + k * 1024); } while (0)
; #define PG8_LDB(dst, b, h) do { _Pragma("unroll") for (int n = 0; n < 2; ++n) _Pragma("unroll") for (int k = 0; k < 2; ++k) dst[n][k] = *(const LAS bf16x8*)(lds + PG8_SB(b, h) + boff + n * 2048 + k * 1024); } while (0)
; #define PG8_MMA(ai, bj, At, Bt) do { __builtin_amdgcn_s_setprio(1); _Pragma("unroll") for (int m = 0; m < 4; ++m) _Pragma("unroll") for (int n = 0; n < 2; ++n) _Pragma("unroll") for (int k = 0; k < 2; ++k) \
;         acc[ai][bj][m][n] = __builtin_amdgcn_mfma_f32_16x16x32_bf16(Bt[n][k], At[m][k], acc[ai][bj][m][n], 0, 0, 0); __builtin_amdgcn_s_setprio(0); } while (0)
; #define PG8_BAR __builtin_amdgcn_s_barrier()
; template <class Epi, class Sched>
; __device__ __forceinline__ void gemm_phase(LAS unsigned char* lds, const Gemm g, const Sched& S, const Epi& E) {
;     ...
;         const bool has_next = S.next(ui + 1, nxt);
;         const char* nA = has_next ? (const char*)g.A + (size_t)nxt.pm * tstepA + (size_t)nxt.pn * apn : cA; const char* nB = has_next ? (const char*)g.Bt + (size_t)nxt.pn * tstepB : cB;
;         for (int t = 0; t < nt; t += 2) {
;             const bool last = (t == nt - 2);
;             const char* a1 = cA + (size_t)(t + 1) * kstep;
;             const char* a2 = last ? nA : cA + (size_t)(t + 2) * kstep; const char* b2 = last ? nB : cB + (size_t)(t + 2) * kstep;
;             const char* a3 = a2 + kstep; const char* b3 = b2 + kstep;
;             PG8_LDB(B0, 0, 0); PG8_LDB(B1, 0, 1); PG8_SCHED; PG8_LDA(At, 0, 0); PG8_STAGE(PG8_SA(1, 1), a1 + hstepA, voffA);
;             PG8_WAIT_V(8); PG8_WAIT_L(0); PG8_BAR; PG8_MMA(0, 0, At, B0); PG8_MMA(0, 1, At, B1); PG8_BAR; PG8_SCHED;
;             PG8_LDA(At, 0, 1); PG8_STAGE(PG8_SB(0, 0), b2, voffB); PG8_STAGE(PG8_SB(0, 1), b2 + hstepB, voffB); PG8_STAGE(PG8_SA(0, 0), a2, voffA);
;             PG8_WAIT_V(8); PG8_WAIT_L(0); PG8_BAR; PG8_MMA(1, 0, At, B0); PG8_MMA(1, 1, At, B1); PG8_BAR; PG8_SCHED;
.Lprio_628:
	s_add_u32 s0, s52, s6
	s_addc_u32 s23, s53, 0
	s_add_u32 s7, s0, 0x100
	s_addc_u32 s26, s23, 0
	s_and_b64 s[14:15], s[56:57], exec
	s_cselect_b32 vcc_hi, s45, s26
	s_cselect_b32 vcc_lo, s44, s7
	s_add_u32 s6, s50, s6
	s_addc_u32 s7, s51, 0
	s_add_u32 s14, s6, 0x100
	s_addc_u32 s15, s7, 0
	s_add_i32 s80, 0, 0x10000
	s_and_b64 s[6:7], s[56:57], exec
	s_cselect_b32 s7, s9, s15
	s_cselect_b32 s6, s13, s14
	s_add_i32 s57, 0, 0x14000
	s_add_u32 s78, s0, 0x40080
	s_addc_u32 s79, s23, 0
	s_add_i32 s97, s80, s24
	s_add_i32 m0, s25, 0xc000
	s_add_i32 s81, s25, 0xe000
	s_add_i32 s88, s97, 0x2000
	s_add_u32 s14, s6, 0x10000
	v_add_u32_e32 v140, s80, v174
	v_add_u32_e32 v164, s57, v174
	s_addc_u32 s15, s7, 0
	s_add_i32 s89, s57, s24
	ds_read_b128 v[128:131], v140
	ds_read_b128 v[132:135], v140 offset:1024
	ds_read_b128 v[136:139], v140 offset:2048
	ds_read_b128 v[140:143], v140 offset:3072
	ds_read_b128 v[144:147], v164
	ds_read_b128 v[148:151], v164 offset:1024
	ds_read_b128 v[152:155], v164 offset:2048
	ds_read_b128 v[164:167], v164 offset:3072
	s_add_i32 s96, s89, 0x2000
	s_add_i32 s35, 0, 0x18000
	s_add_i32 s0, 0, 0x1c000
	s_add_u32 s68, vcc_lo, 0x40000
	s_addc_u32 s69, vcc_hi, 0
	s_add_i32 s23, s35, s24
	s_add_i32 s26, s23, 0x2000
	s_add_u32 s56, s6, 0x10080
	s_addc_u32 s57, s7, 0
	s_add_i32 s83, s0, s24
	s_add_i32 s80, s83, 0x2000
	v_lshl_add_u64 v[192:193], s[78:79], 0, v[156:157]
	ds_read_b128 v[168:171], v191
	ds_read_b128 v[196:199], v191 offset:1024
	ds_read_b128 v[200:203], v191 offset:2048
	ds_read_b128 v[204:207], v191 offset:3072
	ds_read_b128 v[208:211], v191 offset:4096
	ds_read_b128 v[212:215], v191 offset:5120
	ds_read_b128 v[216:219], v191 offset:6144
	ds_read_b128 v[220:223], v191 offset:7168
	global_load_lds_dwordx4 v[192:193], off
	v_lshl_add_u64 v[192:193], s[78:79], 0, v[158:159]
	s_mov_b32 m0, s81
	s_nop 0
	global_load_lds_dwordx4 v[192:193], off
	s_waitcnt vmcnt(8)
	s_waitcnt lgkmcnt(0)
	s_barrier
	v_mfma_f32_16x16x32_bf16 v[124:127], v[128:131], v[168:171], 0
	v_mfma_f32_16x16x32_bf16 v[120:123], v[136:139], v[168:171], 0
	v_mfma_f32_16x16x32_bf16 v[108:111], v[128:131], v[200:203], 0
	v_mfma_f32_16x16x32_bf16 v[104:107], v[136:139], v[200:203], 0
	v_mfma_f32_16x16x32_bf16 v[92:95], v[128:131], v[208:211], 0
	v_mfma_f32_16x16x32_bf16 v[88:91], v[136:139], v[208:211], 0
	v_mfma_f32_16x16x32_bf16 v[76:79], v[128:131], v[216:219], 0
	v_mfma_f32_16x16x32_bf16 v[72:75], v[136:139], v[216:219], 0
	v_mfma_f32_16x16x32_bf16 v[124:127], v[132:135], v[196:199], v[124:127]
	v_mfma_f32_16x16x32_bf16 v[120:123], v[140:143], v[196:199], v[120:123]
	v_mfma_f32_16x16x32_bf16 v[108:111], v[132:135], v[204:207], v[108:111]
	v_mfma_f32_16x16x32_bf16 v[104:107], v[140:143], v[204:207], v[104:107]
	v_mfma_f32_16x16x32_bf16 v[92:95], v[132:135], v[212:215], v[92:95]
	v_mfma_f32_16x16x32_bf16 v[88:91], v[140:143], v[212:215], v[88:91]
	v_mfma_f32_16x16x32_bf16 v[76:79], v[132:135], v[220:223], v[76:79]
	v_mfma_f32_16x16x32_bf16 v[72:75], v[140:143], v[220:223], v[72:75]
	v_mfma_f32_16x16x32_bf16 v[116:119], v[144:147], v[168:171], 0
	v_mfma_f32_16x16x32_bf16 v[112:115], v[152:155], v[168:171], 0
	v_mfma_f32_16x16x32_bf16 v[100:103], v[144:147], v[200:203], 0
	v_mfma_f32_16x16x32_bf16 v[96:99], v[152:155], v[200:203], 0
	v_mfma_f32_16x16x32_bf16 v[84:87], v[144:147], v[208:211], 0
	v_mfma_f32_16x16x32_bf16 v[80:83], v[152:155], v[208:211], 0
	v_mfma_f32_16x16x32_bf16 v[68:71], v[144:147], v[216:219], 0
	v_mfma_f32_16x16x32_bf16 v[64:67], v[152:155], v[216:219], 0
	v_mfma_f32_16x16x32_bf16 v[116:119], v[148:151], v[196:199], v[116:119]
	v_mfma_f32_16x16x32_bf16 v[112:115], v[164:167], v[196:199], v[112:115]
	v_mfma_f32_16x16x32_bf16 v[100:103], v[148:151], v[204:207], v[100:103]
	v_mfma_f32_16x16x32_bf16 v[96:99], v[164:167], v[204:207], v[96:99]
	v_mfma_f32_16x16x32_bf16 v[84:87], v[148:151], v[212:215], v[84:87]
	v_mfma_f32_16x16x32_bf16 v[80:83], v[164:167], v[212:215], v[80:83]
	v_mfma_f32_16x16x32_bf16 v[68:71], v[148:151], v[220:223], v[68:71]
	v_mfma_f32_16x16x32_bf16 v[64:67], v[164:167], v[220:223], v[64:67]
	s_barrier
	s_mov_b32 m0, s97
	v_lshl_add_u64 v[192:193], s[6:7], 0, v[160:161]
	ds_read_b128 v[168:171], v191 offset:16384
	ds_read_b128 v[196:199], v191 offset:17408
	ds_read_b128 v[200:203], v191 offset:18432
	ds_read_b128 v[204:207], v191 offset:19456
	ds_read_b128 v[208:211], v191 offset:20480
	ds_read_b128 v[212:215], v191 offset:21504
	ds_read_b128 v[216:219], v191 offset:22528
	ds_read_b128 v[220:223], v191 offset:23552
	global_load_lds_dwordx4 v[192:193], off
	v_lshl_add_u64 v[224:225], s[6:7], 0, v[162:163]
	s_mov_b32 m0, s88
	v_lshl_add_u64 v[226:227], s[14:15], 0, v[160:161]
	global_load_lds_dwordx4 v[224:225], off
	s_mov_b32 m0, s89
	v_lshl_add_u64 v[228:229], vcc, 0, v[158:159]
	global_load_lds_dwordx4 v[226:227], off
	v_lshl_add_u64 v[226:227], s[14:15], 0, v[162:163]
	s_mov_b32 m0, s96
	s_nop 0
	global_load_lds_dwordx4 v[226:227], off
	v_lshl_add_u64 v[226:227], vcc, 0, v[156:157]
	s_mov_b32 m0, s25
	s_nop 0
	global_load_lds_dwordx4 v[226:227], off
	s_mov_b32 m0, s49
	s_nop 0
	global_load_lds_dwordx4 v[228:229], off
	s_waitcnt vmcnt(8)
	s_waitcnt lgkmcnt(0)
	s_barrier
; #define PG8_STAGE(bufoff, gbase, voff) do { _Pragma("unroll") for (int _i = 0; _i < 2; ++_i) \
;         __builtin_amdgcn_global_load_lds((const unsigned*)((const char*)(gbase) + (voff)[_i]), (LAS unsigned*)(lds + (bufoff) + ldsw + _i * 8192), 16, 0, 0); } while (0)
; #define PG8_LDA(dst, b, h) do { _Pragma("unroll") for (int m = 0; m < 4; ++m) _Pragma("unroll") for (int k = 0; k < 2; ++k) dst[m][k] = *(const LAS bf16x8*)(lds + PG8_SA(b, h) + aoff + m * 2048 + k * 1024); } while (0)
; #define PG8_LDB(dst, b, h) do { _Pragma("unroll") for (int n = 0; n < 2; ++n) _Pragma("unroll") for (int k = 0; k < 2; ++k) dst[n][k] = *(const LAS bf16x8*)(lds + PG8_SB(b, h) + boff + n * 2048 + k * 1024); } while (0)
; #define PG8_MMA(ai, bj, At, Bt) do { __builtin_amdgcn_s_setprio(1); _Pragma("unroll") for (int m = 0; m < 4; ++m) _Pragma("unroll") for (int n = 0; n < 2; ++n) _Pragma("unroll") for (int k = 0; k < 2; ++k) \
;         acc[ai][bj][m][n] = __builtin_amdgcn_mfma_f32_16x16x32_bf16(Bt[n][k], At[m][k], acc[ai][bj][m][n], 0, 0, 0); __builtin_amdgcn_s_setprio(0); } while (0)
; #define PG8_WAIT_V(n) asm volatile("s_waitcnt vmcnt(" #n ")" ::: "memory")
; #define PG8_WAIT_L(n) asm volatile("s_waitcnt lgkmcnt(" #n ")" ::: "memory")
; #define PG8_BAR __builtin_amdgcn_s_barrier()
; #define PG8_SCHED __builtin_amdgcn_sched_barrier(0)
; template <class Epi, class Sched>
; __device__ __forceinline__ void gemm_phase(LAS unsigned char* lds, const Gemm g, const Sched& S, const Epi& E) {
;     ...
;             PG8_WAIT_V(8); PG8_WAIT_L(0); PG8_BAR; PG8_MMA(1, 0, At, B0); PG8_MMA(1, 1, At, B1); PG8_BAR; PG8_SCHED;
;             PG8_LDB(B0, 1, 0); PG8_LDB(B1, 1, 1); PG8_SCHED; PG8_LDA(At, 1, 0); PG8_STAGE(PG8_SA(0, 1), a2 + hstepA, voffA);
;             PG8_WAIT_V(8); PG8_WAIT_L(0); PG8_BAR; PG8_MMA(0, 0, At, B0); PG8_MMA(0, 1, At, B1); PG8_BAR; PG8_SCHED;
	v_mfma_f32_16x16x32_bf16 v[60:63], v[128:131], v[168:171], 0
	v_mfma_f32_16x16x32_bf16 v[56:59], v[136:139], v[168:171], 0
	v_mfma_f32_16x16x32_bf16 v[44:47], v[128:131], v[200:203], 0
	v_mfma_f32_16x16x32_bf16 v[40:43], v[136:139], v[200:203], 0
	v_mfma_f32_16x16x32_bf16 v[28:31], v[128:131], v[208:211], 0
	v_mfma_f32_16x16x32_bf16 v[24:27], v[136:139], v[208:211], 0
	v_mfma_f32_16x16x32_bf16 v[12:15], v[128:131], v[216:219], 0
	v_mfma_f32_16x16x32_bf16 v[8:11], v[136:139], v[216:219], 0
	v_mfma_f32_16x16x32_bf16 v[60:63], v[132:135], v[196:199], v[60:63]
	v_mfma_f32_16x16x32_bf16 v[56:59], v[140:143], v[196:199], v[56:59]
	v_mfma_f32_16x16x32_bf16 v[44:47], v[132:135], v[204:207], v[44:47]
	v_mfma_f32_16x16x32_bf16 v[40:43], v[140:143], v[204:207], v[40:43]
	v_mfma_f32_16x16x32_bf16 v[28:31], v[132:135], v[212:215], v[28:31]
	v_mfma_f32_16x16x32_bf16 v[24:27], v[140:143], v[212:215], v[24:27]
	v_mfma_f32_16x16x32_bf16 v[12:15], v[132:135], v[220:223], v[12:15]
	v_mfma_f32_16x16x32_bf16 v[8:11], v[140:143], v[220:223], v[8:11]
	v_mfma_f32_16x16x32_bf16 v[52:55], v[144:147], v[168:171], 0
	v_mfma_f32_16x16x32_bf16 v[48:51], v[152:155], v[168:171], 0
	v_mfma_f32_16x16x32_bf16 v[36:39], v[144:147], v[200:203], 0
	v_mfma_f32_16x16x32_bf16 v[32:35], v[152:155], v[200:203], 0
	v_mfma_f32_16x16x32_bf16 v[20:23], v[144:147], v[208:211], 0
	v_mfma_f32_16x16x32_bf16 v[16:19], v[152:155], v[208:211], 0
	v_mfma_f32_16x16x32_bf16 v[4:7], v[144:147], v[216:219], 0
	v_mfma_f32_16x16x32_bf16 v[0:3], v[152:155], v[216:219], 0
	v_mfma_f32_16x16x32_bf16 v[52:55], v[148:151], v[196:199], v[52:55]
	v_mfma_f32_16x16x32_bf16 v[48:51], v[164:167], v[196:199], v[48:51]
	v_mfma_f32_16x16x32_bf16 v[36:39], v[148:151], v[204:207], v[36:39]
	v_mfma_f32_16x16x32_bf16 v[32:35], v[164:167], v[204:207], v[32:35]
	v_mfma_f32_16x16x32_bf16 v[20:23], v[148:151], v[212:215], v[20:23]
	v_mfma_f32_16x16x32_bf16 v[16:19], v[164:167], v[212:215], v[16:19]
	v_mfma_f32_16x16x32_bf16 v[4:7], v[148:151], v[220:223], v[4:7]
	v_mfma_f32_16x16x32_bf16 v[0:3], v[164:167], v[220:223], v[0:3]
	s_barrier
	v_add_u32_e32 v140, s35, v174
	v_add_u32_e32 v164, s0, v174
	ds_read_b128 v[128:131], v140
	ds_read_b128 v[132:135], v140 offset:1024
	ds_read_b128 v[136:139], v140 offset:2048
	ds_read_b128 v[140:143], v140 offset:3072
	ds_read_b128 v[144:147], v164
	ds_read_b128 v[148:151], v164 offset:1024
	ds_read_b128 v[152:155], v164 offset:2048
	ds_read_b128 v[164:167], v164 offset:3072
	s_mov_b32 m0, s82
	v_lshl_add_u64 v[230:231], s[68:69], 0, v[156:157]
	ds_read_b128 v[168:171], v191 offset:32768
	ds_read_b128 v[196:199], v191 offset:33792
	ds_read_b128 v[200:203], v191 offset:34816
	ds_read_b128 v[204:207], v191 offset:35840
	ds_read_b128 v[208:211], v191 offset:36864
	ds_read_b128 v[212:215], v191 offset:37888
	ds_read_b128 v[216:219], v191 offset:38912
	ds_read_b128 v[220:223], v191 offset:39936
	global_load_lds_dwordx4 v[230:231], off
	v_lshl_add_u64 v[230:231], s[68:69], 0, v[158:159]
	s_mov_b32 m0, s33
	s_nop 0
	global_load_lds_dwordx4 v[230:231], off
	s_waitcnt vmcnt(8)
	s_waitcnt lgkmcnt(0)
	s_barrier
	v_mfma_f32_16x16x32_bf16 v[124:127], v[128:131], v[168:171], v[124:127]
	v_mfma_f32_16x16x32_bf16 v[120:123], v[136:139], v[168:171], v[120:123]
	v_mfma_f32_16x16x32_bf16 v[108:111], v[128:131], v[200:203], v[108:111]
	v_mfma_f32_16x16x32_bf16 v[104:107], v[136:139], v[200:203], v[104:107]
	v_mfma_f32_16x16x32_bf16 v[92:95], v[128:131], v[208:211], v[92:95]
	v_mfma_f32_16x16x32_bf16 v[88:91], v[136:139], v[208:211], v[88:91]
	v_mfma_f32_16x16x32_bf16 v[76:79], v[128:131], v[216:219], v[76:79]
	v_mfma_f32_16x16x32_bf16 v[72:75], v[136:139], v[216:219], v[72:75]
	v_mfma_f32_16x16x32_bf16 v[124:127], v[132:135], v[196:199], v[124:127]
	v_mfma_f32_16x16x32_bf16 v[120:123], v[140:143], v[196:199], v[120:123]
	v_mfma_f32_16x16x32_bf16 v[108:111], v[132:135], v[204:207], v[108:111]
	v_mfma_f32_16x16x32_bf16 v[104:107], v[140:143], v[204:207], v[104:107]
	v_mfma_f32_16x16x32_bf16 v[92:95], v[132:135], v[212:215], v[92:95]
	v_mfma_f32_16x16x32_bf16 v[88:91], v[140:143], v[212:215], v[88:91]
	v_mfma_f32_16x16x32_bf16 v[76:79], v[132:135], v[220:223], v[76:79]
	v_mfma_f32_16x16x32_bf16 v[72:75], v[140:143], v[220:223], v[72:75]
	v_mfma_f32_16x16x32_bf16 v[116:119], v[144:147], v[168:171], v[116:119]
	v_mfma_f32_16x16x32_bf16 v[112:115], v[152:155], v[168:171], v[112:115]
	v_mfma_f32_16x16x32_bf16 v[100:103], v[144:147], v[200:203], v[100:103]
	v_mfma_f32_16x16x32_bf16 v[96:99], v[152:155], v[200:203], v[96:99]
	v_mfma_f32_16x16x32_bf16 v[84:87], v[144:147], v[208:211], v[84:87]
	v_mfma_f32_16x16x32_bf16 v[80:83], v[152:155], v[208:211], v[80:83]
	v_mfma_f32_16x16x32_bf16 v[68:71], v[144:147], v[216:219], v[68:71]
	v_mfma_f32_16x16x32_bf16 v[64:67], v[152:155], v[216:219], v[64:67]
	v_mfma_f32_16x16x32_bf16 v[116:119], v[148:151], v[196:199], v[116:119]
	v_mfma_f32_16x16x32_bf16 v[112:115], v[164:167], v[196:199], v[112:115]
	v_mfma_f32_16x16x32_bf16 v[100:103], v[148:151], v[204:207], v[100:103]
	v_mfma_f32_16x16x32_bf16 v[96:99], v[164:167], v[204:207], v[96:99]
	v_mfma_f32_16x16x32_bf16 v[84:87], v[148:151], v[212:215], v[84:87]
	v_mfma_f32_16x16x32_bf16 v[80:83], v[164:167], v[212:215], v[80:83]
	v_mfma_f32_16x16x32_bf16 v[68:71], v[148:151], v[220:223], v[68:71]
	v_mfma_f32_16x16x32_bf16 v[64:67], v[164:167], v[220:223], v[64:67]
	s_barrier
; #define PG8_STAGE(bufoff, gbase, voff) do { _Pragma("unroll") for (int _i = 0; _i < 2; ++_i) \
;         __builtin_amdgcn_global_load_lds((const unsigned*)((const char*)(gbase) + (voff)[_i]), (LAS unsigned*)(lds + (bufoff) + ldsw + _i * 8192), 16, 0, 0); } while (0)
; #define PG8_LDA(dst, b, h) do { _Pragma("unroll") for (int m = 0; m < 4; ++m) _Pragma("unroll") for (int k = 0; k < 2; ++k) dst[m][k] = *(const LAS bf16x8*)(lds + PG8_SA(b, h) + aoff + m * 2048 + k * 1024); } while (0)
; #define PG8_LDB(dst, b, h) do { _Pragma("unroll") for (int n = 0; n < 2; ++n) _Pragma("unroll") for (int k = 0; k < 2; ++k) dst[n][k] = *(const LAS bf16x8*)(lds + PG8_SB(b, h) + boff + n * 2048 + k * 1024); } while (0)
; #define PG8_WAIT_V(n) asm volatile("s_waitcnt vmcnt(" #n ")" ::: "memory")
; #define PG8_BAR __builtin_amdgcn_s_barrier()
; template <class Epi, class Sched>
; __device__ __forceinline__ void gemm_phase(LAS unsigned char* lds, const Gemm g, const Sched& S, const Epi& E) {
;     ...
;         for (int t = 0; t < nt; t += 2) {
;             const bool last = (t == nt - 2);
;             const char* a1 = cA + (size_t)(t + 1) * kstep;
;             const char* a2 = last ? nA : cA + (size_t)(t + 2) * kstep; const char* b2 = last ? nB : cB + (size_t)(t + 2) * kstep;
;             const char* a3 = a2 + kstep; const char* b3 = b2 + kstep;
;             PG8_LDB(B0, 0, 0); PG8_LDB(B1, 0, 1); PG8_SCHED; PG8_LDA(At, 0, 0); PG8_STAGE(PG8_SA(1, 1), a1 + hstepA, voffA);
;             PG8_WAIT_V(8); PG8_WAIT_L(0); PG8_BAR; PG8_MMA(0, 0, At, B0); PG8_MMA(0, 1, At, B1); PG8_BAR; PG8_SCHED;
;             PG8_LDA(At, 0, 1); PG8_STAGE(PG8_SB(0, 0), b2, voffB); PG8_STAGE(PG8_SB(0, 1), b2 + hstepB, voffB); PG8_STAGE(PG8_SA(0, 0), a2, voffA);
;             PG8_WAIT_V(8); PG8_WAIT_L(0); PG8_BAR; PG8_MMA(1, 0, At, B0); PG8_MMA(1, 1, At, B1); PG8_BAR; PG8_SCHED;
;             PG8_LDB(B0, 1, 0); PG8_LDB(B1, 1, 1); PG8_SCHED; PG8_LDA(At, 1, 0); PG8_STAGE(PG8_SA(0, 1), a2 + hstepA, voffA);
;             PG8_WAIT_V(8); PG8_WAIT_L(0); PG8_BAR; PG8_MMA(0, 0, At, B0); PG8_MMA(0, 1, At, B1); PG8_BAR; PG8_SCHED;
;             PG8_LDA(At, 1, 1); PG8_STAGE(PG8_SB(1, 0), b3, voffB); PG8_STAGE(PG8_SB(1, 1), b3 + hstepB, voffB); PG8_STAGE(PG8_SA(1, 0), a3, voffA);
;             PG8_WAIT_V(8); PG8_WAIT_L(0); PG8_BAR; PG8_MMA(1, 0, At, B0); PG8_MMA(1, 1, At, B1); PG8_BAR; PG8_SCHED;
;         }
	s_mov_b32 m0, s23
	v_lshl_add_u64 v[192:193], v[192:193], 0, s[30:31]
	ds_read_b128 v[168:171], v191 offset:49152
	ds_read_b128 v[196:199], v191 offset:50176
	ds_read_b128 v[200:203], v191 offset:51200
	ds_read_b128 v[204:207], v191 offset:52224
	ds_read_b128 v[208:211], v191 offset:53248
	ds_read_b128 v[212:215], v191 offset:54272
	ds_read_b128 v[216:219], v191 offset:55296
	ds_read_b128 v[220:223], v191 offset:56320
	global_load_lds_dwordx4 v[192:193], off
	v_lshl_add_u64 v[192:193], v[224:225], 0, s[30:31]
	s_mov_b32 m0, s26
	s_nop 0
	global_load_lds_dwordx4 v[192:193], off
	v_lshl_add_u64 v[192:193], s[56:57], 0, v[160:161]
	s_mov_b32 m0, s83
	s_nop 0
	global_load_lds_dwordx4 v[192:193], off
	v_lshl_add_u64 v[192:193], s[56:57], 0, v[162:163]
	s_mov_b32 m0, s80
	s_nop 0
	global_load_lds_dwordx4 v[192:193], off
	v_lshl_add_u64 v[192:193], v[226:227], 0, s[30:31]
	s_mov_b32 m0, s90
	s_nop 0
	global_load_lds_dwordx4 v[192:193], off
	v_lshl_add_u64 v[192:193], v[228:229], 0, s[30:31]
	s_mov_b32 m0, s21
	s_nop 0
	global_load_lds_dwordx4 v[192:193], off
	s_waitcnt vmcnt(8)
	s_waitcnt lgkmcnt(0)
	s_barrier
	v_mfma_f32_16x16x32_bf16 v[60:63], v[128:131], v[168:171], v[60:63]
	v_mfma_f32_16x16x32_bf16 v[56:59], v[136:139], v[168:171], v[56:59]
	v_mfma_f32_16x16x32_bf16 v[44:47], v[128:131], v[200:203], v[44:47]
	v_mfma_f32_16x16x32_bf16 v[40:43], v[136:139], v[200:203], v[40:43]
	v_mfma_f32_16x16x32_bf16 v[28:31], v[128:131], v[208:211], v[28:31]
	v_mfma_f32_16x16x32_bf16 v[24:27], v[136:139], v[208:211], v[24:27]
	v_mfma_f32_16x16x32_bf16 v[12:15], v[128:131], v[216:219], v[12:15]
	v_mfma_f32_16x16x32_bf16 v[8:11], v[136:139], v[216:219], v[8:11]
	v_mfma_f32_16x16x32_bf16 v[60:63], v[132:135], v[196:199], v[60:63]
	v_mfma_f32_16x16x32_bf16 v[56:59], v[140:143], v[196:199], v[56:59]
	v_mfma_f32_16x16x32_bf16 v[44:47], v[132:135], v[204:207], v[44:47]
	v_mfma_f32_16x16x32_bf16 v[40:43], v[140:143], v[204:207], v[40:43]
	v_mfma_f32_16x16x32_bf16 v[28:31], v[132:135], v[212:215], v[28:31]
	v_mfma_f32_16x16x32_bf16 v[24:27], v[140:143], v[212:215], v[24:27]
	v_mfma_f32_16x16x32_bf16 v[12:15], v[132:135], v[220:223], v[12:15]
	v_mfma_f32_16x16x32_bf16 v[8:11], v[140:143], v[220:223], v[8:11]
	v_mfma_f32_16x16x32_bf16 v[52:55], v[144:147], v[168:171], v[52:55]
	v_mfma_f32_16x16x32_bf16 v[48:51], v[152:155], v[168:171], v[48:51]
	v_mfma_f32_16x16x32_bf16 v[36:39], v[144:147], v[200:203], v[36:39]
	v_mfma_f32_16x16x32_bf16 v[32:35], v[152:155], v[200:203], v[32:35]
	v_mfma_f32_16x16x32_bf16 v[20:23], v[144:147], v[208:211], v[20:23]
	v_mfma_f32_16x16x32_bf16 v[16:19], v[152:155], v[208:211], v[16:19]
	v_mfma_f32_16x16x32_bf16 v[4:7], v[144:147], v[216:219], v[4:7]
	v_mfma_f32_16x16x32_bf16 v[0:3], v[152:155], v[216:219], v[0:3]
	v_mfma_f32_16x16x32_bf16 v[52:55], v[148:151], v[196:199], v[52:55]
	v_mfma_f32_16x16x32_bf16 v[48:51], v[164:167], v[196:199], v[48:51]
	v_mfma_f32_16x16x32_bf16 v[36:39], v[148:151], v[204:207], v[36:39]
	v_mfma_f32_16x16x32_bf16 v[32:35], v[164:167], v[204:207], v[32:35]
	v_mfma_f32_16x16x32_bf16 v[20:23], v[148:151], v[212:215], v[20:23]
	v_mfma_f32_16x16x32_bf16 v[16:19], v[164:167], v[212:215], v[16:19]
	v_mfma_f32_16x16x32_bf16 v[4:7], v[148:151], v[220:223], v[4:7]
	v_mfma_f32_16x16x32_bf16 v[0:3], v[164:167], v[220:223], v[0:3]
	s_barrier
	s_movk_i32 s6, 0x100
	s_andn2_b64 vcc, exec, s[54:55]
	s_mov_b64 s[56:57], -1
	s_mov_b64 s[54:55], 0
.LBB0_628:
	s_add_u32 s0, s52, s6
	s_addc_u32 s23, s53, 0
	s_add_u32 s7, s0, 0x100
	s_addc_u32 s26, s23, 0
	s_and_b64 s[14:15], s[56:57], exec
	s_cselect_b32 vcc_hi, s45, s26
	s_cselect_b32 vcc_lo, s44, s7
	s_add_u32 s6, s50, s6
	s_addc_u32 s7, s51, 0
	s_add_u32 s14, s6, 0x100
	s_addc_u32 s15, s7, 0
	s_add_i32 s80, 0, 0x10000
	s_and_b64 s[6:7], s[56:57], exec
	s_cselect_b32 s7, s9, s15
	s_cselect_b32 s6, s13, s14
	s_add_i32 s57, 0, 0x14000
	s_add_u32 s78, s0, 0x40080
	s_addc_u32 s79, s23, 0
	s_add_i32 s97, s80, s24
	s_add_i32 m0, s25, 0xc000
	s_add_i32 s81, s25, 0xe000
	s_add_i32 s88, s97, 0x2000
	s_add_u32 s14, s6, 0x10000
	v_add_u32_e32 v140, s80, v174
	v_add_u32_e32 v164, s57, v174
	s_addc_u32 s15, s7, 0
	s_add_i32 s89, s57, s24
	ds_read_b128 v[128:131], v140
	ds_read_b128 v[132:135], v140 offset:1024
	ds_read_b128 v[136:139], v140 offset:2048
	ds_read_b128 v[140:143], v140 offset:3072
	ds_read_b128 v[144:147], v164
	ds_read_b128 v[148:151], v164 offset:1024
	ds_read_b128 v[152:155], v164 offset:2048
	ds_read_b128 v[164:167], v164 offset:3072
	s_add_i32 s96, s89, 0x2000
	s_add_i32 s35, 0, 0x18000
	s_add_i32 s0, 0, 0x1c000
	s_add_u32 s68, vcc_lo, 0x40000
	s_addc_u32 s69, vcc_hi, 0
	s_add_i32 s23, s35, s24
	s_add_i32 s26, s23, 0x2000
	s_add_u32 s56, s6, 0x10080
	s_addc_u32 s57, s7, 0
	s_add_i32 s83, s0, s24
	s_add_i32 s80, s83, 0x2000
	v_lshl_add_u64 v[192:193], s[78:79], 0, v[156:157]
	ds_read_b128 v[168:171], v191
	ds_read_b128 v[196:199], v191 offset:1024
	ds_read_b128 v[200:203], v191 offset:2048
	ds_read_b128 v[204:207], v191 offset:3072
	ds_read_b128 v[208:211], v191 offset:4096
	ds_read_b128 v[212:215], v191 offset:5120
	ds_read_b128 v[216:219], v191 offset:6144
	ds_read_b128 v[220:223], v191 offset:7168
	global_load_lds_dwordx4 v[192:193], off
	v_lshl_add_u64 v[192:193], s[78:79], 0, v[158:159]
	s_mov_b32 m0, s81
	s_nop 0
	global_load_lds_dwordx4 v[192:193], off
	s_waitcnt vmcnt(8)
	s_waitcnt lgkmcnt(0)
	s_barrier
; #define PG8_STAGE(bufoff, gbase, voff) do { _Pragma("unroll") for (int _i = 0; _i < 2; ++_i) \
;         __builtin_amdgcn_global_load_lds((const unsigned*)((const char*)(gbase) + (voff)[_i]), (LAS unsigned*)(lds + (bufoff) + ldsw + _i * 8192), 16, 0, 0); } while (0)
; #define PG8_LDA(dst, b, h) do { _Pragma("unroll") for (int m = 0; m < 4; ++m) _Pragma("unroll") for (int k = 0; k < 2; ++k) dst[m][k] = *(const LAS bf16x8*)(lds + PG8_SA(b, h) + aoff + m * 2048 + k * 1024); } while (0)
; #define PG8_LDB(dst, b, h) do { _Pragma("unroll") for (int n = 0; n < 2; ++n) _Pragma("unroll") for (int k = 0; k < 2; ++k) dst[n][k] = *(const LAS bf16x8*)(lds + PG8_SB(b, h) + boff + n * 2048 + k * 1024); } while (0)
; #define PG8_MMA(ai, bj, At, Bt) do { __builtin_amdgcn_s_setprio(1); _Pragma("unroll") for (int m = 0; m < 4; ++m) _Pragma("unroll") for (int n = 0; n < 2; ++n) _Pragma("unroll") for (int k = 0; k < 2; ++k) \
;         acc[ai][bj][m][n] = __builtin_amdgcn_mfma_f32_16x16x32_bf16(Bt[n][k], At[m][k], acc[ai][bj][m][n], 0, 0, 0); __builtin_amdgcn_s_setprio(0); } while (0)
; #define PG8_WAIT_V(n) asm volatile("s_waitcnt vmcnt(" #n ")" ::: "memory")
; #define PG8_WAIT_L(n) asm volatile("s_waitcnt lgkmcnt(" #n ")" ::: "memory")
; #define PG8_BAR __builtin_amdgcn_s_barrier()
; #define PG8_SCHED __builtin_amdgcn_sched_barrier(0)
; template <class Epi, class Sched>
; __device__ __forceinline__ void gemm_phase(LAS unsigned char* lds, const Gemm g, const Sched& S, const Epi& E) {
;     ...
;             PG8_WAIT_V(8); PG8_WAIT_L(0); PG8_BAR; PG8_MMA(0, 0, At, B0); PG8_MMA(0, 1, At, B1); PG8_BAR; PG8_SCHED;
;             PG8_LDA(At, 0, 1); PG8_STAGE(PG8_SB(0, 0), b2, voffB); PG8_STAGE(PG8_SB(0, 1), b2 + hstepB, voffB); PG8_STAGE(PG8_SA(0, 0), a2, voffA);
;             PG8_WAIT_V(8); PG8_WAIT_L(0); PG8_BAR; PG8_MMA(1, 0, At, B0); PG8_MMA(1, 1, At, B1); PG8_BAR; PG8_SCHED;
;             PG8_LDB(B0, 1, 0); PG8_LDB(B1, 1, 1); PG8_SCHED; PG8_LDA(At, 1, 0); PG8_STAGE(PG8_SA(0, 1), a2 + hstepA, voffA);
;             PG8_WAIT_V(8); PG8_WAIT_L(0); PG8_BAR; PG8_MMA(0, 0, At, B0); PG8_MMA(0, 1, At, B1); PG8_BAR; PG8_SCHED;
	v_mfma_f32_16x16x32_bf16 v[124:127], v[128:131], v[168:171], v[124:127]
	v_mfma_f32_16x16x32_bf16 v[120:123], v[136:139], v[168:171], v[120:123]
	v_mfma_f32_16x16x32_bf16 v[108:111], v[128:131], v[200:203], v[108:111]
	v_mfma_f32_16x16x32_bf16 v[104:107], v[136:139], v[200:203], v[104:107]
	v_mfma_f32_16x16x32_bf16 v[92:95], v[128:131], v[208:211], v[92:95]
	v_mfma_f32_16x16x32_bf16 v[88:91], v[136:139], v[208:211], v[88:91]
	v_mfma_f32_16x16x32_bf16 v[76:79], v[128:131], v[216:219], v[76:79]
	v_mfma_f32_16x16x32_bf16 v[72:75], v[136:139], v[216:219], v[72:75]
	v_mfma_f32_16x16x32_bf16 v[124:127], v[132:135], v[196:199], v[124:127]
	v_mfma_f32_16x16x32_bf16 v[120:123], v[140:143], v[196:199], v[120:123]
	v_mfma_f32_16x16x32_bf16 v[108:111], v[132:135], v[204:207], v[108:111]
	v_mfma_f32_16x16x32_bf16 v[104:107], v[140:143], v[204:207], v[104:107]
	v_mfma_f32_16x16x32_bf16 v[92:95], v[132:135], v[212:215], v[92:95]
	v_mfma_f32_16x16x32_bf16 v[88:91], v[140:143], v[212:215], v[88:91]
	v_mfma_f32_16x16x32_bf16 v[76:79], v[132:135], v[220:223], v[76:79]
	v_mfma_f32_16x16x32_bf16 v[72:75], v[140:143], v[220:223], v[72:75]
	v_mfma_f32_16x16x32_bf16 v[116:119], v[144:147], v[168:171], v[116:119]
	v_mfma_f32_16x16x32_bf16 v[112:115], v[152:155], v[168:171], v[112:115]
	v_mfma_f32_16x16x32_bf16 v[100:103], v[144:147], v[200:203], v[100:103]
	v_mfma_f32_16x16x32_bf16 v[96:99], v[152:155], v[200:203], v[96:99]
	v_mfma_f32_16x16x32_bf16 v[84:87], v[144:147], v[208:211], v[84:87]
	v_mfma_f32_16x16x32_bf16 v[80:83], v[152:155], v[208:211], v[80:83]
	v_mfma_f32_16x16x32_bf16 v[68:71], v[144:147], v[216:219], v[68:71]
	v_mfma_f32_16x16x32_bf16 v[64:67], v[152:155], v[216:219], v[64:67]
	v_mfma_f32_16x16x32_bf16 v[116:119], v[148:151], v[196:199], v[116:119]
	v_mfma_f32_16x16x32_bf16 v[112:115], v[164:167], v[196:199], v[112:115]
	v_mfma_f32_16x16x32_bf16 v[100:103], v[148:151], v[204:207], v[100:103]
	v_mfma_f32_16x16x32_bf16 v[96:99], v[164:167], v[204:207], v[96:99]
	v_mfma_f32_16x16x32_bf16 v[84:87], v[148:151], v[212:215], v[84:87]
	v_mfma_f32_16x16x32_bf16 v[80:83], v[164:167], v[212:215], v[80:83]
	v_mfma_f32_16x16x32_bf16 v[68:71], v[148:151], v[220:223], v[68:71]
	v_mfma_f32_16x16x32_bf16 v[64:67], v[164:167], v[220:223], v[64:67]
	s_barrier
	s_mov_b32 m0, s97
	v_lshl_add_u64 v[192:193], s[6:7], 0, v[160:161]
	ds_read_b128 v[168:171], v191 offset:16384
	ds_read_b128 v[196:199], v191 offset:17408
	ds_read_b128 v[200:203], v191 offset:18432
	ds_read_b128 v[204:207], v191 offset:19456
	ds_read_b128 v[208:211], v191 offset:20480
	ds_read_b128 v[212:215], v191 offset:21504
	ds_read_b128 v[216:219], v191 offset:22528
	ds_read_b128 v[220:223], v191 offset:23552
	global_load_lds_dwordx4 v[192:193], off
	v_lshl_add_u64 v[224:225], s[6:7], 0, v[162:163]
	s_mov_b32 m0, s88
	v_lshl_add_u64 v[226:227], s[14:15], 0, v[160:161]
	global_load_lds_dwordx4 v[224:225], off
	s_mov_b32 m0, s89
	v_lshl_add_u64 v[228:229], vcc, 0, v[158:159]
	global_load_lds_dwordx4 v[226:227], off
	v_lshl_add_u64 v[226:227], s[14:15], 0, v[162:163]
	s_mov_b32 m0, s96
	s_nop 0
	global_load_lds_dwordx4 v[226:227], off
	v_lshl_add_u64 v[226:227], vcc, 0, v[156:157]
	s_mov_b32 m0, s25
	s_nop 0
	global_load_lds_dwordx4 v[226:227], off
	s_mov_b32 m0, s49
	s_nop 0
	global_load_lds_dwordx4 v[228:229], off
	s_waitcnt vmcnt(8)
	s_waitcnt lgkmcnt(0)
	s_barrier
	v_mfma_f32_16x16x32_bf16 v[60:63], v[128:131], v[168:171], v[60:63]
	v_mfma_f32_16x16x32_bf16 v[56:59], v[136:139], v[168:171], v[56:59]
	v_mfma_f32_16x16x32_bf16 v[44:47], v[128:131], v[200:203], v[44:47]
	v_mfma_f32_16x16x32_bf16 v[40:43], v[136:139], v[200:203], v[40:43]
	v_mfma_f32_16x16x32_bf16 v[28:31], v[128:131], v[208:211], v[28:31]
	v_mfma_f32_16x16x32_bf16 v[24:27], v[136:139], v[208:211], v[24:27]
	v_mfma_f32_16x16x32_bf16 v[12:15], v[128:131], v[216:219], v[12:15]
	v_mfma_f32_16x16x32_bf16 v[8:11], v[136:139], v[216:219], v[8:11]
	v_mfma_f32_16x16x32_bf16 v[60:63], v[132:135], v[196:199], v[60:63]
	v_mfma_f32_16x16x32_bf16 v[56:59], v[140:143], v[196:199], v[56:59]
	v_mfma_f32_16x16x32_bf16 v[44:47], v[132:135], v[204:207], v[44:47]
	v_mfma_f32_16x16x32_bf16 v[40:43], v[140:143], v[204:207], v[40:43]
	v_mfma_f32_16x16x32_bf16 v[28:31], v[132:135], v[212:215], v[28:31]
	v_mfma_f32_16x16x32_bf16 v[24:27], v[140:143], v[212:215], v[24:27]
	v_mfma_f32_16x16x32_bf16 v[12:15], v[132:135], v[220:223], v[12:15]
	v_mfma_f32_16x16x32_bf16 v[8:11], v[140:143], v[220:223], v[8:11]
	v_mfma_f32_16x16x32_bf16 v[52:55], v[144:147], v[168:171], v[52:55]
	v_mfma_f32_16x16x32_bf16 v[48:51], v[152:155], v[168:171], v[48:51]
	v_mfma_f32_16x16x32_bf16 v[36:39], v[144:147], v[200:203], v[36:39]
	v_mfma_f32_16x16x32_bf16 v[32:35], v[152:155], v[200:203], v[32:35]
	v_mfma_f32_16x16x32_bf16 v[20:23], v[144:147], v[208:211], v[20:23]
	v_mfma_f32_16x16x32_bf16 v[16:19], v[152:155], v[208:211], v[16:19]
	v_mfma_f32_16x16x32_bf16 v[4:7], v[144:147], v[216:219], v[4:7]
	v_mfma_f32_16x16x32_bf16 v[0:3], v[152:155], v[216:219], v[0:3]
	v_mfma_f32_16x16x32_bf16 v[52:55], v[148:151], v[196:199], v[52:55]
	v_mfma_f32_16x16x32_bf16 v[48:51], v[164:167], v[196:199], v[48:51]
	v_mfma_f32_16x16x32_bf16 v[36:39], v[148:151], v[204:207], v[36:39]
	v_mfma_f32_16x16x32_bf16 v[32:35], v[164:167], v[204:207], v[32:35]
	v_mfma_f32_16x16x32_bf16 v[20:23], v[148:151], v[212:215], v[20:23]
	v_mfma_f32_16x16x32_bf16 v[16:19], v[164:167], v[212:215], v[16:19]
	v_mfma_f32_16x16x32_bf16 v[4:7], v[148:151], v[220:223], v[4:7]
	v_mfma_f32_16x16x32_bf16 v[0:3], v[164:167], v[220:223], v[0:3]
	s_barrier
; #define PG8_STAGE(bufoff, gbase, voff) do { _Pragma("unroll") for (int _i = 0; _i < 2; ++_i) \
;         __builtin_amdgcn_global_load_lds((const unsigned*)((const char*)(gbase) + (voff)[_i]), (LAS unsigned*)(lds + (bufoff) + ldsw + _i * 8192), 16, 0, 0); } while (0)
; #define PG8_LDA(dst, b, h) do { _Pragma("unroll") for (int m = 0; m < 4; ++m) _Pragma("unroll") for (int k = 0; k < 2; ++k) dst[m][k] = *(const LAS bf16x8*)(lds + PG8_SA(b, h) + aoff + m * 2048 + k * 1024); } while (0)
; #define PG8_LDB(dst, b, h) do { _Pragma("unroll") for (int n = 0; n < 2; ++n) _Pragma("unroll") for (int k = 0; k < 2; ++k) dst[n][k] = *(const LAS bf16x8*)(lds + PG8_SB(b, h) + boff + n * 2048 + k * 1024); } while (0)
; #define PG8_MMA(ai, bj, At, Bt) do { __builtin_amdgcn_s_setprio(1); _Pragma("unroll") for (int m = 0; m < 4; ++m) _Pragma("unroll") for (int n = 0; n < 2; ++n) _Pragma("unroll") for (int k = 0; k < 2; ++k) \
;         acc[ai][bj][m][n] = __builtin_amdgcn_mfma_f32_16x16x32_bf16(Bt[n][k], At[m][k], acc[ai][bj][m][n], 0, 0, 0); __builtin_amdgcn_s_setprio(0); } while (0)
; #define PG8_WAIT_V(n) asm volatile("s_waitcnt vmcnt(" #n ")" ::: "memory")
; #define PG8_WAIT_L(n) asm volatile("s_waitcnt lgkmcnt(" #n ")" ::: "memory")
; #define PG8_BAR __builtin_amdgcn_s_barrier()
; #define PG8_SCHED __builtin_amdgcn_sched_barrier(0)
; template <class Epi, class Sched>
; __device__ __forceinline__ void gemm_phase(LAS unsigned char* lds, const Gemm g, const Sched& S, const Epi& E) {
;     ...
;             PG8_LDB(B0, 1, 0); PG8_LDB(B1, 1, 1); PG8_SCHED; PG8_LDA(At, 1, 0); PG8_STAGE(PG8_SA(0, 1), a2 + hstepA, voffA);
;             PG8_WAIT_V(8); PG8_WAIT_L(0); PG8_BAR; PG8_MMA(0, 0, At, B0); PG8_MMA(0, 1, At, B1); PG8_BAR; PG8_SCHED;
;             PG8_LDA(At, 1, 1); PG8_STAGE(PG8_SB(1, 0), b3, voffB); PG8_STAGE(PG8_SB(1, 1), b3 + hstepB, voffB); PG8_STAGE(PG8_SA(1, 0), a3, voffA);
;             PG8_WAIT_V(8); PG8_WAIT_L(0); PG8_BAR; PG8_MMA(1, 0, At, B0); PG8_MMA(1, 1, At, B1); PG8_BAR; PG8_SCHED;
;         }
;         if (wr == 0) PG8_BAR;
	v_add_u32_e32 v140, s35, v174
	v_add_u32_e32 v164, s0, v174
	ds_read_b128 v[128:131], v140
	ds_read_b128 v[132:135], v140 offset:1024
	ds_read_b128 v[136:139], v140 offset:2048
	ds_read_b128 v[140:143], v140 offset:3072
	ds_read_b128 v[144:147], v164
	ds_read_b128 v[148:151], v164 offset:1024
	ds_read_b128 v[152:155], v164 offset:2048
	ds_read_b128 v[164:167], v164 offset:3072
	s_mov_b32 m0, s82
	v_lshl_add_u64 v[230:231], s[68:69], 0, v[156:157]
	ds_read_b128 v[168:171], v191 offset:32768
	ds_read_b128 v[196:199], v191 offset:33792
	ds_read_b128 v[200:203], v191 offset:34816
	ds_read_b128 v[204:207], v191 offset:35840
	ds_read_b128 v[208:211], v191 offset:36864
	ds_read_b128 v[212:215], v191 offset:37888
	ds_read_b128 v[216:219], v191 offset:38912
	ds_read_b128 v[220:223], v191 offset:39936
	global_load_lds_dwordx4 v[230:231], off
	v_lshl_add_u64 v[230:231], s[68:69], 0, v[158:159]
	s_mov_b32 m0, s33
	s_nop 0
	global_load_lds_dwordx4 v[230:231], off
	s_waitcnt vmcnt(8)
	s_waitcnt lgkmcnt(0)
	s_barrier
	v_mfma_f32_16x16x32_bf16 v[124:127], v[128:131], v[168:171], v[124:127]
	v_mfma_f32_16x16x32_bf16 v[120:123], v[136:139], v[168:171], v[120:123]
	v_mfma_f32_16x16x32_bf16 v[108:111], v[128:131], v[200:203], v[108:111]
	v_mfma_f32_16x16x32_bf16 v[104:107], v[136:139], v[200:203], v[104:107]
	v_mfma_f32_16x16x32_bf16 v[92:95], v[128:131], v[208:211], v[92:95]
	v_mfma_f32_16x16x32_bf16 v[88:91], v[136:139], v[208:211], v[88:91]
	v_mfma_f32_16x16x32_bf16 v[76:79], v[128:131], v[216:219], v[76:79]
	v_mfma_f32_16x16x32_bf16 v[72:75], v[136:139], v[216:219], v[72:75]
	v_mfma_f32_16x16x32_bf16 v[124:127], v[132:135], v[196:199], v[124:127]
	v_mfma_f32_16x16x32_bf16 v[120:123], v[140:143], v[196:199], v[120:123]
	v_mfma_f32_16x16x32_bf16 v[108:111], v[132:135], v[204:207], v[108:111]
	v_mfma_f32_16x16x32_bf16 v[104:107], v[140:143], v[204:207], v[104:107]
	v_mfma_f32_16x16x32_bf16 v[92:95], v[132:135], v[212:215], v[92:95]
	v_mfma_f32_16x16x32_bf16 v[88:91], v[140:143], v[212:215], v[88:91]
	v_mfma_f32_16x16x32_bf16 v[76:79], v[132:135], v[220:223], v[76:79]
	v_mfma_f32_16x16x32_bf16 v[72:75], v[140:143], v[220:223], v[72:75]
	v_mfma_f32_16x16x32_bf16 v[116:119], v[144:147], v[168:171], v[116:119]
	v_mfma_f32_16x16x32_bf16 v[112:115], v[152:155], v[168:171], v[112:115]
	v_mfma_f32_16x16x32_bf16 v[100:103], v[144:147], v[200:203], v[100:103]
	v_mfma_f32_16x16x32_bf16 v[96:99], v[152:155], v[200:203], v[96:99]
	v_mfma_f32_16x16x32_bf16 v[84:87], v[144:147], v[208:211], v[84:87]
	v_mfma_f32_16x16x32_bf16 v[80:83], v[152:155], v[208:211], v[80:83]
	v_mfma_f32_16x16x32_bf16 v[68:71], v[144:147], v[216:219], v[68:71]
	v_mfma_f32_16x16x32_bf16 v[64:67], v[152:155], v[216:219], v[64:67]
	v_mfma_f32_16x16x32_bf16 v[116:119], v[148:151], v[196:199], v[116:119]
	v_mfma_f32_16x16x32_bf16 v[112:115], v[164:167], v[196:199], v[112:115]
	v_mfma_f32_16x16x32_bf16 v[100:103], v[148:151], v[204:207], v[100:103]
	v_mfma_f32_16x16x32_bf16 v[96:99], v[164:167], v[204:207], v[96:99]
	v_mfma_f32_16x16x32_bf16 v[84:87], v[148:151], v[212:215], v[84:87]
	v_mfma_f32_16x16x32_bf16 v[80:83], v[164:167], v[212:215], v[80:83]
	v_mfma_f32_16x16x32_bf16 v[68:71], v[148:151], v[220:223], v[68:71]
	v_mfma_f32_16x16x32_bf16 v[64:67], v[164:167], v[220:223], v[64:67]
	s_barrier
	s_mov_b32 m0, s23
	v_lshl_add_u64 v[192:193], v[192:193], 0, s[30:31]
	ds_read_b128 v[168:171], v191 offset:49152
	ds_read_b128 v[196:199], v191 offset:50176
	ds_read_b128 v[200:203], v191 offset:51200
	ds_read_b128 v[204:207], v191 offset:52224
	ds_read_b128 v[208:211], v191 offset:53248
	ds_read_b128 v[212:215], v191 offset:54272
	ds_read_b128 v[216:219], v191 offset:55296
	ds_read_b128 v[220:223], v191 offset:56320
	global_load_lds_dwordx4 v[192:193], off
	v_lshl_add_u64 v[192:193], v[224:225], 0, s[30:31]
	s_mov_b32 m0, s26
	s_nop 0
	global_load_lds_dwordx4 v[192:193], off
	v_lshl_add_u64 v[192:193], s[56:57], 0, v[160:161]
	s_mov_b32 m0, s83
	s_nop 0
	global_load_lds_dwordx4 v[192:193], off
	v_lshl_add_u64 v[192:193], s[56:57], 0, v[162:163]
	s_mov_b32 m0, s80
	s_nop 0
	global_load_lds_dwordx4 v[192:193], off
	v_lshl_add_u64 v[192:193], v[226:227], 0, s[30:31]
	s_mov_b32 m0, s90
	s_nop 0
	global_load_lds_dwordx4 v[192:193], off
	v_lshl_add_u64 v[192:193], v[228:229], 0, s[30:31]
	s_mov_b32 m0, s21
	s_nop 0
	global_load_lds_dwordx4 v[192:193], off
	s_waitcnt vmcnt(8)
	s_waitcnt lgkmcnt(0)
	s_barrier
	v_mfma_f32_16x16x32_bf16 v[60:63], v[128:131], v[168:171], v[60:63]
	v_mfma_f32_16x16x32_bf16 v[56:59], v[136:139], v[168:171], v[56:59]
	v_mfma_f32_16x16x32_bf16 v[44:47], v[128:131], v[200:203], v[44:47]
	v_mfma_f32_16x16x32_bf16 v[40:43], v[136:139], v[200:203], v[40:43]
	v_mfma_f32_16x16x32_bf16 v[28:31], v[128:131], v[208:211], v[28:31]
	v_mfma_f32_16x16x32_bf16 v[24:27], v[136:139], v[208:211], v[24:27]
	v_mfma_f32_16x16x32_bf16 v[12:15], v[128:131], v[216:219], v[12:15]
	v_mfma_f32_16x16x32_bf16 v[8:11], v[136:139], v[216:219], v[8:11]
	v_mfma_f32_16x16x32_bf16 v[60:63], v[132:135], v[196:199], v[60:63]
	v_mfma_f32_16x16x32_bf16 v[56:59], v[140:143], v[196:199], v[56:59]
	v_mfma_f32_16x16x32_bf16 v[44:47], v[132:135], v[204:207], v[44:47]
	v_mfma_f32_16x16x32_bf16 v[40:43], v[140:143], v[204:207], v[40:43]
	v_mfma_f32_16x16x32_bf16 v[28:31], v[132:135], v[212:215], v[28:31]
	v_mfma_f32_16x16x32_bf16 v[24:27], v[140:143], v[212:215], v[24:27]
	v_mfma_f32_16x16x32_bf16 v[12:15], v[132:135], v[220:223], v[12:15]
	v_mfma_f32_16x16x32_bf16 v[8:11], v[140:143], v[220:223], v[8:11]
	v_mfma_f32_16x16x32_bf16 v[52:55], v[144:147], v[168:171], v[52:55]
	v_mfma_f32_16x16x32_bf16 v[48:51], v[152:155], v[168:171], v[48:51]
	v_mfma_f32_16x16x32_bf16 v[36:39], v[144:147], v[200:203], v[36:39]
	v_mfma_f32_16x16x32_bf16 v[32:35], v[152:155], v[200:203], v[32:35]
	v_mfma_f32_16x16x32_bf16 v[20:23], v[144:147], v[208:211], v[20:23]
	v_mfma_f32_16x16x32_bf16 v[16:19], v[152:155], v[208:211], v[16:19]
	v_mfma_f32_16x16x32_bf16 v[4:7], v[144:147], v[216:219], v[4:7]
	v_mfma_f32_16x16x32_bf16 v[0:3], v[152:155], v[216:219], v[0:3]
	v_mfma_f32_16x16x32_bf16 v[52:55], v[148:151], v[196:199], v[52:55]
	v_mfma_f32_16x16x32_bf16 v[48:51], v[164:167], v[196:199], v[48:51]
	v_mfma_f32_16x16x32_bf16 v[36:39], v[148:151], v[204:207], v[36:39]
	v_mfma_f32_16x16x32_bf16 v[32:35], v[164:167], v[204:207], v[32:35]
	v_mfma_f32_16x16x32_bf16 v[20:23], v[148:151], v[212:215], v[20:23]
	v_mfma_f32_16x16x32_bf16 v[16:19], v[164:167], v[212:215], v[16:19]
	v_mfma_f32_16x16x32_bf16 v[4:7], v[148:151], v[220:223], v[4:7]
	v_mfma_f32_16x16x32_bf16 v[0:3], v[164:167], v[220:223], v[0:3]
	s_barrier
	s_movk_i32 s6, 0x100
	s_andn2_b64 vcc, exec, s[54:55]
	s_mov_b64 s[56:57], -1
	s_mov_b64 s[54:55], 0
	s_cbranch_vccz .LBB0_628
	s_setprio 0
	s_and_b64 vcc, exec, s[18:19]
	s_cbranch_vccz .LBB0_631
	s_barrier

; #define PG8_STAGE(bufoff, gbase, voff) do { _Pragma("unroll") for (int _i = 0; _i < 2; ++_i) \
;         __builtin_amdgcn_global_load_lds((const unsigned*)((const char*)(gbase) + (voff)[_i]), (LAS unsigned*)(lds + (bufoff) + ldsw + _i * 8192), 16, 0, 0); } while (0)
; #define PG8_LDA(dst, b, h) do { _Pragma("unroll") for (int m = 0; m < 4; ++m) _Pragma("unroll") for (int k = 0; k < 2; ++k) dst[m][k] = *(const LAS bf16x8*)(lds + PG8_SA(b, h) + aoff + m * 2048 + k * 1024); } while (0)
; #define PG8_LDB(dst, b, h) do { _Pragma("unroll") for (int n = 0; n < 2; ++n) _Pragma("unroll") for (int k = 0; k < 2; ++k) dst[n][k] = *(const LAS bf16x8*)(lds + PG8_SB(b, h) + boff + n * 2048 + k * 1024); } while (0)
; #define PG8_MMA(ai, bj, At, Bt) do { __builtin_amdgcn_s_setprio(1); _Pragma("unroll") for (int m = 0; m < 4; ++m) _Pragma("unroll") for (int n = 0; n < 2; ++n) _Pragma("unroll") for (int k = 0; k < 2; ++k) \
;         acc[ai][bj][m][n] = __builtin_amdgcn_mfma_f32_16x16x32_bf16(Bt[n][k], At[m][k], acc[ai][bj][m][n], 0, 0, 0); __builtin_amdgcn_s_setprio(0); } while (0)
; #define PG8_BAR __builtin_amdgcn_s_barrier()
; template <class Epi, class Sched>
; __device__ __forceinline__ void gemm_phase(LAS unsigned char* lds, const Gemm g, const Sched& S, const Epi& E) {
;     ...
;         const bool has_next = S.next(ui + 1, nxt);
;         const char* nA = has_next ? (const char*)g.A + (size_t)nxt.pm * tstepA + (size_t)nxt.pn * apn : cA; const char* nB = has_next ? (const char*)g.Bt + (size_t)nxt.pn * tstepB : cB;
;         for (int t = 0; t < nt; t += 2) {
;             const bool last = (t == nt - 2);
;             const char* a1 = cA + (size_t)(t + 1) * kstep;
;             const char* a2 = last ? nA : cA + (size_t)(t + 2) * kstep; const char* b2 = last ? nB : cB + (size_t)(t + 2) * kstep;
;             const char* a3 = a2 + kstep; const char* b3 = b2 + kstep;
;             PG8_LDB(B0, 0, 0); PG8_LDB(B1, 0, 1); PG8_SCHED; PG8_LDA(At, 0, 0); PG8_STAGE(PG8_SA(1, 1), a1 + hstepA, voffA);
;             PG8_WAIT_V(8); PG8_WAIT_L(0); PG8_BAR; PG8_MMA(0, 0, At, B0); PG8_MMA(0, 1, At, B1); PG8_BAR; PG8_SCHED;
;             PG8_LDA(At, 0, 1); PG8_STAGE(PG8_SB(0, 0), b2, voffB); PG8_STAGE(PG8_SB(0, 1), b2 + hstepB, voffB); PG8_STAGE(PG8_SA(0, 0), a2, voffA);
;             PG8_WAIT_V(8); PG8_WAIT_L(0); PG8_BAR; PG8_MMA(1, 0, At, B0); PG8_MMA(1, 1, At, B1); PG8_BAR; PG8_SCHED;
.Lprio_gu:
	s_add_u32 s0, s44, 0xfffc0080
	s_addc_u32 s6, s45, -1
	s_add_i32 s26, 0, 0x10000
	s_cmp_eq_u32 s55, 12
	s_cselect_b32 s15, s23, s6
	s_cselect_b32 s14, s53, s0
	v_add_u32_e32 v153, s26, v148
	s_cselect_b32 s7, s19, s47
	s_cselect_b32 s6, s54, s46
	s_add_i32 s0, 0, 0x14000
	ds_read_b128 v[142:145], v153
	ds_read_b128 v[154:157], v153 offset:1024
	ds_read_b128 v[162:165], v153 offset:2048
	ds_read_b128 v[166:169], v153 offset:3072
	v_add_u32_e32 v153, s0, v148
	ds_read_b128 v[170:173], v153
	ds_read_b128 v[174:177], v153 offset:1024
	ds_read_b128 v[190:193], v153 offset:2048
	ds_read_b128 v[196:199], v153 offset:3072
	v_lshl_add_u64 v[158:159], s[44:45], 0, v[138:139]
	s_add_i32 m0, s49, 0xc000
	ds_read_b128 v[200:203], v152
	ds_read_b128 v[204:207], v152 offset:1024
	ds_read_b128 v[208:211], v152 offset:2048
	ds_read_b128 v[212:215], v152 offset:3072
	ds_read_b128 v[216:219], v152 offset:4096
	ds_read_b128 v[220:223], v152 offset:5120
	ds_read_b128 v[224:227], v152 offset:6144
	ds_read_b128 v[228:231], v152 offset:7168
	global_load_lds_dwordx4 v[158:159], off
	v_lshl_add_u64 v[158:159], s[44:45], 0, v[140:141]
	s_add_i32 m0, s49, 0xe000
	s_nop 0
	global_load_lds_dwordx4 v[158:159], off
	s_waitcnt vmcnt(8)
	s_waitcnt lgkmcnt(0)
	s_barrier
	v_mfma_f32_16x16x32_bf16 v[128:131], v[142:145], v[200:203], 0
	v_mfma_f32_16x16x32_bf16 v[124:127], v[162:165], v[200:203], 0
	v_mfma_f32_16x16x32_bf16 v[112:115], v[142:145], v[208:211], 0
	v_mfma_f32_16x16x32_bf16 v[108:111], v[162:165], v[208:211], 0
	v_mfma_f32_16x16x32_bf16 v[96:99], v[142:145], v[216:219], 0
	v_mfma_f32_16x16x32_bf16 v[92:95], v[162:165], v[216:219], 0
	v_mfma_f32_16x16x32_bf16 v[80:83], v[142:145], v[224:227], 0
	v_mfma_f32_16x16x32_bf16 v[76:79], v[162:165], v[224:227], 0
	v_mfma_f32_16x16x32_bf16 v[128:131], v[154:157], v[204:207], v[128:131]
	v_mfma_f32_16x16x32_bf16 v[124:127], v[166:169], v[204:207], v[124:127]
	v_mfma_f32_16x16x32_bf16 v[112:115], v[154:157], v[212:215], v[112:115]
	v_mfma_f32_16x16x32_bf16 v[108:111], v[166:169], v[212:215], v[108:111]
	v_mfma_f32_16x16x32_bf16 v[96:99], v[154:157], v[220:223], v[96:99]
	v_mfma_f32_16x16x32_bf16 v[92:95], v[166:169], v[220:223], v[92:95]
	v_mfma_f32_16x16x32_bf16 v[80:83], v[154:157], v[228:231], v[80:83]
	v_mfma_f32_16x16x32_bf16 v[76:79], v[166:169], v[228:231], v[76:79]
	v_mfma_f32_16x16x32_bf16 v[120:123], v[170:173], v[200:203], 0
	v_mfma_f32_16x16x32_bf16 v[116:119], v[190:193], v[200:203], 0
	v_mfma_f32_16x16x32_bf16 v[104:107], v[170:173], v[208:211], 0
	v_mfma_f32_16x16x32_bf16 v[100:103], v[190:193], v[208:211], 0
	v_mfma_f32_16x16x32_bf16 v[88:91], v[170:173], v[216:219], 0
	v_mfma_f32_16x16x32_bf16 v[84:87], v[190:193], v[216:219], 0
	v_mfma_f32_16x16x32_bf16 v[72:75], v[170:173], v[224:227], 0
	v_mfma_f32_16x16x32_bf16 v[68:71], v[190:193], v[224:227], 0
	v_mfma_f32_16x16x32_bf16 v[120:123], v[174:177], v[204:207], v[120:123]
	v_mfma_f32_16x16x32_bf16 v[116:119], v[196:199], v[204:207], v[116:119]
	v_mfma_f32_16x16x32_bf16 v[104:107], v[174:177], v[212:215], v[104:107]
	v_mfma_f32_16x16x32_bf16 v[100:103], v[196:199], v[212:215], v[100:103]
	v_mfma_f32_16x16x32_bf16 v[88:91], v[174:177], v[220:223], v[88:91]
	v_mfma_f32_16x16x32_bf16 v[84:87], v[196:199], v[220:223], v[84:87]
	v_mfma_f32_16x16x32_bf16 v[72:75], v[174:177], v[228:231], v[72:75]
	v_mfma_f32_16x16x32_bf16 v[68:71], v[196:199], v[228:231], v[68:71]
	s_barrier
	s_add_i32 s26, s26, s20
	v_lshl_add_u64 v[158:159], s[6:7], 0, v[160:161]
	s_mov_b32 m0, s26
	ds_read_b128 v[200:203], v152 offset:16384
	ds_read_b128 v[204:207], v152 offset:17408
	ds_read_b128 v[208:211], v152 offset:18432
	ds_read_b128 v[212:215], v152 offset:19456
	ds_read_b128 v[216:219], v152 offset:20480
	ds_read_b128 v[220:223], v152 offset:21504
	ds_read_b128 v[224:227], v152 offset:22528
	ds_read_b128 v[228:231], v152 offset:23552
	global_load_lds_dwordx4 v[158:159], off
	s_add_i32 m0, s26, 0x2000
	s_add_u32 s56, s6, 0x40000
	v_lshl_add_u64 v[232:233], s[6:7], 0, v[136:137]
	s_addc_u32 s57, s7, 0
	s_add_i32 s0, s0, s20
	global_load_lds_dwordx4 v[232:233], off
	v_lshl_add_u64 v[234:235], s[56:57], 0, v[160:161]
	s_mov_b32 m0, s0
	v_lshl_add_u64 v[236:237], s[14:15], 0, v[134:135]
	global_load_lds_dwordx4 v[234:235], off
	v_lshl_add_u64 v[234:235], s[56:57], 0, v[136:137]
	s_add_i32 m0, s0, 0x2000
	s_nop 0
	global_load_lds_dwordx4 v[234:235], off
	v_lshl_add_u64 v[234:235], s[14:15], 0, v[132:133]
	s_mov_b32 m0, s49
	s_nop 0
	global_load_lds_dwordx4 v[234:235], off
	s_mov_b32 m0, s50
	s_nop 0
	global_load_lds_dwordx4 v[236:237], off
	s_waitcnt vmcnt(8)
	s_waitcnt lgkmcnt(0)
	s_barrier
; #define PG8_STAGE(bufoff, gbase, voff) do { _Pragma("unroll") for (int _i = 0; _i < 2; ++_i) \
;         __builtin_amdgcn_global_load_lds((const unsigned*)((const char*)(gbase) + (voff)[_i]), (LAS unsigned*)(lds + (bufoff) + ldsw + _i * 8192), 16, 0, 0); } while (0)
; #define PG8_LDA(dst, b, h) do { _Pragma("unroll") for (int m = 0; m < 4; ++m) _Pragma("unroll") for (int k = 0; k < 2; ++k) dst[m][k] = *(const LAS bf16x8*)(lds + PG8_SA(b, h) + aoff + m * 2048 + k * 1024); } while (0)
; #define PG8_LDB(dst, b, h) do { _Pragma("unroll") for (int n = 0; n < 2; ++n) _Pragma("unroll") for (int k = 0; k < 2; ++k) dst[n][k] = *(const LAS bf16x8*)(lds + PG8_SB(b, h) + boff + n * 2048 + k * 1024); } while (0)
; #define PG8_MMA(ai, bj, At, Bt) do { __builtin_amdgcn_s_setprio(1); _Pragma("unroll") for (int m = 0; m < 4; ++m) _Pragma("unroll") for (int n = 0; n < 2; ++n) _Pragma("unroll") for (int k = 0; k < 2; ++k) \
;         acc[ai][bj][m][n] = __builtin_amdgcn_mfma_f32_16x16x32_bf16(Bt[n][k], At[m][k], acc[ai][bj][m][n], 0, 0, 0); __builtin_amdgcn_s_setprio(0); } while (0)
; #define PG8_WAIT_V(n) asm volatile("s_waitcnt vmcnt(" #n ")" ::: "memory")
; #define PG8_WAIT_L(n) asm volatile("s_waitcnt lgkmcnt(" #n ")" ::: "memory")
; #define PG8_BAR __builtin_amdgcn_s_barrier()
; #define PG8_SCHED __builtin_amdgcn_sched_barrier(0)
; template <class Epi, class Sched>
; __device__ __forceinline__ void gemm_phase(LAS unsigned char* lds, const Gemm g, const Sched& S, const Epi& E) {
;     ...
;             PG8_WAIT_V(8); PG8_WAIT_L(0); PG8_BAR; PG8_MMA(1, 0, At, B0); PG8_MMA(1, 1, At, B1); PG8_BAR; PG8_SCHED;
;             PG8_LDB(B0, 1, 0); PG8_LDB(B1, 1, 1); PG8_SCHED; PG8_LDA(At, 1, 0); PG8_STAGE(PG8_SA(0, 1), a2 + hstepA, voffA);
;             PG8_WAIT_V(8); PG8_WAIT_L(0); PG8_BAR; PG8_MMA(0, 0, At, B0); PG8_MMA(0, 1, At, B1); PG8_BAR; PG8_SCHED;
	v_mfma_f32_16x16x32_bf16 v[64:67], v[142:145], v[200:203], 0
	v_mfma_f32_16x16x32_bf16 v[60:63], v[162:165], v[200:203], 0
	v_mfma_f32_16x16x32_bf16 v[48:51], v[142:145], v[208:211], 0
	v_mfma_f32_16x16x32_bf16 v[44:47], v[162:165], v[208:211], 0
	v_mfma_f32_16x16x32_bf16 v[32:35], v[142:145], v[216:219], 0
	v_mfma_f32_16x16x32_bf16 v[28:31], v[162:165], v[216:219], 0
	v_mfma_f32_16x16x32_bf16 v[16:19], v[142:145], v[224:227], 0
	v_mfma_f32_16x16x32_bf16 v[12:15], v[162:165], v[224:227], 0
	v_mfma_f32_16x16x32_bf16 v[64:67], v[154:157], v[204:207], v[64:67]
	v_mfma_f32_16x16x32_bf16 v[60:63], v[166:169], v[204:207], v[60:63]
	v_mfma_f32_16x16x32_bf16 v[48:51], v[154:157], v[212:215], v[48:51]
	v_mfma_f32_16x16x32_bf16 v[44:47], v[166:169], v[212:215], v[44:47]
	v_mfma_f32_16x16x32_bf16 v[32:35], v[154:157], v[220:223], v[32:35]
	v_mfma_f32_16x16x32_bf16 v[28:31], v[166:169], v[220:223], v[28:31]
	v_mfma_f32_16x16x32_bf16 v[16:19], v[154:157], v[228:231], v[16:19]
	v_mfma_f32_16x16x32_bf16 v[12:15], v[166:169], v[228:231], v[12:15]
	v_mfma_f32_16x16x32_bf16 v[56:59], v[170:173], v[200:203], 0
	v_mfma_f32_16x16x32_bf16 v[52:55], v[190:193], v[200:203], 0
	v_mfma_f32_16x16x32_bf16 v[40:43], v[170:173], v[208:211], 0
	v_mfma_f32_16x16x32_bf16 v[36:39], v[190:193], v[208:211], 0
	v_mfma_f32_16x16x32_bf16 v[24:27], v[170:173], v[216:219], 0
	v_mfma_f32_16x16x32_bf16 v[20:23], v[190:193], v[216:219], 0
	v_mfma_f32_16x16x32_bf16 v[8:11], v[170:173], v[224:227], 0
	v_mfma_f32_16x16x32_bf16 v[4:7], v[190:193], v[224:227], 0
	v_mfma_f32_16x16x32_bf16 v[56:59], v[174:177], v[204:207], v[56:59]
	v_mfma_f32_16x16x32_bf16 v[52:55], v[196:199], v[204:207], v[52:55]
	v_mfma_f32_16x16x32_bf16 v[40:43], v[174:177], v[212:215], v[40:43]
	v_mfma_f32_16x16x32_bf16 v[36:39], v[196:199], v[212:215], v[36:39]
	v_mfma_f32_16x16x32_bf16 v[24:27], v[174:177], v[220:223], v[24:27]
	v_mfma_f32_16x16x32_bf16 v[20:23], v[196:199], v[220:223], v[20:23]
	v_mfma_f32_16x16x32_bf16 v[8:11], v[174:177], v[228:231], v[8:11]
	v_mfma_f32_16x16x32_bf16 v[4:7], v[196:199], v[228:231], v[4:7]
	s_barrier
	s_add_i32 s0, 0, 0x18000
	v_add_u32_e32 v153, s0, v148
	s_add_i32 s26, 0, 0x1c000
	ds_read_b128 v[142:145], v153
	ds_read_b128 v[154:157], v153 offset:1024
	ds_read_b128 v[162:165], v153 offset:2048
	ds_read_b128 v[166:169], v153 offset:3072
	v_add_u32_e32 v153, s26, v148
	ds_read_b128 v[170:173], v153
	ds_read_b128 v[174:177], v153 offset:1024
	ds_read_b128 v[190:193], v153 offset:2048
	ds_read_b128 v[196:199], v153 offset:3072
	s_add_u32 s14, s14, 0x40000
	s_addc_u32 s15, s15, 0
	s_mov_b32 m0, s51
	v_lshl_add_u64 v[238:239], s[14:15], 0, v[132:133]
	ds_read_b128 v[200:203], v152 offset:32768
	ds_read_b128 v[204:207], v152 offset:33792
	ds_read_b128 v[208:211], v152 offset:34816
	ds_read_b128 v[212:215], v152 offset:35840
	ds_read_b128 v[216:219], v152 offset:36864
	ds_read_b128 v[220:223], v152 offset:37888
	ds_read_b128 v[224:227], v152 offset:38912
	ds_read_b128 v[228:231], v152 offset:39936
	global_load_lds_dwordx4 v[238:239], off
	v_lshl_add_u64 v[238:239], s[14:15], 0, v[134:135]
	s_mov_b32 m0, s52
	s_nop 0
	global_load_lds_dwordx4 v[238:239], off
	s_waitcnt vmcnt(8)
	s_waitcnt lgkmcnt(0)
	s_barrier
	v_mfma_f32_16x16x32_bf16 v[128:131], v[142:145], v[200:203], v[128:131]
	v_mfma_f32_16x16x32_bf16 v[124:127], v[162:165], v[200:203], v[124:127]
	v_mfma_f32_16x16x32_bf16 v[112:115], v[142:145], v[208:211], v[112:115]
	v_mfma_f32_16x16x32_bf16 v[108:111], v[162:165], v[208:211], v[108:111]
	v_mfma_f32_16x16x32_bf16 v[96:99], v[142:145], v[216:219], v[96:99]
	v_mfma_f32_16x16x32_bf16 v[92:95], v[162:165], v[216:219], v[92:95]
	v_mfma_f32_16x16x32_bf16 v[80:83], v[142:145], v[224:227], v[80:83]
	v_mfma_f32_16x16x32_bf16 v[76:79], v[162:165], v[224:227], v[76:79]
	v_mfma_f32_16x16x32_bf16 v[128:131], v[154:157], v[204:207], v[128:131]
	v_mfma_f32_16x16x32_bf16 v[124:127], v[166:169], v[204:207], v[124:127]
	v_mfma_f32_16x16x32_bf16 v[112:115], v[154:157], v[212:215], v[112:115]
	v_mfma_f32_16x16x32_bf16 v[108:111], v[166:169], v[212:215], v[108:111]
	v_mfma_f32_16x16x32_bf16 v[96:99], v[154:157], v[220:223], v[96:99]
	v_mfma_f32_16x16x32_bf16 v[92:95], v[166:169], v[220:223], v[92:95]
	v_mfma_f32_16x16x32_bf16 v[80:83], v[154:157], v[228:231], v[80:83]
	v_mfma_f32_16x16x32_bf16 v[76:79], v[166:169], v[228:231], v[76:79]
	v_mfma_f32_16x16x32_bf16 v[120:123], v[170:173], v[200:203], v[120:123]
	v_mfma_f32_16x16x32_bf16 v[116:119], v[190:193], v[200:203], v[116:119]
	v_mfma_f32_16x16x32_bf16 v[104:107], v[170:173], v[208:211], v[104:107]
	v_mfma_f32_16x16x32_bf16 v[100:103], v[190:193], v[208:211], v[100:103]
	v_mfma_f32_16x16x32_bf16 v[88:91], v[170:173], v[216:219], v[88:91]
	v_mfma_f32_16x16x32_bf16 v[84:87], v[190:193], v[216:219], v[84:87]
	v_mfma_f32_16x16x32_bf16 v[72:75], v[170:173], v[224:227], v[72:75]
	v_mfma_f32_16x16x32_bf16 v[68:71], v[190:193], v[224:227], v[68:71]
	v_mfma_f32_16x16x32_bf16 v[120:123], v[174:177], v[204:207], v[120:123]
	v_mfma_f32_16x16x32_bf16 v[116:119], v[196:199], v[204:207], v[116:119]
	v_mfma_f32_16x16x32_bf16 v[104:107], v[174:177], v[212:215], v[104:107]
	v_mfma_f32_16x16x32_bf16 v[100:103], v[196:199], v[212:215], v[100:103]
	v_mfma_f32_16x16x32_bf16 v[88:91], v[174:177], v[220:223], v[88:91]
	v_mfma_f32_16x16x32_bf16 v[84:87], v[196:199], v[220:223], v[84:87]
	v_mfma_f32_16x16x32_bf16 v[72:75], v[174:177], v[228:231], v[72:75]
	v_mfma_f32_16x16x32_bf16 v[68:71], v[196:199], v[228:231], v[68:71]
	s_barrier
; #define PG8_STAGE(bufoff, gbase, voff) do { _Pragma("unroll") for (int _i = 0; _i < 2; ++_i) \
;         __builtin_amdgcn_global_load_lds((const unsigned*)((const char*)(gbase) + (voff)[_i]), (LAS unsigned*)(lds + (bufoff) + ldsw + _i * 8192), 16, 0, 0); } while (0)
; #define PG8_LDA(dst, b, h) do { _Pragma("unroll") for (int m = 0; m < 4; ++m) _Pragma("unroll") for (int k = 0; k < 2; ++k) dst[m][k] = *(const LAS bf16x8*)(lds + PG8_SA(b, h) + aoff + m * 2048 + k * 1024); } while (0)
; #define PG8_LDB(dst, b, h) do { _Pragma("unroll") for (int n = 0; n < 2; ++n) _Pragma("unroll") for (int k = 0; k < 2; ++k) dst[n][k] = *(const LAS bf16x8*)(lds + PG8_SB(b, h) + boff + n * 2048 + k * 1024); } while (0)
; #define PG8_MMA(ai, bj, At, Bt) do { __builtin_amdgcn_s_setprio(1); _Pragma("unroll") for (int m = 0; m < 4; ++m) _Pragma("unroll") for (int n = 0; n < 2; ++n) _Pragma("unroll") for (int k = 0; k < 2; ++k) \
;         acc[ai][bj][m][n] = __builtin_amdgcn_mfma_f32_16x16x32_bf16(Bt[n][k], At[m][k], acc[ai][bj][m][n], 0, 0, 0); __builtin_amdgcn_s_setprio(0); } while (0)
; #define PG8_WAIT_V(n) asm volatile("s_waitcnt vmcnt(" #n ")" ::: "memory")
; #define PG8_WAIT_L(n) asm volatile("s_waitcnt lgkmcnt(" #n ")" ::: "memory")
; #define PG8_BAR __builtin_amdgcn_s_barrier()
; #define PG8_SCHED __builtin_amdgcn_sched_barrier(0)
; template <class Epi, class Sched>
; __device__ __forceinline__ void gemm_phase(LAS unsigned char* lds, const Gemm g, const Sched& S, const Epi& E) {
;     ...
;         for (int t = 0; t < nt; t += 2) {
;             const bool last = (t == nt - 2);
;             const char* a1 = cA + (size_t)(t + 1) * kstep;
;             const char* a2 = last ? nA : cA + (size_t)(t + 2) * kstep; const char* b2 = last ? nB : cB + (size_t)(t + 2) * kstep;
;             const char* a3 = a2 + kstep; const char* b3 = b2 + kstep;
;             PG8_LDB(B0, 0, 0); PG8_LDB(B1, 0, 1); PG8_SCHED; PG8_LDA(At, 0, 0); PG8_STAGE(PG8_SA(1, 1), a1 + hstepA, voffA);
;             PG8_WAIT_V(8); PG8_WAIT_L(0); PG8_BAR; PG8_MMA(0, 0, At, B0); PG8_MMA(0, 1, At, B1); PG8_BAR; PG8_SCHED;
;     ...
;             PG8_LDA(At, 1, 1); PG8_STAGE(PG8_SB(1, 0), b3, voffB); PG8_STAGE(PG8_SB(1, 1), b3 + hstepB, voffB); PG8_STAGE(PG8_SA(1, 0), a3, voffA);
;             PG8_WAIT_V(8); PG8_WAIT_L(0); PG8_BAR; PG8_MMA(1, 0, At, B0); PG8_MMA(1, 1, At, B1); PG8_BAR; PG8_SCHED;
	s_add_i32 s0, s0, s20
	v_lshl_add_u64 v[158:159], v[158:159], 0, s[30:31]
	s_mov_b32 m0, s0
	ds_read_b128 v[200:203], v152 offset:49152
	ds_read_b128 v[204:207], v152 offset:50176
	ds_read_b128 v[208:211], v152 offset:51200
	ds_read_b128 v[212:215], v152 offset:52224
	ds_read_b128 v[216:219], v152 offset:53248
	ds_read_b128 v[220:223], v152 offset:54272
	ds_read_b128 v[224:227], v152 offset:55296
	ds_read_b128 v[228:231], v152 offset:56320
	global_load_lds_dwordx4 v[158:159], off
	s_add_i32 m0, s0, 0x2000
	s_add_u32 s6, s6, 0x40080
	v_lshl_add_u64 v[158:159], v[232:233], 0, s[30:31]
	s_addc_u32 s7, s7, 0
	s_add_i32 s0, s26, s20
	global_load_lds_dwordx4 v[158:159], off
	v_lshl_add_u64 v[158:159], s[6:7], 0, v[160:161]
	s_mov_b32 m0, s0
	s_nop 0
	global_load_lds_dwordx4 v[158:159], off
	v_lshl_add_u64 v[158:159], s[6:7], 0, v[136:137]
	s_add_i32 m0, s0, 0x2000
	s_nop 0
	global_load_lds_dwordx4 v[158:159], off
	v_lshl_add_u64 v[158:159], v[234:235], 0, s[30:31]
	s_mov_b32 m0, s24
	s_nop 0
	global_load_lds_dwordx4 v[158:159], off
	v_lshl_add_u64 v[158:159], v[236:237], 0, s[30:31]
	s_mov_b32 m0, s25
	s_nop 0
	global_load_lds_dwordx4 v[158:159], off
	s_waitcnt vmcnt(8)
	s_waitcnt lgkmcnt(0)
	s_barrier
	v_mfma_f32_16x16x32_bf16 v[64:67], v[142:145], v[200:203], v[64:67]
	v_mfma_f32_16x16x32_bf16 v[60:63], v[162:165], v[200:203], v[60:63]
	v_mfma_f32_16x16x32_bf16 v[48:51], v[142:145], v[208:211], v[48:51]
	v_mfma_f32_16x16x32_bf16 v[44:47], v[162:165], v[208:211], v[44:47]
	v_mfma_f32_16x16x32_bf16 v[32:35], v[142:145], v[216:219], v[32:35]
	v_mfma_f32_16x16x32_bf16 v[28:31], v[162:165], v[216:219], v[28:31]
	v_mfma_f32_16x16x32_bf16 v[16:19], v[142:145], v[224:227], v[16:19]
	v_mfma_f32_16x16x32_bf16 v[12:15], v[162:165], v[224:227], v[12:15]
	v_mfma_f32_16x16x32_bf16 v[64:67], v[154:157], v[204:207], v[64:67]
	v_mfma_f32_16x16x32_bf16 v[60:63], v[166:169], v[204:207], v[60:63]
	v_mfma_f32_16x16x32_bf16 v[48:51], v[154:157], v[212:215], v[48:51]
	v_mfma_f32_16x16x32_bf16 v[44:47], v[166:169], v[212:215], v[44:47]
	v_mfma_f32_16x16x32_bf16 v[32:35], v[154:157], v[220:223], v[32:35]
	v_mfma_f32_16x16x32_bf16 v[28:31], v[166:169], v[220:223], v[28:31]
	v_mfma_f32_16x16x32_bf16 v[16:19], v[154:157], v[228:231], v[16:19]
	v_mfma_f32_16x16x32_bf16 v[12:15], v[166:169], v[228:231], v[12:15]
	v_mfma_f32_16x16x32_bf16 v[56:59], v[170:173], v[200:203], v[56:59]
	v_mfma_f32_16x16x32_bf16 v[52:55], v[190:193], v[200:203], v[52:55]
	v_mfma_f32_16x16x32_bf16 v[40:43], v[170:173], v[208:211], v[40:43]
	v_mfma_f32_16x16x32_bf16 v[36:39], v[190:193], v[208:211], v[36:39]
	v_mfma_f32_16x16x32_bf16 v[24:27], v[170:173], v[216:219], v[24:27]
	v_mfma_f32_16x16x32_bf16 v[20:23], v[190:193], v[216:219], v[20:23]
	v_mfma_f32_16x16x32_bf16 v[8:11], v[170:173], v[224:227], v[8:11]
	v_mfma_f32_16x16x32_bf16 v[4:7], v[190:193], v[224:227], v[4:7]
	v_mfma_f32_16x16x32_bf16 v[56:59], v[174:177], v[204:207], v[56:59]
	v_mfma_f32_16x16x32_bf16 v[52:55], v[196:199], v[204:207], v[52:55]
	v_mfma_f32_16x16x32_bf16 v[40:43], v[174:177], v[212:215], v[40:43]
	v_mfma_f32_16x16x32_bf16 v[36:39], v[196:199], v[212:215], v[36:39]
	v_mfma_f32_16x16x32_bf16 v[24:27], v[174:177], v[220:223], v[24:27]
	v_mfma_f32_16x16x32_bf16 v[20:23], v[196:199], v[220:223], v[20:23]
	v_mfma_f32_16x16x32_bf16 v[8:11], v[174:177], v[228:231], v[8:11]
	v_mfma_f32_16x16x32_bf16 v[4:7], v[196:199], v[228:231], v[4:7]
	s_barrier
	s_add_i32 s55, s55, 2
	s_add_u32 s44, s44, 0x100
	s_addc_u32 s45, s45, 0
	s_add_u32 s46, s46, 0x100
	s_addc_u32 s47, s47, 0
	s_cmp_gt_u32 s55, 13
.LBB0_718:
	s_add_u32 s0, s44, 0xfffc0080
	s_addc_u32 s6, s45, -1
	s_add_i32 s26, 0, 0x10000
	s_cmp_eq_u32 s55, 12
	s_cselect_b32 s15, s23, s6
	s_cselect_b32 s14, s53, s0
	v_add_u32_e32 v153, s26, v148
	s_cselect_b32 s7, s19, s47
	s_cselect_b32 s6, s54, s46
	s_add_i32 s0, 0, 0x14000
	ds_read_b128 v[142:145], v153
	ds_read_b128 v[154:157], v153 offset:1024
	ds_read_b128 v[162:165], v153 offset:2048
	ds_read_b128 v[166:169], v153 offset:3072
	v_add_u32_e32 v153, s0, v148
	ds_read_b128 v[170:173], v153
	ds_read_b128 v[174:177], v153 offset:1024
	ds_read_b128 v[190:193], v153 offset:2048
	ds_read_b128 v[196:199], v153 offset:3072
	v_lshl_add_u64 v[158:159], s[44:45], 0, v[138:139]
	s_add_i32 m0, s49, 0xc000
	ds_read_b128 v[200:203], v152
	ds_read_b128 v[204:207], v152 offset:1024
	ds_read_b128 v[208:211], v152 offset:2048
	ds_read_b128 v[212:215], v152 offset:3072
	ds_read_b128 v[216:219], v152 offset:4096
	ds_read_b128 v[220:223], v152 offset:5120
	ds_read_b128 v[224:227], v152 offset:6144
	ds_read_b128 v[228:231], v152 offset:7168
	global_load_lds_dwordx4 v[158:159], off
	v_lshl_add_u64 v[158:159], s[44:45], 0, v[140:141]
	s_add_i32 m0, s49, 0xe000
	s_nop 0
	global_load_lds_dwordx4 v[158:159], off
	s_waitcnt vmcnt(8)
	s_waitcnt lgkmcnt(0)
	s_barrier
; #define PG8_STAGE(bufoff, gbase, voff) do { _Pragma("unroll") for (int _i = 0; _i < 2; ++_i) \
;         __builtin_amdgcn_global_load_lds((const unsigned*)((const char*)(gbase) + (voff)[_i]), (LAS unsigned*)(lds + (bufoff) + ldsw + _i * 8192), 16, 0, 0); } while (0)
; #define PG8_LDA(dst, b, h) do { _Pragma("unroll") for (int m = 0; m < 4; ++m) _Pragma("unroll") for (int k = 0; k < 2; ++k) dst[m][k] = *(const LAS bf16x8*)(lds + PG8_SA(b, h) + aoff + m * 2048 + k * 1024); } while (0)
; #define PG8_LDB(dst, b, h) do { _Pragma("unroll") for (int n = 0; n < 2; ++n) _Pragma("unroll") for (int k = 0; k < 2; ++k) dst[n][k] = *(const LAS bf16x8*)(lds + PG8_SB(b, h) + boff + n * 2048 + k * 1024); } while (0)
; #define PG8_MMA(ai, bj, At, Bt) do { __builtin_amdgcn_s_setprio(1); _Pragma("unroll") for (int m = 0; m < 4; ++m) _Pragma("unroll") for (int n = 0; n < 2; ++n) _Pragma("unroll") for (int k = 0; k < 2; ++k) \
;         acc[ai][bj][m][n] = __builtin_amdgcn_mfma_f32_16x16x32_bf16(Bt[n][k], At[m][k], acc[ai][bj][m][n], 0, 0, 0); __builtin_amdgcn_s_setprio(0); } while (0)
; #define PG8_WAIT_V(n) asm volatile("s_waitcnt vmcnt(" #n ")" ::: "memory")
; #define PG8_WAIT_L(n) asm volatile("s_waitcnt lgkmcnt(" #n ")" ::: "memory")
; #define PG8_BAR __builtin_amdgcn_s_barrier()
; #define PG8_SCHED __builtin_amdgcn_sched_barrier(0)
; template <class Epi, class Sched>
; __device__ __forceinline__ void gemm_phase(LAS unsigned char* lds, const Gemm g, const Sched& S, const Epi& E) {
;     ...
;             PG8_LDB(B0, 0, 0); PG8_LDB(B1, 0, 1); PG8_SCHED; PG8_LDA(At, 0, 0); PG8_STAGE(PG8_SA(1, 1), a1 + hstepA, voffA);
;             PG8_WAIT_V(8); PG8_WAIT_L(0); PG8_BAR; PG8_MMA(0, 0, At, B0); PG8_MMA(0, 1, At, B1); PG8_BAR; PG8_SCHED;
;             PG8_LDA(At, 0, 1); PG8_STAGE(PG8_SB(0, 0), b2, voffB); PG8_STAGE(PG8_SB(0, 1), b2 + hstepB, voffB); PG8_STAGE(PG8_SA(0, 0), a2, voffA);
;             PG8_WAIT_V(8); PG8_WAIT_L(0); PG8_BAR; PG8_MMA(1, 0, At, B0); PG8_MMA(1, 1, At, B1); PG8_BAR; PG8_SCHED;
	v_mfma_f32_16x16x32_bf16 v[128:131], v[142:145], v[200:203], v[128:131]
	v_mfma_f32_16x16x32_bf16 v[124:127], v[162:165], v[200:203], v[124:127]
	v_mfma_f32_16x16x32_bf16 v[112:115], v[142:145], v[208:211], v[112:115]
	v_mfma_f32_16x16x32_bf16 v[108:111], v[162:165], v[208:211], v[108:111]
	v_mfma_f32_16x16x32_bf16 v[96:99], v[142:145], v[216:219], v[96:99]
	v_mfma_f32_16x16x32_bf16 v[92:95], v[162:165], v[216:219], v[92:95]
	v_mfma_f32_16x16x32_bf16 v[80:83], v[142:145], v[224:227], v[80:83]
	v_mfma_f32_16x16x32_bf16 v[76:79], v[162:165], v[224:227], v[76:79]
	v_mfma_f32_16x16x32_bf16 v[128:131], v[154:157], v[204:207], v[128:131]
	v_mfma_f32_16x16x32_bf16 v[124:127], v[166:169], v[204:207], v[124:127]
	v_mfma_f32_16x16x32_bf16 v[112:115], v[154:157], v[212:215], v[112:115]
	v_mfma_f32_16x16x32_bf16 v[108:111], v[166:169], v[212:215], v[108:111]
	v_mfma_f32_16x16x32_bf16 v[96:99], v[154:157], v[220:223], v[96:99]
	v_mfma_f32_16x16x32_bf16 v[92:95], v[166:169], v[220:223], v[92:95]
	v_mfma_f32_16x16x32_bf16 v[80:83], v[154:157], v[228:231], v[80:83]
	v_mfma_f32_16x16x32_bf16 v[76:79], v[166:169], v[228:231], v[76:79]
	v_mfma_f32_16x16x32_bf16 v[120:123], v[170:173], v[200:203], v[120:123]
	v_mfma_f32_16x16x32_bf16 v[116:119], v[190:193], v[200:203], v[116:119]
	v_mfma_f32_16x16x32_bf16 v[104:107], v[170:173], v[208:211], v[104:107]
	v_mfma_f32_16x16x32_bf16 v[100:103], v[190:193], v[208:211], v[100:103]
	v_mfma_f32_16x16x32_bf16 v[88:91], v[170:173], v[216:219], v[88:91]
	v_mfma_f32_16x16x32_bf16 v[84:87], v[190:193], v[216:219], v[84:87]
	v_mfma_f32_16x16x32_bf16 v[72:75], v[170:173], v[224:227], v[72:75]
	v_mfma_f32_16x16x32_bf16 v[68:71], v[190:193], v[224:227], v[68:71]
	v_mfma_f32_16x16x32_bf16 v[120:123], v[174:177], v[204:207], v[120:123]
	v_mfma_f32_16x16x32_bf16 v[116:119], v[196:199], v[204:207], v[116:119]
	v_mfma_f32_16x16x32_bf16 v[104:107], v[174:177], v[212:215], v[104:107]
	v_mfma_f32_16x16x32_bf16 v[100:103], v[196:199], v[212:215], v[100:103]
	v_mfma_f32_16x16x32_bf16 v[88:91], v[174:177], v[220:223], v[88:91]
	v_mfma_f32_16x16x32_bf16 v[84:87], v[196:199], v[220:223], v[84:87]
	v_mfma_f32_16x16x32_bf16 v[72:75], v[174:177], v[228:231], v[72:75]
	v_mfma_f32_16x16x32_bf16 v[68:71], v[196:199], v[228:231], v[68:71]
	s_barrier
	s_add_i32 s26, s26, s20
	v_lshl_add_u64 v[158:159], s[6:7], 0, v[160:161]
	s_mov_b32 m0, s26
	ds_read_b128 v[200:203], v152 offset:16384
	ds_read_b128 v[204:207], v152 offset:17408
	ds_read_b128 v[208:211], v152 offset:18432
	ds_read_b128 v[212:215], v152 offset:19456
	ds_read_b128 v[216:219], v152 offset:20480
	ds_read_b128 v[220:223], v152 offset:21504
	ds_read_b128 v[224:227], v152 offset:22528
	ds_read_b128 v[228:231], v152 offset:23552
	global_load_lds_dwordx4 v[158:159], off
	s_add_i32 m0, s26, 0x2000
	s_add_u32 s56, s6, 0x40000
	v_lshl_add_u64 v[232:233], s[6:7], 0, v[136:137]
	s_addc_u32 s57, s7, 0
	s_add_i32 s0, s0, s20
	global_load_lds_dwordx4 v[232:233], off
	v_lshl_add_u64 v[234:235], s[56:57], 0, v[160:161]
	s_mov_b32 m0, s0
	v_lshl_add_u64 v[236:237], s[14:15], 0, v[134:135]
	global_load_lds_dwordx4 v[234:235], off
	v_lshl_add_u64 v[234:235], s[56:57], 0, v[136:137]
	s_add_i32 m0, s0, 0x2000
	s_nop 0
	global_load_lds_dwordx4 v[234:235], off
	v_lshl_add_u64 v[234:235], s[14:15], 0, v[132:133]
	s_mov_b32 m0, s49
	s_nop 0
	global_load_lds_dwordx4 v[234:235], off
	s_mov_b32 m0, s50
	s_nop 0
	global_load_lds_dwordx4 v[236:237], off
	s_waitcnt vmcnt(8)
	s_waitcnt lgkmcnt(0)
	s_barrier
	v_mfma_f32_16x16x32_bf16 v[64:67], v[142:145], v[200:203], v[64:67]
	v_mfma_f32_16x16x32_bf16 v[60:63], v[162:165], v[200:203], v[60:63]
	v_mfma_f32_16x16x32_bf16 v[48:51], v[142:145], v[208:211], v[48:51]
	v_mfma_f32_16x16x32_bf16 v[44:47], v[162:165], v[208:211], v[44:47]
	v_mfma_f32_16x16x32_bf16 v[32:35], v[142:145], v[216:219], v[32:35]
	v_mfma_f32_16x16x32_bf16 v[28:31], v[162:165], v[216:219], v[28:31]
	v_mfma_f32_16x16x32_bf16 v[16:19], v[142:145], v[224:227], v[16:19]
	v_mfma_f32_16x16x32_bf16 v[12:15], v[162:165], v[224:227], v[12:15]
	v_mfma_f32_16x16x32_bf16 v[64:67], v[154:157], v[204:207], v[64:67]
	v_mfma_f32_16x16x32_bf16 v[60:63], v[166:169], v[204:207], v[60:63]
	v_mfma_f32_16x16x32_bf16 v[48:51], v[154:157], v[212:215], v[48:51]
	v_mfma_f32_16x16x32_bf16 v[44:47], v[166:169], v[212:215], v[44:47]
	v_mfma_f32_16x16x32_bf16 v[32:35], v[154:157], v[220:223], v[32:35]
	v_mfma_f32_16x16x32_bf16 v[28:31], v[166:169], v[220:223], v[28:31]
	v_mfma_f32_16x16x32_bf16 v[16:19], v[154:157], v[228:231], v[16:19]
	v_mfma_f32_16x16x32_bf16 v[12:15], v[166:169], v[228:231], v[12:15]
	v_mfma_f32_16x16x32_bf16 v[56:59], v[170:173], v[200:203], v[56:59]
	v_mfma_f32_16x16x32_bf16 v[52:55], v[190:193], v[200:203], v[52:55]
	v_mfma_f32_16x16x32_bf16 v[40:43], v[170:173], v[208:211], v[40:43]
	v_mfma_f32_16x16x32_bf16 v[36:39], v[190:193], v[208:211], v[36:39]
	v_mfma_f32_16x16x32_bf16 v[24:27], v[170:173], v[216:219], v[24:27]
	v_mfma_f32_16x16x32_bf16 v[20:23], v[190:193], v[216:219], v[20:23]
	v_mfma_f32_16x16x32_bf16 v[8:11], v[170:173], v[224:227], v[8:11]
	v_mfma_f32_16x16x32_bf16 v[4:7], v[190:193], v[224:227], v[4:7]
	v_mfma_f32_16x16x32_bf16 v[56:59], v[174:177], v[204:207], v[56:59]
	v_mfma_f32_16x16x32_bf16 v[52:55], v[196:199], v[204:207], v[52:55]
	v_mfma_f32_16x16x32_bf16 v[40:43], v[174:177], v[212:215], v[40:43]
	v_mfma_f32_16x16x32_bf16 v[36:39], v[196:199], v[212:215], v[36:39]
	v_mfma_f32_16x16x32_bf16 v[24:27], v[174:177], v[220:223], v[24:27]
	v_mfma_f32_16x16x32_bf16 v[20:23], v[196:199], v[220:223], v[20:23]
	v_mfma_f32_16x16x32_bf16 v[8:11], v[174:177], v[228:231], v[8:11]
	v_mfma_f32_16x16x32_bf16 v[4:7], v[196:199], v[228:231], v[4:7]
	s_barrier
; #define PG8_STAGE(bufoff, gbase, voff) do { _Pragma("unroll") for (int _i = 0; _i < 2; ++_i) \
;         __builtin_amdgcn_global_load_lds((const unsigned*)((const char*)(gbase) + (voff)[_i]), (LAS unsigned*)(lds + (bufoff) + ldsw + _i * 8192), 16, 0, 0); } while (0)
; #define PG8_LDA(dst, b, h) do { _Pragma("unroll") for (int m = 0; m < 4; ++m) _Pragma("unroll") for (int k = 0; k < 2; ++k) dst[m][k] = *(const LAS bf16x8*)(lds + PG8_SA(b, h) + aoff + m * 2048 + k * 1024); } while (0)
; #define PG8_LDB(dst, b, h) do { _Pragma("unroll") for (int n = 0; n < 2; ++n) _Pragma("unroll") for (int k = 0; k < 2; ++k) dst[n][k] = *(const LAS bf16x8*)(lds + PG8_SB(b, h) + boff + n * 2048 + k * 1024); } while (0)
; #define PG8_MMA(ai, bj, At, Bt) do { __builtin_amdgcn_s_setprio(1); _Pragma("unroll") for (int m = 0; m < 4; ++m) _Pragma("unroll") for (int n = 0; n < 2; ++n) _Pragma("unroll") for (int k = 0; k < 2; ++k) \
;         acc[ai][bj][m][n] = __builtin_amdgcn_mfma_f32_16x16x32_bf16(Bt[n][k], At[m][k], acc[ai][bj][m][n], 0, 0, 0); __builtin_amdgcn_s_setprio(0); } while (0)
; #define PG8_WAIT_V(n) asm volatile("s_waitcnt vmcnt(" #n ")" ::: "memory")
; #define PG8_WAIT_L(n) asm volatile("s_waitcnt lgkmcnt(" #n ")" ::: "memory")
; #define PG8_BAR __builtin_amdgcn_s_barrier()
; #define PG8_SCHED __builtin_amdgcn_sched_barrier(0)
; template <class Epi, class Sched>
; __device__ __forceinline__ void gemm_phase(LAS unsigned char* lds, const Gemm g, const Sched& S, const Epi& E) {
;     ...
;             PG8_LDB(B0, 1, 0); PG8_LDB(B1, 1, 1); PG8_SCHED; PG8_LDA(At, 1, 0); PG8_STAGE(PG8_SA(0, 1), a2 + hstepA, voffA);
;             PG8_WAIT_V(8); PG8_WAIT_L(0); PG8_BAR; PG8_MMA(0, 0, At, B0); PG8_MMA(0, 1, At, B1); PG8_BAR; PG8_SCHED;
	s_add_i32 s0, 0, 0x18000
	v_add_u32_e32 v153, s0, v148
	s_add_i32 s26, 0, 0x1c000
	ds_read_b128 v[142:145], v153
	ds_read_b128 v[154:157], v153 offset:1024
	ds_read_b128 v[162:165], v153 offset:2048
	ds_read_b128 v[166:169], v153 offset:3072
	v_add_u32_e32 v153, s26, v148
	ds_read_b128 v[170:173], v153
	ds_read_b128 v[174:177], v153 offset:1024
	ds_read_b128 v[190:193], v153 offset:2048
	ds_read_b128 v[196:199], v153 offset:3072
	s_add_u32 s14, s14, 0x40000
	s_addc_u32 s15, s15, 0
	s_mov_b32 m0, s51
	v_lshl_add_u64 v[238:239], s[14:15], 0, v[132:133]
	ds_read_b128 v[200:203], v152 offset:32768
	ds_read_b128 v[204:207], v152 offset:33792
	ds_read_b128 v[208:211], v152 offset:34816
	ds_read_b128 v[212:215], v152 offset:35840
	ds_read_b128 v[216:219], v152 offset:36864
	ds_read_b128 v[220:223], v152 offset:37888
	ds_read_b128 v[224:227], v152 offset:38912
	ds_read_b128 v[228:231], v152 offset:39936
	global_load_lds_dwordx4 v[238:239], off
	v_lshl_add_u64 v[238:239], s[14:15], 0, v[134:135]
	s_mov_b32 m0, s52
	s_nop 0
	global_load_lds_dwordx4 v[238:239], off
	s_waitcnt vmcnt(8)
	s_waitcnt lgkmcnt(0)
	s_barrier
	v_mfma_f32_16x16x32_bf16 v[128:131], v[142:145], v[200:203], v[128:131]
	v_mfma_f32_16x16x32_bf16 v[124:127], v[162:165], v[200:203], v[124:127]
	v_mfma_f32_16x16x32_bf16 v[112:115], v[142:145], v[208:211], v[112:115]
	v_mfma_f32_16x16x32_bf16 v[108:111], v[162:165], v[208:211], v[108:111]
	v_mfma_f32_16x16x32_bf16 v[96:99], v[142:145], v[216:219], v[96:99]
	v_mfma_f32_16x16x32_bf16 v[92:95], v[162:165], v[216:219], v[92:95]
	v_mfma_f32_16x16x32_bf16 v[80:83], v[142:145], v[224:227], v[80:83]
	v_mfma_f32_16x16x32_bf16 v[76:79], v[162:165], v[224:227], v[76:79]
	v_mfma_f32_16x16x32_bf16 v[128:131], v[154:157], v[204:207], v[128:131]
	v_mfma_f32_16x16x32_bf16 v[124:127], v[166:169], v[204:207], v[124:127]
	v_mfma_f32_16x16x32_bf16 v[112:115], v[154:157], v[212:215], v[112:115]
	v_mfma_f32_16x16x32_bf16 v[108:111], v[166:169], v[212:215], v[108:111]
	v_mfma_f32_16x16x32_bf16 v[96:99], v[154:157], v[220:223], v[96:99]
	v_mfma_f32_16x16x32_bf16 v[92:95], v[166:169], v[220:223], v[92:95]
	v_mfma_f32_16x16x32_bf16 v[80:83], v[154:157], v[228:231], v[80:83]
	v_mfma_f32_16x16x32_bf16 v[76:79], v[166:169], v[228:231], v[76:79]
	v_mfma_f32_16x16x32_bf16 v[120:123], v[170:173], v[200:203], v[120:123]
	v_mfma_f32_16x16x32_bf16 v[116:119], v[190:193], v[200:203], v[116:119]
	v_mfma_f32_16x16x32_bf16 v[104:107], v[170:173], v[208:211], v[104:107]
	v_mfma_f32_16x16x32_bf16 v[100:103], v[190:193], v[208:211], v[100:103]
	v_mfma_f32_16x16x32_bf16 v[88:91], v[170:173], v[216:219], v[88:91]
	v_mfma_f32_16x16x32_bf16 v[84:87], v[190:193], v[216:219], v[84:87]
	v_mfma_f32_16x16x32_bf16 v[72:75], v[170:173], v[224:227], v[72:75]
	v_mfma_f32_16x16x32_bf16 v[68:71], v[190:193], v[224:227], v[68:71]
	v_mfma_f32_16x16x32_bf16 v[120:123], v[174:177], v[204:207], v[120:123]
	v_mfma_f32_16x16x32_bf16 v[116:119], v[196:199], v[204:207], v[116:119]
	v_mfma_f32_16x16x32_bf16 v[104:107], v[174:177], v[212:215], v[104:107]
	v_mfma_f32_16x16x32_bf16 v[100:103], v[196:199], v[212:215], v[100:103]
	v_mfma_f32_16x16x32_bf16 v[88:91], v[174:177], v[220:223], v[88:91]
	v_mfma_f32_16x16x32_bf16 v[84:87], v[196:199], v[220:223], v[84:87]
	v_mfma_f32_16x16x32_bf16 v[72:75], v[174:177], v[228:231], v[72:75]
	v_mfma_f32_16x16x32_bf16 v[68:71], v[196:199], v[228:231], v[68:71]
	s_barrier
; #define PG8_STAGE(bufoff, gbase, voff) do { _Pragma("unroll") for (int _i = 0; _i < 2; ++_i) \
;         __builtin_amdgcn_global_load_lds((const unsigned*)((const char*)(gbase) + (voff)[_i]), (LAS unsigned*)(lds + (bufoff) + ldsw + _i * 8192), 16, 0, 0); } while (0)
; #define PG8_LDA(dst, b, h) do { _Pragma("unroll") for (int m = 0; m < 4; ++m) _Pragma("unroll") for (int k = 0; k < 2; ++k) dst[m][k] = *(const LAS bf16x8*)(lds + PG8_SA(b, h) + aoff + m * 2048 + k * 1024); } while (0)
; #define PG8_MMA(ai, bj, At, Bt) do { __builtin_amdgcn_s_setprio(1); _Pragma("unroll") for (int m = 0; m < 4; ++m) _Pragma("unroll") for (int n = 0; n < 2; ++n) _Pragma("unroll") for (int k = 0; k < 2; ++k) \
;         acc[ai][bj][m][n] = __builtin_amdgcn_mfma_f32_16x16x32_bf16(Bt[n][k], At[m][k], acc[ai][bj][m][n], 0, 0, 0); __builtin_amdgcn_s_setprio(0); } while (0)
; #define PG8_WAIT_V(n) asm volatile("s_waitcnt vmcnt(" #n ")" ::: "memory")
; #define PG8_WAIT_L(n) asm volatile("s_waitcnt lgkmcnt(" #n ")" ::: "memory")
; #define PG8_BAR __builtin_amdgcn_s_barrier()
; #define PG8_SCHED __builtin_amdgcn_sched_barrier(0)
; template <class Epi, class Sched>
; __device__ __forceinline__ void gemm_phase(LAS unsigned char* lds, const Gemm g, const Sched& S, const Epi& E) {
;     ...
;             PG8_LDA(At, 1, 1); PG8_STAGE(PG8_SB(1, 0), b3, voffB); PG8_STAGE(PG8_SB(1, 1), b3 + hstepB, voffB); PG8_STAGE(PG8_SA(1, 0), a3, voffA);
;             PG8_WAIT_V(8); PG8_WAIT_L(0); PG8_BAR; PG8_MMA(1, 0, At, B0); PG8_MMA(1, 1, At, B1); PG8_BAR; PG8_SCHED;
;         }
;         if (wr == 0) PG8_BAR;
;         E(acc, cur, wr, wc, fr, fq, lds, tid, est);
;         if (!has_next) break;
	s_add_i32 s0, s0, s20
	v_lshl_add_u64 v[158:159], v[158:159], 0, s[30:31]
	s_mov_b32 m0, s0
	ds_read_b128 v[200:203], v152 offset:49152
	ds_read_b128 v[204:207], v152 offset:50176
	ds_read_b128 v[208:211], v152 offset:51200
	ds_read_b128 v[212:215], v152 offset:52224
	ds_read_b128 v[216:219], v152 offset:53248
	ds_read_b128 v[220:223], v152 offset:54272
	ds_read_b128 v[224:227], v152 offset:55296
	ds_read_b128 v[228:231], v152 offset:56320
	global_load_lds_dwordx4 v[158:159], off
	s_add_i32 m0, s0, 0x2000
	s_add_u32 s6, s6, 0x40080
	v_lshl_add_u64 v[158:159], v[232:233], 0, s[30:31]
	s_addc_u32 s7, s7, 0
	s_add_i32 s0, s26, s20
	global_load_lds_dwordx4 v[158:159], off
	v_lshl_add_u64 v[158:159], s[6:7], 0, v[160:161]
	s_mov_b32 m0, s0
	s_nop 0
	global_load_lds_dwordx4 v[158:159], off
	v_lshl_add_u64 v[158:159], s[6:7], 0, v[136:137]
	s_add_i32 m0, s0, 0x2000
	s_nop 0
	global_load_lds_dwordx4 v[158:159], off
	v_lshl_add_u64 v[158:159], v[234:235], 0, s[30:31]
	s_mov_b32 m0, s24
	s_nop 0
	global_load_lds_dwordx4 v[158:159], off
	v_lshl_add_u64 v[158:159], v[236:237], 0, s[30:31]
	s_mov_b32 m0, s25
	s_nop 0
	global_load_lds_dwordx4 v[158:159], off
	s_waitcnt vmcnt(8)
	s_waitcnt lgkmcnt(0)
	s_barrier
	v_mfma_f32_16x16x32_bf16 v[64:67], v[142:145], v[200:203], v[64:67]
	v_mfma_f32_16x16x32_bf16 v[60:63], v[162:165], v[200:203], v[60:63]
	v_mfma_f32_16x16x32_bf16 v[48:51], v[142:145], v[208:211], v[48:51]
	v_mfma_f32_16x16x32_bf16 v[44:47], v[162:165], v[208:211], v[44:47]
	v_mfma_f32_16x16x32_bf16 v[32:35], v[142:145], v[216:219], v[32:35]
	v_mfma_f32_16x16x32_bf16 v[28:31], v[162:165], v[216:219], v[28:31]
	v_mfma_f32_16x16x32_bf16 v[16:19], v[142:145], v[224:227], v[16:19]
	v_mfma_f32_16x16x32_bf16 v[12:15], v[162:165], v[224:227], v[12:15]
	v_mfma_f32_16x16x32_bf16 v[64:67], v[154:157], v[204:207], v[64:67]
	v_mfma_f32_16x16x32_bf16 v[60:63], v[166:169], v[204:207], v[60:63]
	v_mfma_f32_16x16x32_bf16 v[48:51], v[154:157], v[212:215], v[48:51]
	v_mfma_f32_16x16x32_bf16 v[44:47], v[166:169], v[212:215], v[44:47]
	v_mfma_f32_16x16x32_bf16 v[32:35], v[154:157], v[220:223], v[32:35]
	v_mfma_f32_16x16x32_bf16 v[28:31], v[166:169], v[220:223], v[28:31]
	v_mfma_f32_16x16x32_bf16 v[16:19], v[154:157], v[228:231], v[16:19]
	v_mfma_f32_16x16x32_bf16 v[12:15], v[166:169], v[228:231], v[12:15]
	v_mfma_f32_16x16x32_bf16 v[56:59], v[170:173], v[200:203], v[56:59]
	v_mfma_f32_16x16x32_bf16 v[52:55], v[190:193], v[200:203], v[52:55]
	v_mfma_f32_16x16x32_bf16 v[40:43], v[170:173], v[208:211], v[40:43]
	v_mfma_f32_16x16x32_bf16 v[36:39], v[190:193], v[208:211], v[36:39]
	v_mfma_f32_16x16x32_bf16 v[24:27], v[170:173], v[216:219], v[24:27]
	v_mfma_f32_16x16x32_bf16 v[20:23], v[190:193], v[216:219], v[20:23]
	v_mfma_f32_16x16x32_bf16 v[8:11], v[170:173], v[224:227], v[8:11]
	v_mfma_f32_16x16x32_bf16 v[4:7], v[190:193], v[224:227], v[4:7]
	v_mfma_f32_16x16x32_bf16 v[56:59], v[174:177], v[204:207], v[56:59]
	v_mfma_f32_16x16x32_bf16 v[52:55], v[196:199], v[204:207], v[52:55]
	v_mfma_f32_16x16x32_bf16 v[40:43], v[174:177], v[212:215], v[40:43]
	v_mfma_f32_16x16x32_bf16 v[36:39], v[196:199], v[212:215], v[36:39]
	v_mfma_f32_16x16x32_bf16 v[24:27], v[174:177], v[220:223], v[24:27]
	v_mfma_f32_16x16x32_bf16 v[20:23], v[196:199], v[220:223], v[20:23]
	v_mfma_f32_16x16x32_bf16 v[8:11], v[174:177], v[228:231], v[8:11]
	v_mfma_f32_16x16x32_bf16 v[4:7], v[196:199], v[228:231], v[4:7]
	s_barrier
	s_add_i32 s55, s55, 2
	s_add_u32 s44, s44, 0x100
	s_addc_u32 s45, s45, 0
	s_add_u32 s46, s46, 0x100
	s_addc_u32 s47, s47, 0
	s_cmp_gt_u32 s55, 13
	s_cbranch_scc0 .LBB0_718
	s_setprio 0
	s_and_b64 vcc, exec, s[16:17]
	s_cbranch_vccz .LBB0_721
	s_barrier

; #define PG8_STAGE(bufoff, gbase, voff) do { _Pragma("unroll") for (int _i = 0; _i < 2; ++_i) \
;         __builtin_amdgcn_global_load_lds((const unsigned*)((const char*)(gbase) + (voff)[_i]), (LAS unsigned*)(lds + (bufoff) + ldsw + _i * 8192), 16, 0, 0); } while (0)
; #define PG8_LDA(dst, b, h) do { _Pragma("unroll") for (int m = 0; m < 4; ++m) _Pragma("unroll") for (int k = 0; k < 2; ++k) dst[m][k] = *(const LAS bf16x8*)(lds + PG8_SA(b, h) + aoff + m * 2048 + k * 1024); } while (0)
; #define PG8_LDB(dst, b, h) do { _Pragma("unroll") for (int n = 0; n < 2; ++n) _Pragma("unroll") for (int k = 0; k < 2; ++k) dst[n][k] = *(const LAS bf16x8*)(lds + PG8_SB(b, h) + boff + n * 2048 + k * 1024); } while (0)
; #define PG8_MMA(ai, bj, At, Bt) do { __builtin_amdgcn_s_setprio(1); _Pragma("unroll") for (int m = 0; m < 4; ++m) _Pragma("unroll") for (int n = 0; n < 2; ++n) _Pragma("unroll") for (int k = 0; k < 2; ++k) \
;         acc[ai][bj][m][n] = __builtin_amdgcn_mfma_f32_16x16x32_bf16(Bt[n][k], At[m][k], acc[ai][bj][m][n], 0, 0, 0); __builtin_amdgcn_s_setprio(0); } while (0)
; #define PG8_BAR __builtin_amdgcn_s_barrier()
; template <class Epi, class Sched>
; __device__ __forceinline__ void gemm_phase(LAS unsigned char* lds, const Gemm g, const Sched& S, const Epi& E) {
;     ...
;         const bool has_next = S.next(ui + 1, nxt);
;         const char* nA = has_next ? (const char*)g.A + (size_t)nxt.pm * tstepA + (size_t)nxt.pn * apn : cA; const char* nB = has_next ? (const char*)g.Bt + (size_t)nxt.pn * tstepB : cB;
;         for (int t = 0; t < nt; t += 2) {
;             const bool last = (t == nt - 2);
;             const char* a1 = cA + (size_t)(t + 1) * kstep;
;             const char* a2 = last ? nA : cA + (size_t)(t + 2) * kstep; const char* b2 = last ? nB : cB + (size_t)(t + 2) * kstep;
;             const char* a3 = a2 + kstep; const char* b3 = b2 + kstep;
;             PG8_LDB(B0, 0, 0); PG8_LDB(B1, 0, 1); PG8_SCHED; PG8_LDA(At, 0, 0); PG8_STAGE(PG8_SA(1, 1), a1 + hstepA, voffA);
;             PG8_WAIT_V(8); PG8_WAIT_L(0); PG8_BAR; PG8_MMA(0, 0, At, B0); PG8_MMA(0, 1, At, B1); PG8_BAR; PG8_SCHED;
;             PG8_LDA(At, 0, 1); PG8_STAGE(PG8_SB(0, 0), b2, voffB); PG8_STAGE(PG8_SB(0, 1), b2 + hstepB, voffB); PG8_STAGE(PG8_SA(0, 0), a2, voffA);
;             PG8_WAIT_V(8); PG8_WAIT_L(0); PG8_BAR; PG8_MMA(1, 0, At, B0); PG8_MMA(1, 1, At, B1); PG8_BAR; PG8_SCHED;
.Lprio_807:
	s_add_u32 s46, s44, 0x100
	s_addc_u32 s47, s45, 0
	s_add_i32 s0, 0, 0x10000
	s_cmp_eq_u32 s54, 40
	s_cselect_b32 s15, s23, s47
	s_cselect_b32 s14, s22, s46
	s_cselect_b32 s7, s35, s53
	s_cselect_b32 s6, s34, s33
	s_add_i32 s26, 0, 0x14000
	v_add_u32_e32 v140, s0, v186
	v_add_u32_e32 v168, s26, v186
	ds_read_b128 v[128:131], v140
	ds_read_b128 v[132:135], v140 offset:1024
	ds_read_b128 v[136:139], v140 offset:2048
	ds_read_b128 v[140:143], v140 offset:3072
	ds_read_b128 v[144:147], v168
	ds_read_b128 v[148:151], v168 offset:1024
	ds_read_b128 v[152:155], v168 offset:2048
	ds_read_b128 v[168:171], v168 offset:3072
	v_lshl_add_u64 v[226:227], s[44:45], 0, v[164:165]
	s_add_i32 m0, s49, 0xc000
	ds_read_b128 v[172:175], v196
	ds_read_b128 v[198:201], v196 offset:1024
	ds_read_b128 v[202:205], v196 offset:2048
	ds_read_b128 v[206:209], v196 offset:3072
	ds_read_b128 v[210:213], v196 offset:4096
	ds_read_b128 v[214:217], v196 offset:5120
	ds_read_b128 v[218:221], v196 offset:6144
	ds_read_b128 v[222:225], v196 offset:7168
	global_load_lds_dwordx4 v[226:227], off
	v_lshl_add_u64 v[226:227], s[44:45], 0, v[166:167]
	s_add_i32 m0, s49, 0xe000
	s_nop 0
	global_load_lds_dwordx4 v[226:227], off
	s_waitcnt vmcnt(8)
	s_waitcnt lgkmcnt(0)
	s_barrier
	v_mfma_f32_16x16x32_bf16 v[124:127], v[128:131], v[172:175], 0
	v_mfma_f32_16x16x32_bf16 v[120:123], v[136:139], v[172:175], 0
	v_mfma_f32_16x16x32_bf16 v[108:111], v[128:131], v[202:205], 0
	v_mfma_f32_16x16x32_bf16 v[104:107], v[136:139], v[202:205], 0
	v_mfma_f32_16x16x32_bf16 v[92:95], v[128:131], v[210:213], 0
	v_mfma_f32_16x16x32_bf16 v[88:91], v[136:139], v[210:213], 0
	v_mfma_f32_16x16x32_bf16 v[76:79], v[128:131], v[218:221], 0
	v_mfma_f32_16x16x32_bf16 v[72:75], v[136:139], v[218:221], 0
	v_mfma_f32_16x16x32_bf16 v[124:127], v[132:135], v[198:201], v[124:127]
	v_mfma_f32_16x16x32_bf16 v[120:123], v[140:143], v[198:201], v[120:123]
	v_mfma_f32_16x16x32_bf16 v[108:111], v[132:135], v[206:209], v[108:111]
	v_mfma_f32_16x16x32_bf16 v[104:107], v[140:143], v[206:209], v[104:107]
	v_mfma_f32_16x16x32_bf16 v[92:95], v[132:135], v[214:217], v[92:95]
	v_mfma_f32_16x16x32_bf16 v[88:91], v[140:143], v[214:217], v[88:91]
	v_mfma_f32_16x16x32_bf16 v[76:79], v[132:135], v[222:225], v[76:79]
	v_mfma_f32_16x16x32_bf16 v[72:75], v[140:143], v[222:225], v[72:75]
	v_mfma_f32_16x16x32_bf16 v[116:119], v[144:147], v[172:175], 0
	v_mfma_f32_16x16x32_bf16 v[112:115], v[152:155], v[172:175], 0
	v_mfma_f32_16x16x32_bf16 v[100:103], v[144:147], v[202:205], 0
	v_mfma_f32_16x16x32_bf16 v[96:99], v[152:155], v[202:205], 0
	v_mfma_f32_16x16x32_bf16 v[84:87], v[144:147], v[210:213], 0
	v_mfma_f32_16x16x32_bf16 v[80:83], v[152:155], v[210:213], 0
	v_mfma_f32_16x16x32_bf16 v[68:71], v[144:147], v[218:221], 0
	v_mfma_f32_16x16x32_bf16 v[64:67], v[152:155], v[218:221], 0
	v_mfma_f32_16x16x32_bf16 v[116:119], v[148:151], v[198:201], v[116:119]
	v_mfma_f32_16x16x32_bf16 v[112:115], v[168:171], v[198:201], v[112:115]
	v_mfma_f32_16x16x32_bf16 v[100:103], v[148:151], v[206:209], v[100:103]
	v_mfma_f32_16x16x32_bf16 v[96:99], v[168:171], v[206:209], v[96:99]
	v_mfma_f32_16x16x32_bf16 v[84:87], v[148:151], v[214:217], v[84:87]
	v_mfma_f32_16x16x32_bf16 v[80:83], v[168:171], v[214:217], v[80:83]
	v_mfma_f32_16x16x32_bf16 v[68:71], v[148:151], v[222:225], v[68:71]
	v_mfma_f32_16x16x32_bf16 v[64:67], v[168:171], v[222:225], v[64:67]
	s_barrier
	s_add_i32 s0, s0, s20
	v_lshl_add_u64 v[226:227], s[6:7], 0, v[160:161]
	s_mov_b32 m0, s0
	ds_read_b128 v[172:175], v196 offset:16384
	ds_read_b128 v[198:201], v196 offset:17408
	ds_read_b128 v[202:205], v196 offset:18432
	ds_read_b128 v[206:209], v196 offset:19456
	ds_read_b128 v[210:213], v196 offset:20480
	ds_read_b128 v[214:217], v196 offset:21504
	ds_read_b128 v[218:221], v196 offset:22528
	ds_read_b128 v[222:225], v196 offset:23552
	global_load_lds_dwordx4 v[226:227], off
	s_add_i32 m0, s0, 0x2000
	s_add_u32 s44, s6, 0xb0000
	v_lshl_add_u64 v[228:229], s[6:7], 0, v[162:163]
	s_addc_u32 s45, s7, 0
	s_add_i32 s0, s26, s20
	global_load_lds_dwordx4 v[228:229], off
	v_lshl_add_u64 v[230:231], s[44:45], 0, v[160:161]
	s_mov_b32 m0, s0
	v_lshl_add_u64 v[232:233], s[14:15], 0, v[158:159]
	global_load_lds_dwordx4 v[230:231], off
	v_lshl_add_u64 v[230:231], s[44:45], 0, v[162:163]
	s_add_i32 m0, s0, 0x2000
	s_nop 0
	global_load_lds_dwordx4 v[230:231], off
	v_lshl_add_u64 v[230:231], s[14:15], 0, v[156:157]
	s_mov_b32 m0, s49
	s_nop 0
	global_load_lds_dwordx4 v[230:231], off
	s_mov_b32 m0, s50
	s_nop 0
	global_load_lds_dwordx4 v[232:233], off
	s_waitcnt vmcnt(8)
	s_waitcnt lgkmcnt(0)
	s_barrier
; #define PG8_STAGE(bufoff, gbase, voff) do { _Pragma("unroll") for (int _i = 0; _i < 2; ++_i) \
;         __builtin_amdgcn_global_load_lds((const unsigned*)((const char*)(gbase) + (voff)[_i]), (LAS unsigned*)(lds + (bufoff) + ldsw + _i * 8192), 16, 0, 0); } while (0)
; #define PG8_LDA(dst, b, h) do { _Pragma("unroll") for (int m = 0; m < 4; ++m) _Pragma("unroll") for (int k = 0; k < 2; ++k) dst[m][k] = *(const LAS bf16x8*)(lds + PG8_SA(b, h) + aoff + m * 2048 + k * 1024); } while (0)
; #define PG8_LDB(dst, b, h) do { _Pragma("unroll") for (int n = 0; n < 2; ++n) _Pragma("unroll") for (int k = 0; k < 2; ++k) dst[n][k] = *(const LAS bf16x8*)(lds + PG8_SB(b, h) + boff + n * 2048 + k * 1024); } while (0)
; #define PG8_MMA(ai, bj, At, Bt) do { __builtin_amdgcn_s_setprio(1); _Pragma("unroll") for (int m = 0; m < 4; ++m) _Pragma("unroll") for (int n = 0; n < 2; ++n) _Pragma("unroll") for (int k = 0; k < 2; ++k) \
;         acc[ai][bj][m][n] = __builtin_amdgcn_mfma_f32_16x16x32_bf16(Bt[n][k], At[m][k], acc[ai][bj][m][n], 0, 0, 0); __builtin_amdgcn_s_setprio(0); } while (0)
; #define PG8_WAIT_V(n) asm volatile("s_waitcnt vmcnt(" #n ")" ::: "memory")
; #define PG8_WAIT_L(n) asm volatile("s_waitcnt lgkmcnt(" #n ")" ::: "memory")
; #define PG8_BAR __builtin_amdgcn_s_barrier()
; #define PG8_SCHED __builtin_amdgcn_sched_barrier(0)
; template <class Epi, class Sched>
; __device__ __forceinline__ void gemm_phase(LAS unsigned char* lds, const Gemm g, const Sched& S, const Epi& E) {
;     ...
;             PG8_WAIT_V(8); PG8_WAIT_L(0); PG8_BAR; PG8_MMA(0, 0, At, B0); PG8_MMA(0, 1, At, B1); PG8_BAR; PG8_SCHED;
;             PG8_LDA(At, 0, 1); PG8_STAGE(PG8_SB(0, 0), b2, voffB); PG8_STAGE(PG8_SB(0, 1), b2 + hstepB, voffB); PG8_STAGE(PG8_SA(0, 0), a2, voffA);
;             PG8_WAIT_V(8); PG8_WAIT_L(0); PG8_BAR; PG8_MMA(1, 0, At, B0); PG8_MMA(1, 1, At, B1); PG8_BAR; PG8_SCHED;
;             PG8_LDB(B0, 1, 0); PG8_LDB(B1, 1, 1); PG8_SCHED; PG8_LDA(At, 1, 0); PG8_STAGE(PG8_SA(0, 1), a2 + hstepA, voffA);
;             PG8_WAIT_V(8); PG8_WAIT_L(0); PG8_BAR; PG8_MMA(0, 0, At, B0); PG8_MMA(0, 1, At, B1); PG8_BAR; PG8_SCHED;
	v_mfma_f32_16x16x32_bf16 v[60:63], v[128:131], v[172:175], 0
	v_mfma_f32_16x16x32_bf16 v[56:59], v[136:139], v[172:175], 0
	v_mfma_f32_16x16x32_bf16 v[44:47], v[128:131], v[202:205], 0
	v_mfma_f32_16x16x32_bf16 v[40:43], v[136:139], v[202:205], 0
	v_mfma_f32_16x16x32_bf16 v[28:31], v[128:131], v[210:213], 0
	v_mfma_f32_16x16x32_bf16 v[24:27], v[136:139], v[210:213], 0
	v_mfma_f32_16x16x32_bf16 v[12:15], v[128:131], v[218:221], 0
	v_mfma_f32_16x16x32_bf16 v[8:11], v[136:139], v[218:221], 0
	v_mfma_f32_16x16x32_bf16 v[60:63], v[132:135], v[198:201], v[60:63]
	v_mfma_f32_16x16x32_bf16 v[56:59], v[140:143], v[198:201], v[56:59]
	v_mfma_f32_16x16x32_bf16 v[44:47], v[132:135], v[206:209], v[44:47]
	v_mfma_f32_16x16x32_bf16 v[40:43], v[140:143], v[206:209], v[40:43]
	v_mfma_f32_16x16x32_bf16 v[28:31], v[132:135], v[214:217], v[28:31]
	v_mfma_f32_16x16x32_bf16 v[24:27], v[140:143], v[214:217], v[24:27]
	v_mfma_f32_16x16x32_bf16 v[12:15], v[132:135], v[222:225], v[12:15]
	v_mfma_f32_16x16x32_bf16 v[8:11], v[140:143], v[222:225], v[8:11]
	v_mfma_f32_16x16x32_bf16 v[52:55], v[144:147], v[172:175], 0
	v_mfma_f32_16x16x32_bf16 v[48:51], v[152:155], v[172:175], 0
	v_mfma_f32_16x16x32_bf16 v[36:39], v[144:147], v[202:205], 0
	v_mfma_f32_16x16x32_bf16 v[32:35], v[152:155], v[202:205], 0
	v_mfma_f32_16x16x32_bf16 v[20:23], v[144:147], v[210:213], 0
	v_mfma_f32_16x16x32_bf16 v[16:19], v[152:155], v[210:213], 0
	v_mfma_f32_16x16x32_bf16 v[4:7], v[144:147], v[218:221], 0
	v_mfma_f32_16x16x32_bf16 v[0:3], v[152:155], v[218:221], 0
	v_mfma_f32_16x16x32_bf16 v[52:55], v[148:151], v[198:201], v[52:55]
	v_mfma_f32_16x16x32_bf16 v[48:51], v[168:171], v[198:201], v[48:51]
	v_mfma_f32_16x16x32_bf16 v[36:39], v[148:151], v[206:209], v[36:39]
	v_mfma_f32_16x16x32_bf16 v[32:35], v[168:171], v[206:209], v[32:35]
	v_mfma_f32_16x16x32_bf16 v[20:23], v[148:151], v[214:217], v[20:23]
	v_mfma_f32_16x16x32_bf16 v[16:19], v[168:171], v[214:217], v[16:19]
	v_mfma_f32_16x16x32_bf16 v[4:7], v[148:151], v[222:225], v[4:7]
	v_mfma_f32_16x16x32_bf16 v[0:3], v[168:171], v[222:225], v[0:3]
	s_barrier
	s_add_i32 s0, 0, 0x18000
	s_add_i32 s26, 0, 0x1c000
	v_add_u32_e32 v140, s0, v186
	v_add_u32_e32 v168, s26, v186
	ds_read_b128 v[128:131], v140
	ds_read_b128 v[132:135], v140 offset:1024
	ds_read_b128 v[136:139], v140 offset:2048
	ds_read_b128 v[140:143], v140 offset:3072
	ds_read_b128 v[144:147], v168
	ds_read_b128 v[148:151], v168 offset:1024
	ds_read_b128 v[152:155], v168 offset:2048
	ds_read_b128 v[168:171], v168 offset:3072
	s_add_u32 s14, s14, 0xb0000
	s_addc_u32 s15, s15, 0
	s_mov_b32 m0, s51
	v_lshl_add_u64 v[234:235], s[14:15], 0, v[156:157]
	ds_read_b128 v[172:175], v196 offset:32768
	ds_read_b128 v[198:201], v196 offset:33792
	ds_read_b128 v[202:205], v196 offset:34816
	ds_read_b128 v[206:209], v196 offset:35840
	ds_read_b128 v[210:213], v196 offset:36864
	ds_read_b128 v[214:217], v196 offset:37888
	ds_read_b128 v[218:221], v196 offset:38912
	ds_read_b128 v[222:225], v196 offset:39936
	global_load_lds_dwordx4 v[234:235], off
	v_lshl_add_u64 v[234:235], s[14:15], 0, v[158:159]
	s_mov_b32 m0, s52
	s_nop 0
	global_load_lds_dwordx4 v[234:235], off
	s_waitcnt vmcnt(8)
	s_waitcnt lgkmcnt(0)
	s_barrier
	v_mfma_f32_16x16x32_bf16 v[124:127], v[128:131], v[172:175], v[124:127]
	v_mfma_f32_16x16x32_bf16 v[120:123], v[136:139], v[172:175], v[120:123]
	v_mfma_f32_16x16x32_bf16 v[108:111], v[128:131], v[202:205], v[108:111]
	v_mfma_f32_16x16x32_bf16 v[104:107], v[136:139], v[202:205], v[104:107]
	v_mfma_f32_16x16x32_bf16 v[92:95], v[128:131], v[210:213], v[92:95]
	v_mfma_f32_16x16x32_bf16 v[88:91], v[136:139], v[210:213], v[88:91]
	v_mfma_f32_16x16x32_bf16 v[76:79], v[128:131], v[218:221], v[76:79]
	v_mfma_f32_16x16x32_bf16 v[72:75], v[136:139], v[218:221], v[72:75]
	v_mfma_f32_16x16x32_bf16 v[124:127], v[132:135], v[198:201], v[124:127]
	v_mfma_f32_16x16x32_bf16 v[120:123], v[140:143], v[198:201], v[120:123]
	v_mfma_f32_16x16x32_bf16 v[108:111], v[132:135], v[206:209], v[108:111]
	v_mfma_f32_16x16x32_bf16 v[104:107], v[140:143], v[206:209], v[104:107]
	v_mfma_f32_16x16x32_bf16 v[92:95], v[132:135], v[214:217], v[92:95]
	v_mfma_f32_16x16x32_bf16 v[88:91], v[140:143], v[214:217], v[88:91]
	v_mfma_f32_16x16x32_bf16 v[76:79], v[132:135], v[222:225], v[76:79]
	v_mfma_f32_16x16x32_bf16 v[72:75], v[140:143], v[222:225], v[72:75]
	v_mfma_f32_16x16x32_bf16 v[116:119], v[144:147], v[172:175], v[116:119]
	v_mfma_f32_16x16x32_bf16 v[112:115], v[152:155], v[172:175], v[112:115]
	v_mfma_f32_16x16x32_bf16 v[100:103], v[144:147], v[202:205], v[100:103]
	v_mfma_f32_16x16x32_bf16 v[96:99], v[152:155], v[202:205], v[96:99]
	v_mfma_f32_16x16x32_bf16 v[84:87], v[144:147], v[210:213], v[84:87]
	v_mfma_f32_16x16x32_bf16 v[80:83], v[152:155], v[210:213], v[80:83]
	v_mfma_f32_16x16x32_bf16 v[68:71], v[144:147], v[218:221], v[68:71]
	v_mfma_f32_16x16x32_bf16 v[64:67], v[152:155], v[218:221], v[64:67]
	v_mfma_f32_16x16x32_bf16 v[116:119], v[148:151], v[198:201], v[116:119]
	v_mfma_f32_16x16x32_bf16 v[112:115], v[168:171], v[198:201], v[112:115]
	v_mfma_f32_16x16x32_bf16 v[100:103], v[148:151], v[206:209], v[100:103]
	v_mfma_f32_16x16x32_bf16 v[96:99], v[168:171], v[206:209], v[96:99]
	v_mfma_f32_16x16x32_bf16 v[84:87], v[148:151], v[214:217], v[84:87]
	v_mfma_f32_16x16x32_bf16 v[80:83], v[168:171], v[214:217], v[80:83]
	v_mfma_f32_16x16x32_bf16 v[68:71], v[148:151], v[222:225], v[68:71]
	v_mfma_f32_16x16x32_bf16 v[64:67], v[168:171], v[222:225], v[64:67]
	s_barrier
; #define PG8_STAGE(bufoff, gbase, voff) do { _Pragma("unroll") for (int _i = 0; _i < 2; ++_i) \
;         __builtin_amdgcn_global_load_lds((const unsigned*)((const char*)(gbase) + (voff)[_i]), (LAS unsigned*)(lds + (bufoff) + ldsw + _i * 8192), 16, 0, 0); } while (0)
; #define PG8_LDA(dst, b, h) do { _Pragma("unroll") for (int m = 0; m < 4; ++m) _Pragma("unroll") for (int k = 0; k < 2; ++k) dst[m][k] = *(const LAS bf16x8*)(lds + PG8_SA(b, h) + aoff + m * 2048 + k * 1024); } while (0)
; #define PG8_LDB(dst, b, h) do { _Pragma("unroll") for (int n = 0; n < 2; ++n) _Pragma("unroll") for (int k = 0; k < 2; ++k) dst[n][k] = *(const LAS bf16x8*)(lds + PG8_SB(b, h) + boff + n * 2048 + k * 1024); } while (0)
; #define PG8_MMA(ai, bj, At, Bt) do { __builtin_amdgcn_s_setprio(1); _Pragma("unroll") for (int m = 0; m < 4; ++m) _Pragma("unroll") for (int n = 0; n < 2; ++n) _Pragma("unroll") for (int k = 0; k < 2; ++k) \
;         acc[ai][bj][m][n] = __builtin_amdgcn_mfma_f32_16x16x32_bf16(Bt[n][k], At[m][k], acc[ai][bj][m][n], 0, 0, 0); __builtin_amdgcn_s_setprio(0); } while (0)
; #define PG8_WAIT_V(n) asm volatile("s_waitcnt vmcnt(" #n ")" ::: "memory")
; #define PG8_WAIT_L(n) asm volatile("s_waitcnt lgkmcnt(" #n ")" ::: "memory")
; #define PG8_BAR __builtin_amdgcn_s_barrier()
; #define PG8_SCHED __builtin_amdgcn_sched_barrier(0)
; template <class Epi, class Sched>
; __device__ __forceinline__ void gemm_phase(LAS unsigned char* lds, const Gemm g, const Sched& S, const Epi& E) {
;     ...
;         for (int t = 0; t < nt; t += 2) {
;             const bool last = (t == nt - 2);
;             const char* a1 = cA + (size_t)(t + 1) * kstep;
;             const char* a2 = last ? nA : cA + (size_t)(t + 2) * kstep; const char* b2 = last ? nB : cB + (size_t)(t + 2) * kstep;
;             const char* a3 = a2 + kstep; const char* b3 = b2 + kstep;
;             PG8_LDB(B0, 0, 0); PG8_LDB(B1, 0, 1); PG8_SCHED; PG8_LDA(At, 0, 0); PG8_STAGE(PG8_SA(1, 1), a1 + hstepA, voffA);
;             PG8_WAIT_V(8); PG8_WAIT_L(0); PG8_BAR; PG8_MMA(0, 0, At, B0); PG8_MMA(0, 1, At, B1); PG8_BAR; PG8_SCHED;
;     ...
;             PG8_LDA(At, 1, 1); PG8_STAGE(PG8_SB(1, 0), b3, voffB); PG8_STAGE(PG8_SB(1, 1), b3 + hstepB, voffB); PG8_STAGE(PG8_SA(1, 0), a3, voffA);
;             PG8_WAIT_V(8); PG8_WAIT_L(0); PG8_BAR; PG8_MMA(1, 0, At, B0); PG8_MMA(1, 1, At, B1); PG8_BAR; PG8_SCHED;
	s_add_i32 s0, s0, s20
	v_lshl_add_u64 v[226:227], v[226:227], 0, s[30:31]
	s_mov_b32 m0, s0
	ds_read_b128 v[172:175], v196 offset:49152
	ds_read_b128 v[198:201], v196 offset:50176
	ds_read_b128 v[202:205], v196 offset:51200
	ds_read_b128 v[206:209], v196 offset:52224
	ds_read_b128 v[210:213], v196 offset:53248
	ds_read_b128 v[214:217], v196 offset:54272
	ds_read_b128 v[218:221], v196 offset:55296
	ds_read_b128 v[222:225], v196 offset:56320
	global_load_lds_dwordx4 v[226:227], off
	s_add_i32 m0, s0, 0x2000
	s_add_u32 s6, s6, 0xb0080
	v_lshl_add_u64 v[226:227], v[228:229], 0, s[30:31]
	s_addc_u32 s7, s7, 0
	s_add_i32 s0, s26, s20
	global_load_lds_dwordx4 v[226:227], off
	v_lshl_add_u64 v[226:227], s[6:7], 0, v[160:161]
	s_mov_b32 m0, s0
	s_nop 0
	global_load_lds_dwordx4 v[226:227], off
	v_lshl_add_u64 v[226:227], s[6:7], 0, v[162:163]
	s_add_i32 m0, s0, 0x2000
	s_nop 0
	global_load_lds_dwordx4 v[226:227], off
	v_lshl_add_u64 v[226:227], v[230:231], 0, s[30:31]
	s_mov_b32 m0, s24
	s_nop 0
	global_load_lds_dwordx4 v[226:227], off
	v_lshl_add_u64 v[226:227], v[232:233], 0, s[30:31]
	s_mov_b32 m0, s25
	s_nop 0
	global_load_lds_dwordx4 v[226:227], off
	s_waitcnt vmcnt(8)
	s_waitcnt lgkmcnt(0)
	s_barrier
	v_mfma_f32_16x16x32_bf16 v[60:63], v[128:131], v[172:175], v[60:63]
	v_mfma_f32_16x16x32_bf16 v[56:59], v[136:139], v[172:175], v[56:59]
	v_mfma_f32_16x16x32_bf16 v[44:47], v[128:131], v[202:205], v[44:47]
	v_mfma_f32_16x16x32_bf16 v[40:43], v[136:139], v[202:205], v[40:43]
	v_mfma_f32_16x16x32_bf16 v[28:31], v[128:131], v[210:213], v[28:31]
	v_mfma_f32_16x16x32_bf16 v[24:27], v[136:139], v[210:213], v[24:27]
	v_mfma_f32_16x16x32_bf16 v[12:15], v[128:131], v[218:221], v[12:15]
	v_mfma_f32_16x16x32_bf16 v[8:11], v[136:139], v[218:221], v[8:11]
	v_mfma_f32_16x16x32_bf16 v[60:63], v[132:135], v[198:201], v[60:63]
	v_mfma_f32_16x16x32_bf16 v[56:59], v[140:143], v[198:201], v[56:59]
	v_mfma_f32_16x16x32_bf16 v[44:47], v[132:135], v[206:209], v[44:47]
	v_mfma_f32_16x16x32_bf16 v[40:43], v[140:143], v[206:209], v[40:43]
	v_mfma_f32_16x16x32_bf16 v[28:31], v[132:135], v[214:217], v[28:31]
	v_mfma_f32_16x16x32_bf16 v[24:27], v[140:143], v[214:217], v[24:27]
	v_mfma_f32_16x16x32_bf16 v[12:15], v[132:135], v[222:225], v[12:15]
	v_mfma_f32_16x16x32_bf16 v[8:11], v[140:143], v[222:225], v[8:11]
	v_mfma_f32_16x16x32_bf16 v[52:55], v[144:147], v[172:175], v[52:55]
	v_mfma_f32_16x16x32_bf16 v[48:51], v[152:155], v[172:175], v[48:51]
	v_mfma_f32_16x16x32_bf16 v[36:39], v[144:147], v[202:205], v[36:39]
	v_mfma_f32_16x16x32_bf16 v[32:35], v[152:155], v[202:205], v[32:35]
	v_mfma_f32_16x16x32_bf16 v[20:23], v[144:147], v[210:213], v[20:23]
	v_mfma_f32_16x16x32_bf16 v[16:19], v[152:155], v[210:213], v[16:19]
	v_mfma_f32_16x16x32_bf16 v[4:7], v[144:147], v[218:221], v[4:7]
	v_mfma_f32_16x16x32_bf16 v[0:3], v[152:155], v[218:221], v[0:3]
	v_mfma_f32_16x16x32_bf16 v[52:55], v[148:151], v[198:201], v[52:55]
	v_mfma_f32_16x16x32_bf16 v[48:51], v[168:171], v[198:201], v[48:51]
	v_mfma_f32_16x16x32_bf16 v[36:39], v[148:151], v[206:209], v[36:39]
	v_mfma_f32_16x16x32_bf16 v[32:35], v[168:171], v[206:209], v[32:35]
	v_mfma_f32_16x16x32_bf16 v[20:23], v[148:151], v[214:217], v[20:23]
	v_mfma_f32_16x16x32_bf16 v[16:19], v[168:171], v[214:217], v[16:19]
	v_mfma_f32_16x16x32_bf16 v[4:7], v[148:151], v[222:225], v[4:7]
	v_mfma_f32_16x16x32_bf16 v[0:3], v[168:171], v[222:225], v[0:3]
	s_barrier
	s_add_i32 s54, s54, 2
	s_add_u32 s33, s33, 0x100
	s_addc_u32 s53, s53, 0
	s_cmp_gt_u32 s54, 41
	s_mov_b64 s[44:45], s[46:47]
.LBB0_807:
	s_add_u32 s46, s44, 0x100
	s_addc_u32 s47, s45, 0
	s_add_i32 s0, 0, 0x10000
	s_cmp_eq_u32 s54, 40
	s_cselect_b32 s15, s23, s47
	s_cselect_b32 s14, s22, s46
	s_cselect_b32 s7, s35, s53
	s_cselect_b32 s6, s34, s33
	s_add_i32 s26, 0, 0x14000
	v_add_u32_e32 v140, s0, v186
	v_add_u32_e32 v168, s26, v186
	ds_read_b128 v[128:131], v140
	ds_read_b128 v[132:135], v140 offset:1024
	ds_read_b128 v[136:139], v140 offset:2048
	ds_read_b128 v[140:143], v140 offset:3072
	ds_read_b128 v[144:147], v168
	ds_read_b128 v[148:151], v168 offset:1024
	ds_read_b128 v[152:155], v168 offset:2048
	ds_read_b128 v[168:171], v168 offset:3072
	v_lshl_add_u64 v[226:227], s[44:45], 0, v[164:165]
	s_add_i32 m0, s49, 0xc000
	ds_read_b128 v[172:175], v196
	ds_read_b128 v[198:201], v196 offset:1024
	ds_read_b128 v[202:205], v196 offset:2048
	ds_read_b128 v[206:209], v196 offset:3072
	ds_read_b128 v[210:213], v196 offset:4096
	ds_read_b128 v[214:217], v196 offset:5120
	ds_read_b128 v[218:221], v196 offset:6144
	ds_read_b128 v[222:225], v196 offset:7168
	global_load_lds_dwordx4 v[226:227], off
	v_lshl_add_u64 v[226:227], s[44:45], 0, v[166:167]
	s_add_i32 m0, s49, 0xe000
	s_nop 0
	global_load_lds_dwordx4 v[226:227], off
	s_waitcnt vmcnt(8)
	s_waitcnt lgkmcnt(0)
	s_barrier
; #define PG8_STAGE(bufoff, gbase, voff) do { _Pragma("unroll") for (int _i = 0; _i < 2; ++_i) \
;         __builtin_amdgcn_global_load_lds((const unsigned*)((const char*)(gbase) + (voff)[_i]), (LAS unsigned*)(lds + (bufoff) + ldsw + _i * 8192), 16, 0, 0); } while (0)
; #define PG8_LDA(dst, b, h) do { _Pragma("unroll") for (int m = 0; m < 4; ++m) _Pragma("unroll") for (int k = 0; k < 2; ++k) dst[m][k] = *(const LAS bf16x8*)(lds + PG8_SA(b, h) + aoff + m * 2048 + k * 1024); } while (0)
; #define PG8_MMA(ai, bj, At, Bt) do { __builtin_amdgcn_s_setprio(1); _Pragma("unroll") for (int m = 0; m < 4; ++m) _Pragma("unroll") for (int n = 0; n < 2; ++n) _Pragma("unroll") for (int k = 0; k < 2; ++k) \
;         acc[ai][bj][m][n] = __builtin_amdgcn_mfma_f32_16x16x32_bf16(Bt[n][k], At[m][k], acc[ai][bj][m][n], 0, 0, 0); __builtin_amdgcn_s_setprio(0); } while (0)
; #define PG8_WAIT_V(n) asm volatile("s_waitcnt vmcnt(" #n ")" ::: "memory")
; #define PG8_WAIT_L(n) asm volatile("s_waitcnt lgkmcnt(" #n ")" ::: "memory")
; #define PG8_BAR __builtin_amdgcn_s_barrier()
; #define PG8_SCHED __builtin_amdgcn_sched_barrier(0)
; template <class Epi, class Sched>
; __device__ __forceinline__ void gemm_phase(LAS unsigned char* lds, const Gemm g, const Sched& S, const Epi& E) {
;     ...
;             PG8_WAIT_V(8); PG8_WAIT_L(0); PG8_BAR; PG8_MMA(0, 0, At, B0); PG8_MMA(0, 1, At, B1); PG8_BAR; PG8_SCHED;
;             PG8_LDA(At, 0, 1); PG8_STAGE(PG8_SB(0, 0), b2, voffB); PG8_STAGE(PG8_SB(0, 1), b2 + hstepB, voffB); PG8_STAGE(PG8_SA(0, 0), a2, voffA);
;             PG8_WAIT_V(8); PG8_WAIT_L(0); PG8_BAR; PG8_MMA(1, 0, At, B0); PG8_MMA(1, 1, At, B1); PG8_BAR; PG8_SCHED;
	v_mfma_f32_16x16x32_bf16 v[124:127], v[128:131], v[172:175], v[124:127]
	v_mfma_f32_16x16x32_bf16 v[120:123], v[136:139], v[172:175], v[120:123]
	v_mfma_f32_16x16x32_bf16 v[108:111], v[128:131], v[202:205], v[108:111]
	v_mfma_f32_16x16x32_bf16 v[104:107], v[136:139], v[202:205], v[104:107]
	v_mfma_f32_16x16x32_bf16 v[92:95], v[128:131], v[210:213], v[92:95]
	v_mfma_f32_16x16x32_bf16 v[88:91], v[136:139], v[210:213], v[88:91]
	v_mfma_f32_16x16x32_bf16 v[76:79], v[128:131], v[218:221], v[76:79]
	v_mfma_f32_16x16x32_bf16 v[72:75], v[136:139], v[218:221], v[72:75]
	v_mfma_f32_16x16x32_bf16 v[124:127], v[132:135], v[198:201], v[124:127]
	v_mfma_f32_16x16x32_bf16 v[120:123], v[140:143], v[198:201], v[120:123]
	v_mfma_f32_16x16x32_bf16 v[108:111], v[132:135], v[206:209], v[108:111]
	v_mfma_f32_16x16x32_bf16 v[104:107], v[140:143], v[206:209], v[104:107]
	v_mfma_f32_16x16x32_bf16 v[92:95], v[132:135], v[214:217], v[92:95]
	v_mfma_f32_16x16x32_bf16 v[88:91], v[140:143], v[214:217], v[88:91]
	v_mfma_f32_16x16x32_bf16 v[76:79], v[132:135], v[222:225], v[76:79]
	v_mfma_f32_16x16x32_bf16 v[72:75], v[140:143], v[222:225], v[72:75]
	v_mfma_f32_16x16x32_bf16 v[116:119], v[144:147], v[172:175], v[116:119]
	v_mfma_f32_16x16x32_bf16 v[112:115], v[152:155], v[172:175], v[112:115]
	v_mfma_f32_16x16x32_bf16 v[100:103], v[144:147], v[202:205], v[100:103]
	v_mfma_f32_16x16x32_bf16 v[96:99], v[152:155], v[202:205], v[96:99]
	v_mfma_f32_16x16x32_bf16 v[84:87], v[144:147], v[210:213], v[84:87]
	v_mfma_f32_16x16x32_bf16 v[80:83], v[152:155], v[210:213], v[80:83]
	v_mfma_f32_16x16x32_bf16 v[68:71], v[144:147], v[218:221], v[68:71]
	v_mfma_f32_16x16x32_bf16 v[64:67], v[152:155], v[218:221], v[64:67]
	v_mfma_f32_16x16x32_bf16 v[116:119], v[148:151], v[198:201], v[116:119]
	v_mfma_f32_16x16x32_bf16 v[112:115], v[168:171], v[198:201], v[112:115]
	v_mfma_f32_16x16x32_bf16 v[100:103], v[148:151], v[206:209], v[100:103]
	v_mfma_f32_16x16x32_bf16 v[96:99], v[168:171], v[206:209], v[96:99]
	v_mfma_f32_16x16x32_bf16 v[84:87], v[148:151], v[214:217], v[84:87]
	v_mfma_f32_16x16x32_bf16 v[80:83], v[168:171], v[214:217], v[80:83]
	v_mfma_f32_16x16x32_bf16 v[68:71], v[148:151], v[222:225], v[68:71]
	v_mfma_f32_16x16x32_bf16 v[64:67], v[168:171], v[222:225], v[64:67]
	s_barrier
	s_add_i32 s0, s0, s20
	v_lshl_add_u64 v[226:227], s[6:7], 0, v[160:161]
	s_mov_b32 m0, s0
	ds_read_b128 v[172:175], v196 offset:16384
	ds_read_b128 v[198:201], v196 offset:17408
	ds_read_b128 v[202:205], v196 offset:18432
	ds_read_b128 v[206:209], v196 offset:19456
	ds_read_b128 v[210:213], v196 offset:20480
	ds_read_b128 v[214:217], v196 offset:21504
	ds_read_b128 v[218:221], v196 offset:22528
	ds_read_b128 v[222:225], v196 offset:23552
	global_load_lds_dwordx4 v[226:227], off
	s_add_i32 m0, s0, 0x2000
	s_add_u32 s44, s6, 0xb0000
	v_lshl_add_u64 v[228:229], s[6:7], 0, v[162:163]
	s_addc_u32 s45, s7, 0
	s_add_i32 s0, s26, s20
	global_load_lds_dwordx4 v[228:229], off
	v_lshl_add_u64 v[230:231], s[44:45], 0, v[160:161]
	s_mov_b32 m0, s0
	v_lshl_add_u64 v[232:233], s[14:15], 0, v[158:159]
	global_load_lds_dwordx4 v[230:231], off
	v_lshl_add_u64 v[230:231], s[44:45], 0, v[162:163]
	s_add_i32 m0, s0, 0x2000
	s_nop 0
	global_load_lds_dwordx4 v[230:231], off
	v_lshl_add_u64 v[230:231], s[14:15], 0, v[156:157]
	s_mov_b32 m0, s49
	s_nop 0
	global_load_lds_dwordx4 v[230:231], off
	s_mov_b32 m0, s50
	s_nop 0
	global_load_lds_dwordx4 v[232:233], off
	s_waitcnt vmcnt(8)
	s_waitcnt lgkmcnt(0)
	s_barrier
	v_mfma_f32_16x16x32_bf16 v[60:63], v[128:131], v[172:175], v[60:63]
	v_mfma_f32_16x16x32_bf16 v[56:59], v[136:139], v[172:175], v[56:59]
	v_mfma_f32_16x16x32_bf16 v[44:47], v[128:131], v[202:205], v[44:47]
	v_mfma_f32_16x16x32_bf16 v[40:43], v[136:139], v[202:205], v[40:43]
	v_mfma_f32_16x16x32_bf16 v[28:31], v[128:131], v[210:213], v[28:31]
	v_mfma_f32_16x16x32_bf16 v[24:27], v[136:139], v[210:213], v[24:27]
	v_mfma_f32_16x16x32_bf16 v[12:15], v[128:131], v[218:221], v[12:15]
	v_mfma_f32_16x16x32_bf16 v[8:11], v[136:139], v[218:221], v[8:11]
	v_mfma_f32_16x16x32_bf16 v[60:63], v[132:135], v[198:201], v[60:63]
	v_mfma_f32_16x16x32_bf16 v[56:59], v[140:143], v[198:201], v[56:59]
	v_mfma_f32_16x16x32_bf16 v[44:47], v[132:135], v[206:209], v[44:47]
	v_mfma_f32_16x16x32_bf16 v[40:43], v[140:143], v[206:209], v[40:43]
	v_mfma_f32_16x16x32_bf16 v[28:31], v[132:135], v[214:217], v[28:31]
	v_mfma_f32_16x16x32_bf16 v[24:27], v[140:143], v[214:217], v[24:27]
	v_mfma_f32_16x16x32_bf16 v[12:15], v[132:135], v[222:225], v[12:15]
	v_mfma_f32_16x16x32_bf16 v[8:11], v[140:143], v[222:225], v[8:11]
	v_mfma_f32_16x16x32_bf16 v[52:55], v[144:147], v[172:175], v[52:55]
	v_mfma_f32_16x16x32_bf16 v[48:51], v[152:155], v[172:175], v[48:51]
	v_mfma_f32_16x16x32_bf16 v[36:39], v[144:147], v[202:205], v[36:39]
	v_mfma_f32_16x16x32_bf16 v[32:35], v[152:155], v[202:205], v[32:35]
	v_mfma_f32_16x16x32_bf16 v[20:23], v[144:147], v[210:213], v[20:23]
	v_mfma_f32_16x16x32_bf16 v[16:19], v[152:155], v[210:213], v[16:19]
	v_mfma_f32_16x16x32_bf16 v[4:7], v[144:147], v[218:221], v[4:7]
	v_mfma_f32_16x16x32_bf16 v[0:3], v[152:155], v[218:221], v[0:3]
	v_mfma_f32_16x16x32_bf16 v[52:55], v[148:151], v[198:201], v[52:55]
	v_mfma_f32_16x16x32_bf16 v[48:51], v[168:171], v[198:201], v[48:51]
	v_mfma_f32_16x16x32_bf16 v[36:39], v[148:151], v[206:209], v[36:39]
	v_mfma_f32_16x16x32_bf16 v[32:35], v[168:171], v[206:209], v[32:35]
	v_mfma_f32_16x16x32_bf16 v[20:23], v[148:151], v[214:217], v[20:23]
	v_mfma_f32_16x16x32_bf16 v[16:19], v[168:171], v[214:217], v[16:19]
	v_mfma_f32_16x16x32_bf16 v[4:7], v[148:151], v[222:225], v[4:7]
	v_mfma_f32_16x16x32_bf16 v[0:3], v[168:171], v[222:225], v[0:3]
	s_barrier
; #define PG8_STAGE(bufoff, gbase, voff) do { _Pragma("unroll") for (int _i = 0; _i < 2; ++_i) \
;         __builtin_amdgcn_global_load_lds((const unsigned*)((const char*)(gbase) + (voff)[_i]), (LAS unsigned*)(lds + (bufoff) + ldsw + _i * 8192), 16, 0, 0); } while (0)
; #define PG8_LDA(dst, b, h) do { _Pragma("unroll") for (int m = 0; m < 4; ++m) _Pragma("unroll") for (int k = 0; k < 2; ++k) dst[m][k] = *(const LAS bf16x8*)(lds + PG8_SA(b, h) + aoff + m * 2048 + k * 1024); } while (0)
; #define PG8_LDB(dst, b, h) do { _Pragma("unroll") for (int n = 0; n < 2; ++n) _Pragma("unroll") for (int k = 0; k < 2; ++k) dst[n][k] = *(const LAS bf16x8*)(lds + PG8_SB(b, h) + boff + n * 2048 + k * 1024); } while (0)
; #define PG8_MMA(ai, bj, At, Bt) do { __builtin_amdgcn_s_setprio(1); _Pragma("unroll") for (int m = 0; m < 4; ++m) _Pragma("unroll") for (int n = 0; n < 2; ++n) _Pragma("unroll") for (int k = 0; k < 2; ++k) \
;         acc[ai][bj][m][n] = __builtin_amdgcn_mfma_f32_16x16x32_bf16(Bt[n][k], At[m][k], acc[ai][bj][m][n], 0, 0, 0); __builtin_amdgcn_s_setprio(0); } while (0)
; #define PG8_WAIT_V(n) asm volatile("s_waitcnt vmcnt(" #n ")" ::: "memory")
; #define PG8_WAIT_L(n) asm volatile("s_waitcnt lgkmcnt(" #n ")" ::: "memory")
; #define PG8_BAR __builtin_amdgcn_s_barrier()
; #define PG8_SCHED __builtin_amdgcn_sched_barrier(0)
; template <class Epi, class Sched>
; __device__ __forceinline__ void gemm_phase(LAS unsigned char* lds, const Gemm g, const Sched& S, const Epi& E) {
;     ...
;             PG8_LDB(B0, 1, 0); PG8_LDB(B1, 1, 1); PG8_SCHED; PG8_LDA(At, 1, 0); PG8_STAGE(PG8_SA(0, 1), a2 + hstepA, voffA);
;             PG8_WAIT_V(8); PG8_WAIT_L(0); PG8_BAR; PG8_MMA(0, 0, At, B0); PG8_MMA(0, 1, At, B1); PG8_BAR; PG8_SCHED;
;             PG8_LDA(At, 1, 1); PG8_STAGE(PG8_SB(1, 0), b3, voffB); PG8_STAGE(PG8_SB(1, 1), b3 + hstepB, voffB); PG8_STAGE(PG8_SA(1, 0), a3, voffA);
;             PG8_WAIT_V(8); PG8_WAIT_L(0); PG8_BAR; PG8_MMA(1, 0, At, B0); PG8_MMA(1, 1, At, B1); PG8_BAR; PG8_SCHED;
;         }
;         if (wr == 0) PG8_BAR;
	s_add_i32 s0, 0, 0x18000
	s_add_i32 s26, 0, 0x1c000
	v_add_u32_e32 v140, s0, v186
	v_add_u32_e32 v168, s26, v186
	ds_read_b128 v[128:131], v140
	ds_read_b128 v[132:135], v140 offset:1024
	ds_read_b128 v[136:139], v140 offset:2048
	ds_read_b128 v[140:143], v140 offset:3072
	ds_read_b128 v[144:147], v168
	ds_read_b128 v[148:151], v168 offset:1024
	ds_read_b128 v[152:155], v168 offset:2048
	ds_read_b128 v[168:171], v168 offset:3072
	s_add_u32 s14, s14, 0xb0000
	s_addc_u32 s15, s15, 0
	s_mov_b32 m0, s51
	v_lshl_add_u64 v[234:235], s[14:15], 0, v[156:157]
	ds_read_b128 v[172:175], v196 offset:32768
	ds_read_b128 v[198:201], v196 offset:33792
	ds_read_b128 v[202:205], v196 offset:34816
	ds_read_b128 v[206:209], v196 offset:35840
	ds_read_b128 v[210:213], v196 offset:36864
	ds_read_b128 v[214:217], v196 offset:37888
	ds_read_b128 v[218:221], v196 offset:38912
	ds_read_b128 v[222:225], v196 offset:39936
	global_load_lds_dwordx4 v[234:235], off
	v_lshl_add_u64 v[234:235], s[14:15], 0, v[158:159]
	s_mov_b32 m0, s52
	s_nop 0
	global_load_lds_dwordx4 v[234:235], off
	s_waitcnt vmcnt(8)
	s_waitcnt lgkmcnt(0)
	s_barrier
	v_mfma_f32_16x16x32_bf16 v[124:127], v[128:131], v[172:175], v[124:127]
	v_mfma_f32_16x16x32_bf16 v[120:123], v[136:139], v[172:175], v[120:123]
	v_mfma_f32_16x16x32_bf16 v[108:111], v[128:131], v[202:205], v[108:111]
	v_mfma_f32_16x16x32_bf16 v[104:107], v[136:139], v[202:205], v[104:107]
	v_mfma_f32_16x16x32_bf16 v[92:95], v[128:131], v[210:213], v[92:95]
	v_mfma_f32_16x16x32_bf16 v[88:91], v[136:139], v[210:213], v[88:91]
	v_mfma_f32_16x16x32_bf16 v[76:79], v[128:131], v[218:221], v[76:79]
	v_mfma_f32_16x16x32_bf16 v[72:75], v[136:139], v[218:221], v[72:75]
	v_mfma_f32_16x16x32_bf16 v[124:127], v[132:135], v[198:201], v[124:127]
	v_mfma_f32_16x16x32_bf16 v[120:123], v[140:143], v[198:201], v[120:123]
	v_mfma_f32_16x16x32_bf16 v[108:111], v[132:135], v[206:209], v[108:111]
	v_mfma_f32_16x16x32_bf16 v[104:107], v[140:143], v[206:209], v[104:107]
	v_mfma_f32_16x16x32_bf16 v[92:95], v[132:135], v[214:217], v[92:95]
	v_mfma_f32_16x16x32_bf16 v[88:91], v[140:143], v[214:217], v[88:91]
	v_mfma_f32_16x16x32_bf16 v[76:79], v[132:135], v[222:225], v[76:79]
	v_mfma_f32_16x16x32_bf16 v[72:75], v[140:143], v[222:225], v[72:75]
	v_mfma_f32_16x16x32_bf16 v[116:119], v[144:147], v[172:175], v[116:119]
	v_mfma_f32_16x16x32_bf16 v[112:115], v[152:155], v[172:175], v[112:115]
	v_mfma_f32_16x16x32_bf16 v[100:103], v[144:147], v[202:205], v[100:103]
	v_mfma_f32_16x16x32_bf16 v[96:99], v[152:155], v[202:205], v[96:99]
	v_mfma_f32_16x16x32_bf16 v[84:87], v[144:147], v[210:213], v[84:87]
	v_mfma_f32_16x16x32_bf16 v[80:83], v[152:155], v[210:213], v[80:83]
	v_mfma_f32_16x16x32_bf16 v[68:71], v[144:147], v[218:221], v[68:71]
	v_mfma_f32_16x16x32_bf16 v[64:67], v[152:155], v[218:221], v[64:67]
	v_mfma_f32_16x16x32_bf16 v[116:119], v[148:151], v[198:201], v[116:119]
	v_mfma_f32_16x16x32_bf16 v[112:115], v[168:171], v[198:201], v[112:115]
	v_mfma_f32_16x16x32_bf16 v[100:103], v[148:151], v[206:209], v[100:103]
	v_mfma_f32_16x16x32_bf16 v[96:99], v[168:171], v[206:209], v[96:99]
	v_mfma_f32_16x16x32_bf16 v[84:87], v[148:151], v[214:217], v[84:87]
	v_mfma_f32_16x16x32_bf16 v[80:83], v[168:171], v[214:217], v[80:83]
	v_mfma_f32_16x16x32_bf16 v[68:71], v[148:151], v[222:225], v[68:71]
	v_mfma_f32_16x16x32_bf16 v[64:67], v[168:171], v[222:225], v[64:67]
	s_barrier
	s_add_i32 s0, s0, s20
	v_lshl_add_u64 v[226:227], v[226:227], 0, s[30:31]
	s_mov_b32 m0, s0
	ds_read_b128 v[172:175], v196 offset:49152
	ds_read_b128 v[198:201], v196 offset:50176
	ds_read_b128 v[202:205], v196 offset:51200
	ds_read_b128 v[206:209], v196 offset:52224
	ds_read_b128 v[210:213], v196 offset:53248
	ds_read_b128 v[214:217], v196 offset:54272
	ds_read_b128 v[218:221], v196 offset:55296
	ds_read_b128 v[222:225], v196 offset:56320
	global_load_lds_dwordx4 v[226:227], off
	s_add_i32 m0, s0, 0x2000
	s_add_u32 s6, s6, 0xb0080
	v_lshl_add_u64 v[226:227], v[228:229], 0, s[30:31]
	s_addc_u32 s7, s7, 0
	s_add_i32 s0, s26, s20
	global_load_lds_dwordx4 v[226:227], off
	v_lshl_add_u64 v[226:227], s[6:7], 0, v[160:161]
	s_mov_b32 m0, s0
	s_nop 0
	global_load_lds_dwordx4 v[226:227], off
	v_lshl_add_u64 v[226:227], s[6:7], 0, v[162:163]
	s_add_i32 m0, s0, 0x2000
	s_nop 0
	global_load_lds_dwordx4 v[226:227], off
	v_lshl_add_u64 v[226:227], v[230:231], 0, s[30:31]
	s_mov_b32 m0, s24
	s_nop 0
	global_load_lds_dwordx4 v[226:227], off
	v_lshl_add_u64 v[226:227], v[232:233], 0, s[30:31]
	s_mov_b32 m0, s25
	s_nop 0
	global_load_lds_dwordx4 v[226:227], off
	s_waitcnt vmcnt(8)
	s_waitcnt lgkmcnt(0)
	s_barrier
	v_mfma_f32_16x16x32_bf16 v[60:63], v[128:131], v[172:175], v[60:63]
	v_mfma_f32_16x16x32_bf16 v[56:59], v[136:139], v[172:175], v[56:59]
	v_mfma_f32_16x16x32_bf16 v[44:47], v[128:131], v[202:205], v[44:47]
	v_mfma_f32_16x16x32_bf16 v[40:43], v[136:139], v[202:205], v[40:43]
	v_mfma_f32_16x16x32_bf16 v[28:31], v[128:131], v[210:213], v[28:31]
	v_mfma_f32_16x16x32_bf16 v[24:27], v[136:139], v[210:213], v[24:27]
	v_mfma_f32_16x16x32_bf16 v[12:15], v[128:131], v[218:221], v[12:15]
	v_mfma_f32_16x16x32_bf16 v[8:11], v[136:139], v[218:221], v[8:11]
	v_mfma_f32_16x16x32_bf16 v[60:63], v[132:135], v[198:201], v[60:63]
	v_mfma_f32_16x16x32_bf16 v[56:59], v[140:143], v[198:201], v[56:59]
	v_mfma_f32_16x16x32_bf16 v[44:47], v[132:135], v[206:209], v[44:47]
	v_mfma_f32_16x16x32_bf16 v[40:43], v[140:143], v[206:209], v[40:43]
	v_mfma_f32_16x16x32_bf16 v[28:31], v[132:135], v[214:217], v[28:31]
	v_mfma_f32_16x16x32_bf16 v[24:27], v[140:143], v[214:217], v[24:27]
	v_mfma_f32_16x16x32_bf16 v[12:15], v[132:135], v[222:225], v[12:15]
	v_mfma_f32_16x16x32_bf16 v[8:11], v[140:143], v[222:225], v[8:11]
	v_mfma_f32_16x16x32_bf16 v[52:55], v[144:147], v[172:175], v[52:55]
	v_mfma_f32_16x16x32_bf16 v[48:51], v[152:155], v[172:175], v[48:51]
	v_mfma_f32_16x16x32_bf16 v[36:39], v[144:147], v[202:205], v[36:39]
	v_mfma_f32_16x16x32_bf16 v[32:35], v[152:155], v[202:205], v[32:35]
	v_mfma_f32_16x16x32_bf16 v[20:23], v[144:147], v[210:213], v[20:23]
	v_mfma_f32_16x16x32_bf16 v[16:19], v[152:155], v[210:213], v[16:19]
	v_mfma_f32_16x16x32_bf16 v[4:7], v[144:147], v[218:221], v[4:7]
	v_mfma_f32_16x16x32_bf16 v[0:3], v[152:155], v[218:221], v[0:3]
	v_mfma_f32_16x16x32_bf16 v[52:55], v[148:151], v[198:201], v[52:55]
	v_mfma_f32_16x16x32_bf16 v[48:51], v[168:171], v[198:201], v[48:51]
	v_mfma_f32_16x16x32_bf16 v[36:39], v[148:151], v[206:209], v[36:39]
	v_mfma_f32_16x16x32_bf16 v[32:35], v[168:171], v[206:209], v[32:35]
	v_mfma_f32_16x16x32_bf16 v[20:23], v[148:151], v[214:217], v[20:23]
	v_mfma_f32_16x16x32_bf16 v[16:19], v[168:171], v[214:217], v[16:19]
	v_mfma_f32_16x16x32_bf16 v[4:7], v[148:151], v[222:225], v[4:7]
	v_mfma_f32_16x16x32_bf16 v[0:3], v[168:171], v[222:225], v[0:3]
	s_barrier
	s_add_i32 s54, s54, 2
	s_add_u32 s33, s33, 0x100
	s_addc_u32 s53, s53, 0
	s_cmp_gt_u32 s54, 41
	s_mov_b64 s[44:45], s[46:47]
	s_cbranch_scc0 .LBB0_807
	s_setprio 0
	s_and_b64 vcc, exec, s[18:19]
	s_cbranch_vccz .LBB0_810
	s_barrier
